# combo28 + FFT first-pass LDS addresses: one base (+ one second base) with immediate offsets in the three 16-point half-pass loops, 204 dead address instructions removed
# baseline (speedup 1.0000x reference)
.Lmy_fft_kj:
	v_mov_b32 v66, 0
	v_mov_b32_e32 v68, v1
	v_add_u32_e32 v0, v66, v0
	v_cvt_f32_i32_e32 v70, v0
	v_ashrrev_i32_e32 v66, 5, v0
	v_lshlrev_b32_e32 v69, 3, v0
	v_lshlrev_b32_e32 v66, 3, v66
	v_add3_u32 v127, 0, v66, v69
	v_add_u32_e32 v220, 0x10800, v127
	v_mul_f32_e32 v0, 0x38800000, v70
	v_sin_f32_e32 v107, v0
	v_cos_f32_e32 v106, v0
	v_xor_b32_e32 v124, 0x80000000, v107
	v_mov_b32_e32 v125, v107
	v_pk_mul_f32 v[128:129], v[124:125], v[106:107] op_sel:[0,1] op_sel_hi:[1,0]
	v_pk_fma_f32 v[128:129], v[106:107], v[106:107], v[128:129] op_sel_hi:[1,0,1]
	v_pk_mul_f32 v[132:133], v[124:125], v[128:129] op_sel:[0,1] op_sel_hi:[1,0]
	s_waitcnt vmcnt(21)
	v_sub_f32_e32 v70, v112, v120
	v_pk_fma_f32 v[132:133], v[128:129], v[106:107], v[132:133] op_sel_hi:[1,0,1]
	s_waitcnt vmcnt(20)
	v_sub_f32_e32 v76, v113, v121
	v_pk_mul_f32 v[136:137], v[124:125], v[132:133] op_sel:[0,1] op_sel_hi:[1,0]
	v_pk_fma_f32 v[136:137], v[132:133], v[106:107], v[136:137] op_sel_hi:[1,0,1]
	v_pk_mul_f32 v[140:141], v[124:125], v[136:137] op_sel:[0,1] op_sel_hi:[1,0]
	v_pk_fma_f32 v[140:141], v[136:137], v[106:107], v[140:141] op_sel_hi:[1,0,1]
	v_sub_f32_e32 v66, v109, v119
	v_pk_mul_f32 v[144:145], v[124:125], v[140:141] op_sel:[0,1] op_sel_hi:[1,0]
	v_mul_f32_e32 v73, 0xbf3504f3, v70
	v_pk_fma_f32 v[144:145], v[140:141], v[106:107], v[144:145] op_sel_hi:[1,0,1]
	v_mul_f32_e32 v85, 0xbf6c835e, v76
	v_pk_mul_f32 v[148:149], v[124:125], v[144:145] op_sel:[0,1] op_sel_hi:[1,0]
	v_pk_fma_f32 v[148:149], v[144:145], v[106:107], v[148:149] op_sel_hi:[1,0,1]
	v_pk_mul_f32 v[152:153], v[124:125], v[148:149] op_sel:[0,1] op_sel_hi:[1,0]
	v_pk_fma_f32 v[152:153], v[148:149], v[106:107], v[152:153] op_sel_hi:[1,0,1]
	v_pk_mul_f32 v[156:157], v[124:125], v[152:153] op_sel:[0,1] op_sel_hi:[1,0]
	v_pk_fma_f32 v[156:157], v[152:153], v[106:107], v[156:157] op_sel_hi:[1,0,1]
	v_sub_f32_e32 v0, v108, v118
	v_pk_mul_f32 v[160:161], v[124:125], v[156:157] op_sel:[0,1] op_sel_hi:[1,0]
	v_pk_add_f32 v[108:109], v[108:109], v[118:119]
	v_pk_fma_f32 v[160:161], v[156:157], v[106:107], v[160:161] op_sel_hi:[1,0,1]
	v_mul_f32_e32 v69, 0xbec3ef15, v66
	v_pk_mul_f32 v[164:165], v[124:125], v[160:161] op_sel:[0,1] op_sel_hi:[1,0]
	v_pk_fma_f32 v[70:71], v[70:71], s[10:11], v[72:73] op_sel_hi:[1,0,1]
	v_pk_fma_f32 v[72:73], v[76:77], s[14:15], v[84:85] op_sel_hi:[1,0,1]
	s_waitcnt vmcnt(18)
	v_sub_f32_e32 v82, v115, v123
	v_pk_add_f32 v[76:77], v[114:115], v[122:123]
	v_mov_b32_e32 v83, v1
	v_mov_b32_e32 v90, v1
	s_movk_i32 s5, 0x200
	v_pk_fma_f32 v[164:165], v[160:161], v[106:107], v[164:165] op_sel_hi:[1,0,1]
	v_pk_fma_f32 v[66:67], v[66:67], s[6:7], v[68:69] op_sel_hi:[1,0,1]
	v_pk_add_f32 v[68:69], v[112:113], v[120:121]
	v_mul_f32_e32 v91, 0xbf6c835e, v82
	s_waitcnt vmcnt(17)
	v_sub_f32_e32 v80, v116, v110
	v_pk_add_f32 v[112:113], v[108:109], v[76:77] neg_lo:[0,1] neg_hi:[0,1]
	v_mov_b32_e32 v81, v1
	v_mov_b32_e32 v88, v1
	v_mov_b32_e32 v101, v1
	v_mov_b32_e32 v102, v1
	v_pk_mul_f32 v[168:169], v[124:125], v[164:165] op_sel:[0,1] op_sel_hi:[1,0]
	v_pk_fma_f32 v[82:83], v[82:83], s[4:5], v[90:91] op_sel_hi:[1,0,1]
	v_mul_f32_e32 v89, 0xbf3504f3, v80
	s_waitcnt vmcnt(16)
	v_sub_f32_e32 v78, v117, v111
	v_pk_add_f32 v[90:91], v[116:117], v[110:111]
	v_mov_b32_e32 v100, v113
	v_mul_f32_e32 v103, 0xbf3504f3, v113
	v_mov_b32_e32 v79, v1
	v_mov_b32_e32 v86, v1
	v_pk_fma_f32 v[168:169], v[164:165], v[106:107], v[168:169] op_sel_hi:[1,0,1]
	v_sub_f32_e32 v75, v114, v122
	v_pk_fma_f32 v[80:81], v[80:81], s[8:9], v[88:89] op_sel_hi:[1,0,1]
	v_mul_f32_e32 v87, 0xbec3ef15, v78
	v_pk_add_f32 v[88:89], v[66:67], v[82:83]
	v_pk_add_f32 v[66:67], v[66:67], v[82:83] neg_lo:[0,1] neg_hi:[0,1]
	v_pk_fma_f32 v[82:83], v[100:101], s[10:11], v[102:103] op_sel_hi:[1,0,1]
	v_pk_add_f32 v[100:101], v[68:69], v[90:91] neg_lo:[0,1] neg_hi:[0,1]
	v_mov_b32_e32 v74, v1
	v_mov_b32_e32 v97, v1
	v_mov_b32_e32 v98, v1
	v_pk_mul_f32 v[174:175], v[124:125], v[168:169] op_sel:[0,1] op_sel_hi:[1,0]
	v_xor_b32_e32 v75, 0x80000000, v75
	v_pk_add_f32 v[76:77], v[108:109], v[76:77]
	v_pk_add_f32 v[68:69], v[68:69], v[90:91]
	v_pk_fma_f32 v[78:79], v[78:79], s[12:13], v[86:87] op_sel_hi:[1,0,1]
	v_pk_add_f32 v[90:91], v[70:71], v[80:81]
	v_pk_add_f32 v[70:71], v[70:71], v[80:81] neg_lo:[0,1] neg_hi:[0,1]
	v_mov_b32_e32 v96, v101
	v_mul_f32_e32 v99, 0xbf3504f3, v101
	v_pk_fma_f32 v[174:175], v[168:169], v[106:107], v[174:175] op_sel_hi:[1,0,1]
	v_pk_add_f32 v[84:85], v[0:1], v[74:75]
	v_pk_add_f32 v[80:81], v[76:77], v[68:69] neg_lo:[0,1] neg_hi:[0,1]
	v_pk_add_f32 v[68:69], v[76:77], v[68:69]
	v_xor_b32_e32 v77, 0x80000000, v70
	v_mov_b32_e32 v76, v71
	v_pk_add_f32 v[70:71], v[72:73], v[78:79]
	v_pk_add_f32 v[72:73], v[72:73], v[78:79] neg_lo:[0,1] neg_hi:[0,1]
	v_pk_fma_f32 v[78:79], v[96:97], s[8:9], v[98:99] op_sel_hi:[1,0,1]
	v_mov_b32_e32 v94, v1
	v_pk_mul_f32 v[178:179], v[124:125], v[174:175] op_sel:[0,1] op_sel_hi:[1,0]
	v_pk_add_f32 v[74:75], v[0:1], v[74:75] neg_lo:[0,1] neg_hi:[0,1]
	v_mov_b32_e32 v0, v112
	v_pk_mul_f32 v[86:87], v[66:67], s[16:17]
	v_xor_b32_e32 v95, 0x80000000, v100
	v_mov_b32_e32 v92, v80
	v_pk_add_f32 v[80:81], v[80:81], 0 neg_lo:[1,1] neg_hi:[1,1]
	v_pk_add_f32 v[96:97], v[84:85], v[90:91]
	v_pk_add_f32 v[84:85], v[84:85], v[90:91] neg_lo:[0,1] neg_hi:[0,1]
	v_pk_add_f32 v[90:91], v[68:69], v[68:69] op_sel:[0,1] op_sel_hi:[1,0]
	v_pk_mul_f32 v[98:99], v[72:73], s[16:17]
	v_pk_add_f32 v[100:101], v[82:83], v[78:79]
	v_pk_add_f32 v[78:79], v[82:83], v[78:79] neg_lo:[0,1] neg_hi:[0,1]
	v_pk_add_f32 v[82:83], v[88:89], v[70:71]
	v_pk_add_f32 v[70:71], v[88:89], v[70:71] neg_lo:[0,1] neg_hi:[0,1]
	v_mov_b32_e32 v93, v1
	v_mov_b32_e32 v126, v107
	v_pk_add_f32 v[130:131], v[128:129], 0 neg_lo:[1,1] neg_hi:[1,1]
	v_pk_add_f32 v[158:159], v[156:157], 0 neg_lo:[1,1] neg_hi:[1,1]
	v_pk_fma_f32 v[178:179], v[174:175], v[106:107], v[178:179] op_sel_hi:[1,0,1]
	v_pk_fma_f32 v[66:67], v[66:67], s[10:11], v[86:87] op_sel:[0,0,1] op_sel_hi:[1,0,0]
	v_pk_add_f32 v[86:87], v[0:1], v[94:95]
	v_pk_add_f32 v[94:95], v[0:1], v[94:95] neg_lo:[0,1] neg_hi:[0,1]
	v_mov_b32_e32 v80, v1
	v_pk_add_f32 v[88:89], v[74:75], v[76:77]
	v_pk_add_f32 v[74:75], v[74:75], v[76:77] neg_lo:[0,1] neg_hi:[0,1]
	v_mov_b32_e32 v91, v1
	v_pk_fma_f32 v[72:73], v[72:73], s[8:9], v[98:99] op_sel:[0,0,1] op_sel_hi:[1,0,0]
	v_xor_b32_e32 v77, 0x80000000, v78
	v_mov_b32_e32 v76, v79
	v_xor_b32_e32 v79, 0x80000000, v70
	v_mov_b32_e32 v78, v71
	v_pk_add_f32 v[98:99], v[96:97], v[82:83]
	v_mov_b32_e32 v130, v129
	v_pk_add_f32 v[134:135], v[132:133], 0 neg_lo:[1,1] neg_hi:[1,1]
	v_pk_add_f32 v[142:143], v[140:141], 0 neg_lo:[1,1] neg_hi:[1,1]
	v_mov_b32_e32 v158, v157
	v_pk_mul_f32 v[124:125], v[124:125], v[178:179] op_sel:[0,1] op_sel_hi:[1,0]
	v_pk_add_f32 v[70:71], v[92:93], v[80:81]
	v_pk_add_f32 v[80:81], v[92:93], v[80:81] neg_lo:[0,1] neg_hi:[0,1]
	v_pk_add_f32 v[92:93], v[86:87], v[100:101]
	v_pk_add_f32 v[82:83], v[96:97], v[82:83] neg_lo:[0,1] neg_hi:[0,1]
	ds_write_b64 v127, v[90:91]
	v_pk_add_f32 v[90:91], v[66:67], v[72:73]
	v_pk_add_f32 v[112:113], v[66:67], v[72:73] op_sel:[1,1] op_sel_hi:[0,0] neg_lo:[0,1] neg_hi:[1,0]
	v_pk_add_f32 v[72:73], v[94:95], v[76:77]
	v_pk_add_f32 v[76:77], v[94:95], v[76:77] neg_lo:[0,1] neg_hi:[0,1]
	v_pk_add_f32 v[94:95], v[84:85], v[78:79]
	v_pk_add_f32 v[78:79], v[84:85], v[78:79] neg_lo:[0,1] neg_hi:[0,1]
	v_pk_mul_f32 v[84:85], v[126:127], v[98:99] op_sel:[0,1] op_sel_hi:[0,0] neg_hi:[1,0]
	v_mov_b32_e32 v134, v133
	v_pk_add_f32 v[138:139], v[136:137], 0 neg_lo:[1,1] neg_hi:[1,1]
	v_mov_b32_e32 v142, v141
	v_pk_add_f32 v[146:147], v[144:145], 0 neg_lo:[1,1] neg_hi:[1,1]
	v_pk_add_f32 v[150:151], v[148:149], 0 neg_lo:[1,1] neg_hi:[1,1]
	v_pk_add_f32 v[166:167], v[164:165], 0 neg_lo:[1,1] neg_hi:[1,1]
	v_pk_fma_f32 v[124:125], v[178:179], v[106:107], v[124:125] op_sel_hi:[1,0,1]
	v_pk_mul_f32 v[96:97], v[92:93], v[130:131] op_sel:[1,0] op_sel_hi:[0,1]
	v_pk_mul_f32 v[102:103], v[82:83], v[158:159] op_sel:[1,0] op_sel_hi:[0,1]
	v_pk_add_f32 v[66:67], v[88:89], v[90:91]
	v_pk_fma_f32 v[84:85], v[98:99], v[106:107], v[84:85] op_sel_hi:[1,0,1]
	v_mov_b32_e32 v138, v137
	v_mov_b32_e32 v146, v145
	v_mov_b32_e32 v150, v149
	v_pk_add_f32 v[154:155], v[152:153], 0 neg_lo:[1,1] neg_hi:[1,1]
	v_pk_add_f32 v[162:163], v[160:161], 0 neg_lo:[1,1] neg_hi:[1,1]
	v_mov_b32_e32 v166, v165
	v_pk_add_f32 v[172:173], v[168:169], 0 neg_lo:[1,1] neg_hi:[1,1]
	v_pk_add_f32 v[176:177], v[174:175], 0 neg_lo:[1,1] neg_hi:[1,1]
	v_pk_add_f32 v[180:181], v[178:179], 0 neg_lo:[1,1] neg_hi:[1,1]
	v_pk_add_f32 v[182:183], v[124:125], 0 neg_lo:[1,1] neg_hi:[1,1]
	v_pk_add_f32 v[68:69], v[68:69], v[68:69] op_sel:[0,1] op_sel_hi:[1,0] neg_lo:[0,1] neg_hi:[0,1]
	v_pk_add_f32 v[88:89], v[88:89], v[90:91] neg_lo:[0,1] neg_hi:[0,1]
	v_pk_fma_f32 v[90:91], v[92:93], v[128:129], v[96:97] op_sel_hi:[1,0,1]
	v_pk_mul_f32 v[92:93], v[94:95], v[142:143] op_sel:[1,0] op_sel_hi:[0,1]
	v_pk_fma_f32 v[82:83], v[82:83], v[156:157], v[102:103] op_sel_hi:[1,0,1]
	v_pk_add_f32 v[102:103], v[74:75], v[112:113]
	ds_write_b64 v127, v[84:85] offset:8448
	ds_write_b64 v127, v[90:91] offset:16896
	v_pk_mul_f32 v[84:85], v[66:67], v[134:135] op_sel:[1,0] op_sel_hi:[0,1]
	v_mov_b32_e32 v154, v153
	v_mov_b32_e32 v162, v161
	v_mov_b32_e32 v172, v169
	v_mov_b32_e32 v176, v175
	v_mov_b32_e32 v180, v179
	v_mov_b32_e32 v182, v125
	v_mov_b32_e32 v0, v68
	v_pk_mov_b32 v[68:69], s[2:3], v[68:69] op_sel:[1,0]
	v_pk_add_f32 v[86:87], v[86:87], v[100:101] neg_lo:[0,1] neg_hi:[0,1]
	v_pk_mul_f32 v[100:101], v[70:71], v[138:139] op_sel:[1,0] op_sel_hi:[0,1]
	v_pk_mul_f32 v[96:97], v[72:73], v[146:147] op_sel:[1,0] op_sel_hi:[0,1]
	v_pk_add_f32 v[74:75], v[74:75], v[112:113] neg_lo:[0,1] neg_hi:[0,1]
	v_pk_fma_f32 v[90:91], v[94:95], v[140:141], v[92:93] op_sel_hi:[1,0,1]
	v_pk_mul_f32 v[92:93], v[88:89], v[166:167] op_sel:[1,0] op_sel_hi:[0,1]
	v_pk_fma_f32 v[66:67], v[66:67], v[132:133], v[84:85] op_sel_hi:[1,0,1]
	v_pk_mul_f32 v[84:85], v[102:103], v[150:151] op_sel:[1,0] op_sel_hi:[0,1]
	s_mov_b64 s[46:47], 0
	s_and_b64 vcc, exec, s[0:1]
	v_pk_mul_f32 v[68:69], v[68:69], v[154:155]
	v_pk_mul_f32 v[108:109], v[86:87], v[162:163] op_sel:[1,0] op_sel_hi:[0,1]
	v_pk_mul_f32 v[110:111], v[80:81], v[172:173] op_sel:[1,0] op_sel_hi:[0,1]
	v_pk_fma_f32 v[70:71], v[70:71], v[136:137], v[100:101] op_sel_hi:[1,0,1]
	v_pk_mul_f32 v[98:99], v[78:79], v[176:177] op_sel:[1,0] op_sel_hi:[0,1]
	v_pk_mul_f32 v[100:101], v[76:77], v[180:181] op_sel:[1,0] op_sel_hi:[0,1]
	v_pk_fma_f32 v[72:73], v[72:73], v[144:145], v[96:97] op_sel_hi:[1,0,1]
	v_pk_fma_f32 v[88:89], v[88:89], v[164:165], v[92:93] op_sel_hi:[1,0,1]
	v_pk_mul_f32 v[92:93], v[74:75], v[182:183] op_sel:[1,0] op_sel_hi:[0,1]
	ds_write_b64 v127, v[66:67] offset:25344
	ds_write_b64 v127, v[70:71] offset:33792
	ds_write_b64 v127, v[90:91] offset:42240
	ds_write_b64 v127, v[72:73] offset:50688
	v_pk_fma_f32 v[66:67], v[102:103], v[148:149], v[84:85] op_sel_hi:[1,0,1]
	v_pk_fma_f32 v[68:69], v[0:1], v[152:153], v[68:69] op_sel_hi:[1,0,1]
	v_pk_fma_f32 v[86:87], v[86:87], v[160:161], v[108:109] op_sel_hi:[1,0,1]
	v_pk_fma_f32 v[80:81], v[80:81], v[168:169], v[110:111] op_sel_hi:[1,0,1]
	v_pk_fma_f32 v[78:79], v[78:79], v[174:175], v[98:99] op_sel_hi:[1,0,1]
	v_pk_fma_f32 v[76:77], v[76:77], v[178:179], v[100:101] op_sel_hi:[1,0,1]
	v_pk_fma_f32 v[70:71], v[74:75], v[124:125], v[92:93] op_sel_hi:[1,0,1]
	ds_write_b64 v127, v[66:67] offset:59136
	ds_write_b64 v220, v[68:69]
	ds_write_b64 v220, v[82:83] offset:8448
	ds_write_b64 v220, v[86:87] offset:16896
	ds_write_b64 v220, v[88:89] offset:25344
	ds_write_b64 v220, v[80:81] offset:33792
	ds_write_b64 v220, v[78:79] offset:42240
	ds_write_b64 v220, v[76:77] offset:50688
	ds_write_b64 v220, v[70:71] offset:59136
	s_cbranch_vccz .LBB0_359
	s_waitcnt lgkmcnt(0)
	s_barrier
	v_mov_b32 v0, 0
	s_mov_b32 s5, s14
	v_add_u32_e32 v74, v0, v170
	v_lshlrev_b32_e32 v0, 5, v74
	v_and_b32_e32 v71, 0xfffffc00, v0
	v_or_b32_e32 v75, 0x80, v71
	v_and_b32_e32 v70, 31, v74
	v_ashrrev_i32_e32 v75, 2, v75
	v_lshlrev_b32_e32 v78, 3, v71
	v_lshlrev_b32_e32 v79, 3, v70
	v_add_u32_e32 v75, 0, v75
	v_add3_u32 v111, v75, v78, v79
	v_or_b32_e32 v75, 0xa0, v71
	v_ashrrev_i32_e32 v75, 2, v75
	v_add_u32_e32 v75, 0, v75
	v_add3_u32 v110, v75, v78, v79
	v_or_b32_e32 v75, 0xc0, v71
	v_ashrrev_i32_e32 v75, 2, v75
	v_add_u32_e32 v75, 0, v75
	v_add3_u32 v109, v75, v78, v79
	v_or_b32_e32 v75, 0xe0, v71
	v_ashrrev_i32_e32 v75, 2, v75
	v_add_u32_e32 v75, 0, v75
	v_add3_u32 v108, v75, v78, v79
	v_or_b32_e32 v75, 0x100, v71
	v_ashrrev_i32_e32 v75, 2, v75
	v_add_u32_e32 v75, 0, v75
	v_add3_u32 v107, v75, v78, v79
	v_or_b32_e32 v75, 0x120, v71
	v_ashrrev_i32_e32 v75, 2, v75
	v_add_u32_e32 v75, 0, v75
	v_add3_u32 v106, v75, v78, v79
	v_or_b32_e32 v75, 0x140, v71
	v_ashrrev_i32_e32 v75, 2, v75
	v_add_u32_e32 v75, 0, v75
	v_add3_u32 v105, v75, v78, v79
	v_or_b32_e32 v75, 0x160, v71
	v_ashrrev_i32_e32 v75, 2, v75
	v_add_u32_e32 v75, 0, v75
	v_add3_u32 v103, v75, v78, v79
	v_or_b32_e32 v75, 0x180, v71
	v_ashrrev_i32_e32 v75, 2, v75
	v_add_u32_e32 v75, 0, v75
	v_add3_u32 v102, v75, v78, v79
	v_or_b32_e32 v75, 0x1a0, v71
	v_ashrrev_i32_e32 v75, 2, v75
	v_add_u32_e32 v75, 0, v75
	v_add3_u32 v101, v75, v78, v79
	v_or_b32_e32 v75, 0x1c0, v71
	v_ashrrev_i32_e32 v75, 2, v75
	v_add_u32_e32 v75, 0, v75
	v_add3_u32 v100, v75, v78, v79
	v_or_b32_e32 v75, 0x1e0, v71
	v_ashrrev_i32_e32 v75, 2, v75
	v_add_u32_e32 v75, 0, v75
	v_add3_u32 v99, v75, v78, v79
	v_or_b32_e32 v75, 0x200, v71
	v_ashrrev_i32_e32 v75, 2, v75
	v_add_u32_e32 v75, 0, v75
	v_add3_u32 v98, v75, v78, v79
	v_or_b32_e32 v75, 0x220, v71
	v_ashrrev_i32_e32 v75, 2, v75
	v_add_u32_e32 v75, 0, v75
	v_add3_u32 v97, v75, v78, v79
	v_or_b32_e32 v75, 0x240, v71
	v_ashrrev_i32_e32 v75, 2, v75
	v_add_u32_e32 v75, 0, v75
	v_add3_u32 v96, v75, v78, v79
	v_or_b32_e32 v75, 0x260, v71
	v_ashrrev_i32_e32 v75, 2, v75
	v_add_u32_e32 v75, 0, v75
	v_add3_u32 v95, v75, v78, v79
	v_or_b32_e32 v75, 0x280, v71
	v_or_b32_e32 v67, 32, v71
	v_ashrrev_i32_e32 v75, 2, v75
	v_ashrrev_i32_e32 v67, 2, v67
	v_add_u32_e32 v75, 0, v75
	v_add_u32_e32 v67, 0, v67
	v_add3_u32 v94, v75, v78, v79
	v_or_b32_e32 v75, 0x2a0, v71
	v_add3_u32 v114, v67, v78, v79
	v_or_b32_e32 v67, 64, v71
	v_ashrrev_i32_e32 v75, 2, v75
	v_ashrrev_i32_e32 v67, 2, v67
	v_add_u32_e32 v75, 0, v75
	v_add_u32_e32 v67, 0, v67
	v_add3_u32 v93, v75, v78, v79
	v_or_b32_e32 v75, 0x2c0, v71
	v_ashrrev_i32_e32 v66, 2, v71
	v_add3_u32 v113, v67, v78, v79
	v_or_b32_e32 v67, 0x60, v71
	v_ashrrev_i32_e32 v75, 2, v75
	v_add_u32_e32 v66, 0, v66
	v_ashrrev_i32_e32 v67, 2, v67
	v_add_u32_e32 v75, 0, v75
	v_add3_u32 v66, v66, v78, v79
	v_add_u32_e32 v67, 0, v67
	v_add3_u32 v92, v75, v78, v79
	v_or_b32_e32 v75, 0x2e0, v71
	v_add3_u32 v112, v67, v78, v79
	ds_read_b64 v[66:67], v66
	ds_read_b64 v[68:69], v114 offset:256
	ds_read_b64 v[72:73], v113 offset:512
	ds_read_b64 v[76:77], v112 offset:768
	ds_read_b64 v[80:81], v111 offset:1024
	ds_read_b64 v[82:83], v110 offset:1280
	ds_read_b64 v[116:117], v109 offset:1536
	ds_read_b64 v[118:119], v108 offset:1792
	ds_read_b64 v[120:121], v107 offset:2048
	ds_read_b64 v[122:123], v106 offset:2304
	ds_read_b64 v[124:125], v105 offset:2560
	ds_read_b64 v[126:127], v103 offset:2816
	ds_read_b64 v[128:129], v102 offset:3072
	ds_read_b64 v[130:131], v101 offset:3328
	ds_read_b64 v[132:133], v100 offset:3584
	ds_read_b64 v[134:135], v99 offset:3840
	ds_read_b64 v[136:137], v98 offset:4096
	ds_read_b64 v[138:139], v97 offset:4352
	ds_read_b64 v[140:141], v96 offset:4608
	ds_read_b64 v[142:143], v95 offset:4864
	v_ashrrev_i32_e32 v75, 2, v75
	v_add_u32_e32 v75, 0, v75
	v_add3_u32 v91, v75, v78, v79
	v_or_b32_e32 v75, 0x300, v71
	v_ashrrev_i32_e32 v75, 2, v75
	s_waitcnt lgkmcnt(3)
	v_pk_add_f32 v[168:169], v[66:67], v[136:137]
	v_pk_add_f32 v[66:67], v[66:67], v[136:137] neg_lo:[0,1] neg_hi:[0,1]
	s_waitcnt lgkmcnt(2)
	v_pk_add_f32 v[136:137], v[68:69], v[138:139]
	v_pk_add_f32 v[68:69], v[68:69], v[138:139] neg_lo:[0,1] neg_hi:[0,1]
	v_add_u32_e32 v75, 0, v75
	v_pk_mul_f32 v[138:139], v[68:69], s[18:19]
	v_add3_u32 v90, v75, v78, v79
	v_or_b32_e32 v75, 0x320, v71
	v_pk_fma_f32 v[68:69], v[68:69], s[20:21], v[138:139] op_sel:[0,0,1] op_sel_hi:[1,0,0]
	s_waitcnt lgkmcnt(1)
	v_pk_add_f32 v[138:139], v[72:73], v[140:141]
	v_pk_add_f32 v[72:73], v[72:73], v[140:141] neg_lo:[0,1] neg_hi:[0,1]
	v_ashrrev_i32_e32 v75, 2, v75
	v_pk_mul_f32 v[140:141], v[72:73], s[4:5]
	ds_read_b64 v[144:145], v94 offset:5120
	ds_read_b64 v[146:147], v93 offset:5376
	ds_read_b64 v[148:149], v92 offset:5632
	ds_read_b64 v[150:151], v91 offset:5888
	v_add_u32_e32 v75, 0, v75
	v_pk_fma_f32 v[72:73], v[72:73], s[6:7], v[140:141] op_sel:[0,0,1] op_sel_hi:[1,0,0]
	s_waitcnt lgkmcnt(4)
	v_pk_add_f32 v[140:141], v[76:77], v[142:143]
	v_pk_add_f32 v[76:77], v[76:77], v[142:143] neg_lo:[0,1] neg_hi:[0,1]
	v_add3_u32 v89, v75, v78, v79
	v_or_b32_e32 v75, 0x340, v71
	v_pk_mul_f32 v[142:143], v[76:77], s[22:23]
	v_ashrrev_i32_e32 v75, 2, v75
	v_pk_fma_f32 v[76:77], v[76:77], s[24:25], v[142:143] op_sel:[0,0,1] op_sel_hi:[1,0,0]
	s_waitcnt lgkmcnt(3)
	v_pk_add_f32 v[142:143], v[80:81], v[144:145]
	v_pk_add_f32 v[80:81], v[80:81], v[144:145] neg_lo:[0,1] neg_hi:[0,1]
	s_mov_b32 s9, s10
	v_add_u32_e32 v75, 0, v75
	v_pk_mul_f32 v[144:145], v[80:81], s[8:9]
	v_add3_u32 v88, v75, v78, v79
	v_or_b32_e32 v75, 0x360, v71
	v_pk_fma_f32 v[80:81], v[80:81], s[10:11], v[144:145] op_sel:[0,0,1] op_sel_hi:[1,0,0]
	s_waitcnt lgkmcnt(2)
	v_pk_add_f32 v[144:145], v[82:83], v[146:147]
	v_pk_add_f32 v[82:83], v[82:83], v[146:147] neg_lo:[0,1] neg_hi:[0,1]
	s_mov_b32 s27, s24
	v_ashrrev_i32_e32 v75, 2, v75
	v_pk_mul_f32 v[146:147], v[82:83], s[26:27]
	s_mov_b32 s0, s23
	v_add_u32_e32 v75, 0, v75
	v_pk_fma_f32 v[82:83], v[82:83], s[0:1], v[146:147] op_sel:[0,0,1] op_sel_hi:[1,0,0]
	s_waitcnt lgkmcnt(1)
	v_pk_add_f32 v[146:147], v[116:117], v[148:149]
	v_pk_add_f32 v[116:117], v[116:117], v[148:149] neg_lo:[0,1] neg_hi:[0,1]
	s_mov_b32 s13, s6
	v_add3_u32 v87, v75, v78, v79
	v_or_b32_e32 v75, 0x380, v71
	v_pk_mul_f32 v[148:149], v[116:117], s[12:13]
	ds_read_b64 v[152:153], v90 offset:6144
	ds_read_b64 v[154:155], v89 offset:6400
	ds_read_b64 v[156:157], v88 offset:6656
	ds_read_b64 v[158:159], v87 offset:6912
	v_ashrrev_i32_e32 v75, 2, v75
	v_pk_fma_f32 v[116:117], v[116:117], s[14:15], v[148:149] op_sel:[0,0,1] op_sel_hi:[1,0,0]
	s_waitcnt lgkmcnt(4)
	v_pk_add_f32 v[148:149], v[118:119], v[150:151]
	v_pk_add_f32 v[118:119], v[118:119], v[150:151] neg_lo:[0,1] neg_hi:[0,1]
	s_mov_b32 s35, s20
	v_add_u32_e32 v75, 0, v75
	v_pk_mul_f32 v[150:151], v[118:119], s[34:35]
	s_mov_b32 s44, s19
	v_add3_u32 v86, v75, v78, v79
	v_or_b32_e32 v75, 0x3a0, v71
	v_or_b32_e32 v71, 0x3c0, v71
	v_pk_fma_f32 v[118:119], v[118:119], s[44:45], v[150:151] op_sel:[0,0,1] op_sel_hi:[1,0,0]
	s_waitcnt lgkmcnt(3)
	v_pk_add_f32 v[150:151], v[120:121], v[152:153]
	v_pk_add_f32 v[152:153], v[120:121], v[152:153] op_sel:[1,1] op_sel_hi:[0,0] neg_lo:[0,1] neg_hi:[1,0]
	v_ashrrev_i32_e32 v71, 2, v71
	s_waitcnt lgkmcnt(2)
	v_pk_add_f32 v[120:121], v[122:123], v[154:155]
	v_pk_add_f32 v[122:123], v[122:123], v[154:155] neg_lo:[0,1] neg_hi:[0,1]
	v_add_u32_e32 v71, 0, v71
	v_or_b32_e32 v0, 0x3e0, v0
	v_pk_mul_f32 v[154:155], v[122:123], s[34:35]
	v_ashrrev_i32_e32 v75, 2, v75
	v_add3_u32 v84, v71, v78, v79
	v_ashrrev_i32_e32 v71, 2, v0
	v_pk_fma_f32 v[122:123], v[122:123], s[18:19], v[154:155] op_sel:[0,0,1] op_sel_hi:[1,0,0]
	s_waitcnt lgkmcnt(1)
	v_pk_add_f32 v[154:155], v[124:125], v[156:157]
	v_pk_add_f32 v[124:125], v[124:125], v[156:157] neg_lo:[0,1] neg_hi:[0,1]
	v_add_u32_e32 v75, 0, v75
	v_add_u32_e32 v71, 0, v71
	v_lshlrev_b32_e32 v0, 3, v0
	v_pk_mul_f32 v[156:157], v[124:125], s[12:13]
	v_add3_u32 v85, v75, v78, v79
	v_add3_u32 v0, v71, v0, v79
	ds_read_b64 v[160:161], v86 offset:7168
	ds_read_b64 v[162:163], v85 offset:7424
	ds_read_b64 v[164:165], v84 offset:7680
	ds_read_b64 v[166:167], v0
	v_pk_fma_f32 v[124:125], v[124:125], s[4:5], v[156:157] op_sel:[0,0,1] op_sel_hi:[1,0,0]
	s_waitcnt lgkmcnt(4)
	v_pk_add_f32 v[156:157], v[126:127], v[158:159]
	v_pk_add_f32 v[126:127], v[126:127], v[158:159] neg_lo:[0,1] neg_hi:[0,1]
	v_lshlrev_b32_e32 v70, 4, v70
	v_pk_mul_f32 v[158:159], v[126:127], s[26:27]
	v_cvt_f32_u32_e32 v75, v70
	v_pk_fma_f32 v[126:127], v[126:127], s[22:23], v[158:159] op_sel:[0,0,1] op_sel_hi:[1,0,0]
	s_waitcnt lgkmcnt(3)
	v_pk_add_f32 v[158:159], v[128:129], v[160:161]
	v_pk_add_f32 v[128:129], v[128:129], v[160:161] neg_lo:[0,1] neg_hi:[0,1]
	v_and_b32_e32 v74, 0x1fffffe0, v74
	v_pk_mul_f32 v[160:161], v[128:129], s[8:9]
	v_mul_f32_e32 v115, 0x38800000, v75
	v_pk_fma_f32 v[128:129], v[128:129], s[8:9], v[160:161] op_sel:[0,0,1] op_sel_hi:[1,0,0]
	s_waitcnt lgkmcnt(2)
	v_pk_add_f32 v[160:161], v[130:131], v[162:163]
	v_pk_add_f32 v[130:131], v[130:131], v[162:163] neg_lo:[0,1] neg_hi:[0,1]
	v_lshl_add_u32 v74, v74, 3, 0
	v_pk_mul_f32 v[162:163], v[130:131], s[22:23]
	v_sin_f32_e32 v75, v115
	v_pk_fma_f32 v[130:131], v[130:131], s[26:27], v[162:163] op_sel:[0,0,1] op_sel_hi:[1,0,0]
	s_waitcnt lgkmcnt(1)
	v_pk_add_f32 v[162:163], v[132:133], v[164:165]
	v_pk_add_f32 v[132:133], v[132:133], v[164:165] neg_lo:[0,1] neg_hi:[0,1]
	v_add3_u32 v74, v74, v78, v79
	v_pk_mul_f32 v[164:165], v[132:133], s[4:5]
	v_xor_b32_e32 v78, 0x80000000, v75
	v_pk_fma_f32 v[132:133], v[132:133], s[12:13], v[164:165] op_sel:[0,0,1] op_sel_hi:[1,0,0]
	s_waitcnt lgkmcnt(0)
	v_pk_add_f32 v[164:165], v[134:135], v[166:167]
	v_pk_add_f32 v[134:135], v[134:135], v[166:167] neg_lo:[0,1] neg_hi:[0,1]
	v_mov_b32_e32 v79, v75
	v_pk_mul_f32 v[166:167], v[134:135], s[18:19]
	s_add_u32 s41, s56, s42
	v_pk_fma_f32 v[134:135], v[134:135], s[34:35], v[166:167] op_sel:[0,0,1] op_sel_hi:[1,0,0]
	v_pk_add_f32 v[166:167], v[168:169], v[150:151]
	v_pk_add_f32 v[150:151], v[168:169], v[150:151] neg_lo:[0,1] neg_hi:[0,1]
	v_pk_add_f32 v[168:169], v[136:137], v[120:121]
	v_pk_add_f32 v[120:121], v[136:137], v[120:121] neg_lo:[0,1] neg_hi:[0,1]
	s_addc_u32 s61, s57, s43
	v_pk_mul_f32 v[136:137], v[120:121], s[4:5]
	s_nop 0
	v_pk_fma_f32 v[120:121], v[120:121], s[6:7], v[136:137] op_sel:[0,0,1] op_sel_hi:[1,0,0]
	v_pk_add_f32 v[136:137], v[138:139], v[154:155]
	v_pk_add_f32 v[138:139], v[138:139], v[154:155] neg_lo:[0,1] neg_hi:[0,1]
	s_nop 0
	v_pk_mul_f32 v[154:155], v[138:139], s[8:9]
	s_nop 0
	v_pk_fma_f32 v[138:139], v[138:139], s[10:11], v[154:155] op_sel:[0,0,1] op_sel_hi:[1,0,0]
	v_pk_add_f32 v[154:155], v[140:141], v[156:157]
	v_pk_add_f32 v[140:141], v[140:141], v[156:157] neg_lo:[0,1] neg_hi:[0,1]
	s_nop 0
	v_pk_mul_f32 v[156:157], v[140:141], s[12:13]
	s_nop 0
	v_pk_fma_f32 v[140:141], v[140:141], s[14:15], v[156:157] op_sel:[0,0,1] op_sel_hi:[1,0,0]
	v_pk_add_f32 v[156:157], v[142:143], v[158:159]
	v_pk_add_f32 v[158:159], v[142:143], v[158:159] op_sel:[1,1] op_sel_hi:[0,0] neg_lo:[0,1] neg_hi:[1,0]
	s_nop 0
	v_pk_add_f32 v[142:143], v[144:145], v[160:161]
	v_pk_add_f32 v[144:145], v[144:145], v[160:161] neg_lo:[0,1] neg_hi:[0,1]
	s_nop 0
	v_pk_mul_f32 v[160:161], v[144:145], s[12:13]
	s_nop 0
	v_pk_fma_f32 v[144:145], v[144:145], s[4:5], v[160:161] op_sel:[0,0,1] op_sel_hi:[1,0,0]
	v_pk_add_f32 v[160:161], v[146:147], v[162:163]
	v_pk_add_f32 v[146:147], v[146:147], v[162:163] neg_lo:[0,1] neg_hi:[0,1]
	s_nop 0
	v_pk_mul_f32 v[162:163], v[146:147], s[8:9]
	s_nop 0
	v_pk_fma_f32 v[146:147], v[146:147], s[8:9], v[162:163] op_sel:[0,0,1] op_sel_hi:[1,0,0]
	v_pk_add_f32 v[162:163], v[148:149], v[164:165]
	v_pk_add_f32 v[148:149], v[148:149], v[164:165] neg_lo:[0,1] neg_hi:[0,1]
	s_nop 0
	v_pk_mul_f32 v[164:165], v[148:149], s[4:5]
	s_nop 0
	v_pk_fma_f32 v[148:149], v[148:149], s[12:13], v[164:165] op_sel:[0,0,1] op_sel_hi:[1,0,0]
	v_pk_add_f32 v[164:165], v[66:67], v[152:153]
	v_pk_add_f32 v[66:67], v[66:67], v[152:153] neg_lo:[0,1] neg_hi:[0,1]
	v_pk_add_f32 v[152:153], v[68:69], v[122:123]
	v_pk_add_f32 v[68:69], v[68:69], v[122:123] neg_lo:[0,1] neg_hi:[0,1]
	s_nop 0
	v_pk_mul_f32 v[122:123], v[68:69], s[4:5]
	s_nop 0
	v_pk_fma_f32 v[68:69], v[68:69], s[6:7], v[122:123] op_sel:[0,0,1] op_sel_hi:[1,0,0]
	v_pk_add_f32 v[122:123], v[72:73], v[124:125]
	v_pk_add_f32 v[72:73], v[72:73], v[124:125] neg_lo:[0,1] neg_hi:[0,1]
	s_nop 0
	v_pk_mul_f32 v[124:125], v[72:73], s[8:9]
	s_nop 0
	v_pk_fma_f32 v[72:73], v[72:73], s[10:11], v[124:125] op_sel:[0,0,1] op_sel_hi:[1,0,0]
	v_pk_add_f32 v[124:125], v[76:77], v[126:127]
	v_pk_add_f32 v[76:77], v[76:77], v[126:127] neg_lo:[0,1] neg_hi:[0,1]
	s_nop 0
	v_pk_mul_f32 v[126:127], v[76:77], s[12:13]
	s_nop 0
	v_pk_fma_f32 v[76:77], v[76:77], s[14:15], v[126:127] op_sel:[0,0,1] op_sel_hi:[1,0,0]
	v_pk_add_f32 v[126:127], v[80:81], v[128:129]
	v_pk_add_f32 v[128:129], v[80:81], v[128:129] op_sel:[1,1] op_sel_hi:[0,0] neg_lo:[0,1] neg_hi:[1,0]
	s_nop 0
	v_pk_add_f32 v[80:81], v[82:83], v[130:131]
	v_pk_add_f32 v[82:83], v[82:83], v[130:131] neg_lo:[0,1] neg_hi:[0,1]
	s_nop 0
	v_pk_mul_f32 v[130:131], v[82:83], s[12:13]
	s_nop 0
	v_pk_fma_f32 v[82:83], v[82:83], s[4:5], v[130:131] op_sel:[0,0,1] op_sel_hi:[1,0,0]
	v_pk_add_f32 v[130:131], v[116:117], v[132:133]
	v_pk_add_f32 v[116:117], v[116:117], v[132:133] neg_lo:[0,1] neg_hi:[0,1]
	s_nop 0
	v_pk_mul_f32 v[132:133], v[116:117], s[8:9]
	s_nop 0
	v_pk_fma_f32 v[116:117], v[116:117], s[8:9], v[132:133] op_sel:[0,0,1] op_sel_hi:[1,0,0]
	v_pk_add_f32 v[132:133], v[118:119], v[134:135]
	v_pk_add_f32 v[118:119], v[118:119], v[134:135] neg_lo:[0,1] neg_hi:[0,1]
	s_nop 0
	v_pk_mul_f32 v[134:135], v[118:119], s[4:5]
	s_nop 0
	v_pk_fma_f32 v[118:119], v[118:119], s[12:13], v[134:135] op_sel:[0,0,1] op_sel_hi:[1,0,0]
	v_pk_add_f32 v[134:135], v[166:167], v[156:157]
	v_pk_add_f32 v[156:157], v[166:167], v[156:157] neg_lo:[0,1] neg_hi:[0,1]
	v_pk_add_f32 v[166:167], v[168:169], v[142:143]
	v_pk_add_f32 v[142:143], v[168:169], v[142:143] neg_lo:[0,1] neg_hi:[0,1]
	s_nop 0
	v_pk_mul_f32 v[168:169], v[142:143], s[8:9]
	s_nop 0
	v_pk_fma_f32 v[142:143], v[142:143], s[10:11], v[168:169] op_sel:[0,0,1] op_sel_hi:[1,0,0]
	v_pk_add_f32 v[168:169], v[136:137], v[160:161]
	v_pk_add_f32 v[160:161], v[136:137], v[160:161] op_sel:[1,1] op_sel_hi:[0,0] neg_lo:[0,1] neg_hi:[1,0]
	s_nop 0
	v_pk_add_f32 v[136:137], v[154:155], v[162:163]
	v_pk_add_f32 v[154:155], v[154:155], v[162:163] neg_lo:[0,1] neg_hi:[0,1]
	s_nop 0
	v_pk_mul_f32 v[162:163], v[154:155], s[8:9]
	s_nop 0
	v_pk_fma_f32 v[154:155], v[154:155], s[8:9], v[162:163] op_sel:[0,0,1] op_sel_hi:[1,0,0]
	v_pk_add_f32 v[162:163], v[150:151], v[158:159]
	v_pk_add_f32 v[150:151], v[150:151], v[158:159] neg_lo:[0,1] neg_hi:[0,1]
	v_pk_add_f32 v[158:159], v[120:121], v[144:145]
	v_pk_add_f32 v[120:121], v[120:121], v[144:145] neg_lo:[0,1] neg_hi:[0,1]
	s_nop 0
	v_pk_mul_f32 v[144:145], v[120:121], s[8:9]
	s_nop 0
	v_pk_fma_f32 v[120:121], v[120:121], s[10:11], v[144:145] op_sel:[0,0,1] op_sel_hi:[1,0,0]
	v_pk_add_f32 v[144:145], v[138:139], v[146:147]
	v_pk_add_f32 v[146:147], v[138:139], v[146:147] op_sel:[1,1] op_sel_hi:[0,0] neg_lo:[0,1] neg_hi:[1,0]
	s_nop 0
	v_pk_add_f32 v[138:139], v[140:141], v[148:149]
	v_pk_add_f32 v[140:141], v[140:141], v[148:149] neg_lo:[0,1] neg_hi:[0,1]
	s_nop 0
	v_pk_mul_f32 v[148:149], v[140:141], s[8:9]
	s_nop 0
	v_pk_fma_f32 v[140:141], v[140:141], s[8:9], v[148:149] op_sel:[0,0,1] op_sel_hi:[1,0,0]
	v_pk_add_f32 v[148:149], v[164:165], v[126:127]
	v_pk_add_f32 v[126:127], v[164:165], v[126:127] neg_lo:[0,1] neg_hi:[0,1]
	v_pk_add_f32 v[164:165], v[152:153], v[80:81]
	v_pk_add_f32 v[80:81], v[152:153], v[80:81] neg_lo:[0,1] neg_hi:[0,1]
	s_nop 0
	v_pk_mul_f32 v[152:153], v[80:81], s[8:9]
	s_nop 0
	v_pk_fma_f32 v[80:81], v[80:81], s[10:11], v[152:153] op_sel:[0,0,1] op_sel_hi:[1,0,0]
	v_pk_add_f32 v[152:153], v[122:123], v[130:131]
	v_pk_add_f32 v[130:131], v[122:123], v[130:131] op_sel:[1,1] op_sel_hi:[0,0] neg_lo:[0,1] neg_hi:[1,0]
	s_nop 0
	v_pk_add_f32 v[122:123], v[124:125], v[132:133]
	v_pk_add_f32 v[124:125], v[124:125], v[132:133] neg_lo:[0,1] neg_hi:[0,1]
	s_nop 0
	v_pk_mul_f32 v[132:133], v[124:125], s[8:9]
	s_nop 0
	v_pk_fma_f32 v[124:125], v[124:125], s[8:9], v[132:133] op_sel:[0,0,1] op_sel_hi:[1,0,0]
	v_pk_add_f32 v[132:133], v[66:67], v[128:129]
	v_pk_add_f32 v[66:67], v[66:67], v[128:129] neg_lo:[0,1] neg_hi:[0,1]
	v_pk_add_f32 v[128:129], v[68:69], v[82:83]
	v_pk_add_f32 v[68:69], v[68:69], v[82:83] neg_lo:[0,1] neg_hi:[0,1]
	s_nop 0
	v_pk_mul_f32 v[82:83], v[68:69], s[8:9]
	s_nop 0
	v_pk_fma_f32 v[68:69], v[68:69], s[10:11], v[82:83] op_sel:[0,0,1] op_sel_hi:[1,0,0]
	v_pk_add_f32 v[82:83], v[72:73], v[116:117]
	v_pk_add_f32 v[116:117], v[72:73], v[116:117] op_sel:[1,1] op_sel_hi:[0,0] neg_lo:[0,1] neg_hi:[1,0]
	s_nop 0
	v_pk_add_f32 v[72:73], v[76:77], v[118:119]
	v_pk_add_f32 v[76:77], v[76:77], v[118:119] neg_lo:[0,1] neg_hi:[0,1]
	v_pk_add_f32 v[174:175], v[66:67], v[116:117]
	v_pk_mul_f32 v[118:119], v[76:77], s[8:9]
	v_pk_add_f32 v[116:117], v[66:67], v[116:117] neg_lo:[0,1] neg_hi:[0,1]
	v_pk_fma_f32 v[76:77], v[76:77], s[8:9], v[118:119] op_sel:[0,0,1] op_sel_hi:[1,0,0]
	v_pk_add_f32 v[118:119], v[134:135], v[168:169]
	v_pk_add_f32 v[134:135], v[134:135], v[168:169] neg_lo:[0,1] neg_hi:[0,1]
	v_pk_add_f32 v[168:169], v[166:167], v[136:137]
	v_pk_add_f32 v[166:167], v[166:167], v[136:137] op_sel:[1,1] op_sel_hi:[0,0] neg_lo:[0,1] neg_hi:[1,0]
	v_pk_add_f32 v[180:181], v[118:119], v[168:169]
	v_pk_add_f32 v[136:137], v[156:157], v[160:161]
	v_pk_add_f32 v[156:157], v[156:157], v[160:161] neg_lo:[0,1] neg_hi:[0,1]
	v_pk_add_f32 v[160:161], v[142:143], v[154:155]
	v_pk_add_f32 v[154:155], v[142:143], v[154:155] op_sel:[1,1] op_sel_hi:[0,0] neg_lo:[0,1] neg_hi:[1,0]
	v_pk_add_f32 v[178:179], v[68:69], v[76:77] op_sel:[1,1] op_sel_hi:[0,0] neg_lo:[0,1] neg_hi:[1,0]
	v_pk_add_f32 v[142:143], v[162:163], v[144:145]
	v_pk_add_f32 v[144:145], v[162:163], v[144:145] neg_lo:[0,1] neg_hi:[0,1]
	v_pk_add_f32 v[162:163], v[158:159], v[138:139]
	v_pk_add_f32 v[158:159], v[158:159], v[138:139] op_sel:[1,1] op_sel_hi:[0,0] neg_lo:[0,1] neg_hi:[1,0]
	ds_write_b64 v74, v[180:181]
	v_pk_add_f32 v[138:139], v[150:151], v[146:147]
	v_pk_add_f32 v[146:147], v[150:151], v[146:147] neg_lo:[0,1] neg_hi:[0,1]
	v_pk_add_f32 v[150:151], v[120:121], v[140:141]
	v_pk_add_f32 v[140:141], v[120:121], v[140:141] op_sel:[1,1] op_sel_hi:[0,0] neg_lo:[0,1] neg_hi:[1,0]
	v_cos_f32_e32 v74, v115
	v_pk_add_f32 v[120:121], v[148:149], v[152:153]
	v_pk_add_f32 v[148:149], v[148:149], v[152:153] neg_lo:[0,1] neg_hi:[0,1]
	v_pk_add_f32 v[152:153], v[164:165], v[122:123]
	v_pk_add_f32 v[164:165], v[164:165], v[122:123] op_sel:[1,1] op_sel_hi:[0,0] neg_lo:[0,1] neg_hi:[1,0]
	v_pk_add_f32 v[122:123], v[126:127], v[130:131]
	v_pk_add_f32 v[126:127], v[126:127], v[130:131] neg_lo:[0,1] neg_hi:[0,1]
	v_pk_add_f32 v[130:131], v[80:81], v[124:125]
	v_pk_add_f32 v[124:125], v[80:81], v[124:125] op_sel:[1,1] op_sel_hi:[0,0] neg_lo:[0,1] neg_hi:[1,0]
	v_pk_add_f32 v[80:81], v[132:133], v[82:83]
	v_pk_add_f32 v[132:133], v[132:133], v[82:83] neg_lo:[0,1] neg_hi:[0,1]
	v_pk_add_f32 v[176:177], v[68:69], v[76:77]
	v_pk_add_f32 v[118:119], v[118:119], v[168:169] neg_lo:[0,1] neg_hi:[0,1]
	v_pk_add_f32 v[168:169], v[134:135], v[166:167]
	v_pk_add_f32 v[82:83], v[134:135], v[166:167] neg_lo:[0,1] neg_hi:[0,1]
	v_pk_add_f32 v[134:135], v[136:137], v[160:161]
	v_pk_add_f32 v[136:137], v[136:137], v[160:161] neg_lo:[0,1] neg_hi:[0,1]
	v_pk_add_f32 v[160:161], v[156:157], v[154:155]
	v_pk_add_f32 v[68:69], v[156:157], v[154:155] neg_lo:[0,1] neg_hi:[0,1]
	v_pk_add_f32 v[154:155], v[142:143], v[162:163]
	v_pk_add_f32 v[142:143], v[142:143], v[162:163] neg_lo:[0,1] neg_hi:[0,1]
	v_pk_add_f32 v[156:157], v[144:145], v[158:159]
	v_pk_add_f32 v[76:77], v[144:145], v[158:159] neg_lo:[0,1] neg_hi:[0,1]
	v_pk_add_f32 v[144:145], v[138:139], v[150:151]
	v_pk_add_f32 v[138:139], v[138:139], v[150:151] neg_lo:[0,1] neg_hi:[0,1]
	v_pk_add_f32 v[150:151], v[146:147], v[140:141]
	v_pk_add_f32 v[66:67], v[146:147], v[140:141] neg_lo:[0,1] neg_hi:[0,1]
	v_pk_add_f32 v[140:141], v[120:121], v[152:153]
	v_pk_add_f32 v[162:163], v[116:117], v[178:179]
	v_pk_add_f32 v[70:71], v[116:117], v[178:179] neg_lo:[0,1] neg_hi:[0,1]
	v_mov_b32_e32 v116, v75
	v_pk_mul_f32 v[116:117], v[116:117], v[140:141] op_sel:[0,1] op_sel_hi:[0,0] neg_hi:[1,0]
	v_pk_fma_f32 v[116:117], v[140:141], v[74:75], v[116:117] op_sel_hi:[1,0,1]
	ds_write_b64 v114, v[116:117] offset:256
	v_pk_mul_f32 v[114:115], v[78:79], v[74:75] op_sel:[0,1] op_sel_hi:[1,0]
	v_pk_add_f32 v[172:173], v[128:129], v[72:73]
	v_pk_fma_f32 v[114:115], v[74:75], v[74:75], v[114:115] op_sel_hi:[1,0,1]
	v_pk_add_f32 v[128:129], v[128:129], v[72:73] op_sel:[1,1] op_sel_hi:[0,0] neg_lo:[0,1] neg_hi:[1,0]
	v_pk_mul_f32 v[116:117], v[154:155], v[114:115] op_sel:[1,1] op_sel_hi:[0,1] neg_hi:[0,1]
	v_pk_fma_f32 v[116:117], v[154:155], v[114:115], v[116:117] op_sel_hi:[1,0,1]
	ds_write_b64 v113, v[116:117] offset:512
	v_pk_mul_f32 v[116:117], v[78:79], v[114:115] op_sel:[0,1] op_sel_hi:[1,0]
	v_pk_add_f32 v[120:121], v[120:121], v[152:153] neg_lo:[0,1] neg_hi:[0,1]
	v_pk_fma_f32 v[114:115], v[114:115], v[74:75], v[116:117] op_sel_hi:[1,0,1]
	v_pk_add_f32 v[152:153], v[122:123], v[130:131]
	v_pk_add_f32 v[122:123], v[122:123], v[130:131] neg_lo:[0,1] neg_hi:[0,1]
	v_pk_add_f32 v[130:131], v[126:127], v[124:125]
	v_pk_add_f32 v[72:73], v[126:127], v[124:125] neg_lo:[0,1] neg_hi:[0,1]
	v_pk_add_f32 v[124:125], v[80:81], v[172:173]
	v_pk_mul_f32 v[116:117], v[124:125], v[114:115] op_sel:[1,1] op_sel_hi:[0,1] neg_hi:[0,1]
	v_pk_add_f32 v[126:127], v[80:81], v[172:173] neg_lo:[0,1] neg_hi:[0,1]
	v_pk_fma_f32 v[116:117], v[124:125], v[114:115], v[116:117] op_sel_hi:[1,0,1]
	ds_write_b64 v112, v[116:117] offset:768
	v_pk_mul_f32 v[112:113], v[78:79], v[114:115] op_sel:[0,1] op_sel_hi:[1,0]
	v_pk_add_f32 v[158:159], v[132:133], v[128:129]
	v_pk_fma_f32 v[112:113], v[114:115], v[74:75], v[112:113] op_sel_hi:[1,0,1]
	v_pk_add_f32 v[80:81], v[132:133], v[128:129] neg_lo:[0,1] neg_hi:[0,1]
	v_pk_add_f32 v[128:129], v[174:175], v[176:177]
	v_pk_mul_f32 v[114:115], v[134:135], v[112:113] op_sel:[1,1] op_sel_hi:[0,1] neg_hi:[0,1]
	v_pk_add_f32 v[146:147], v[148:149], v[164:165]
	v_pk_fma_f32 v[114:115], v[134:135], v[112:113], v[114:115] op_sel_hi:[1,0,1]
	ds_write_b64 v111, v[114:115] offset:1024
	v_pk_mul_f32 v[114:115], v[78:79], v[112:113] op_sel:[0,1] op_sel_hi:[1,0]
	v_pk_add_f32 v[132:133], v[174:175], v[176:177] neg_lo:[0,1] neg_hi:[0,1]
	v_pk_fma_f32 v[112:113], v[112:113], v[74:75], v[114:115] op_sel_hi:[1,0,1]
	v_pk_add_f32 v[148:149], v[148:149], v[164:165] neg_lo:[0,1] neg_hi:[0,1]
	s_nop 0
	v_pk_mul_f32 v[114:115], v[152:153], v[112:113] op_sel:[1,1] op_sel_hi:[0,1] neg_hi:[0,1]
	s_nop 0
	v_pk_fma_f32 v[114:115], v[152:153], v[112:113], v[114:115] op_sel_hi:[1,0,1]
	ds_write_b64 v110, v[114:115] offset:1280
	v_pk_mul_f32 v[110:111], v[78:79], v[112:113] op_sel:[0,1] op_sel_hi:[1,0]
	s_nop 0
	v_pk_fma_f32 v[110:111], v[112:113], v[74:75], v[110:111] op_sel_hi:[1,0,1]
	s_nop 0
	s_nop 0
	v_pk_mul_f32 v[112:113], v[144:145], v[110:111] op_sel:[1,1] op_sel_hi:[0,1] neg_hi:[0,1]
	s_nop 0
	v_pk_fma_f32 v[112:113], v[144:145], v[110:111], v[112:113] op_sel_hi:[1,0,1]
	ds_write_b64 v109, v[112:113] offset:1536
	v_pk_mul_f32 v[112:113], v[78:79], v[110:111] op_sel:[0,1] op_sel_hi:[1,0]
	s_nop 0
	v_pk_fma_f32 v[110:111], v[110:111], v[74:75], v[112:113] op_sel_hi:[1,0,1]
	s_nop 0
	s_nop 0
	v_pk_mul_f32 v[112:113], v[128:129], v[110:111] op_sel:[1,1] op_sel_hi:[0,1] neg_hi:[0,1]
	s_nop 0
	v_pk_fma_f32 v[112:113], v[128:129], v[110:111], v[112:113] op_sel_hi:[1,0,1]
	ds_write_b64 v108, v[112:113] offset:1792
	v_pk_mul_f32 v[108:109], v[78:79], v[110:111] op_sel:[0,1] op_sel_hi:[1,0]
	s_nop 0
	v_pk_fma_f32 v[108:109], v[110:111], v[74:75], v[108:109] op_sel_hi:[1,0,1]
	s_nop 0
	s_nop 0
	v_pk_mul_f32 v[110:111], v[168:169], v[108:109] op_sel:[1,1] op_sel_hi:[0,1] neg_hi:[0,1]
	s_nop 0
	v_pk_fma_f32 v[110:111], v[168:169], v[108:109], v[110:111] op_sel_hi:[1,0,1]
	ds_write_b64 v107, v[110:111] offset:2048
	v_pk_mul_f32 v[110:111], v[78:79], v[108:109] op_sel:[0,1] op_sel_hi:[1,0]
	s_nop 0
	v_pk_fma_f32 v[108:109], v[108:109], v[74:75], v[110:111] op_sel_hi:[1,0,1]
	s_nop 0
	s_nop 0
	v_pk_mul_f32 v[110:111], v[146:147], v[108:109] op_sel:[1,1] op_sel_hi:[0,1] neg_hi:[0,1]
	s_nop 0
	v_pk_fma_f32 v[110:111], v[146:147], v[108:109], v[110:111] op_sel_hi:[1,0,1]
	ds_write_b64 v106, v[110:111] offset:2304
	v_pk_mul_f32 v[106:107], v[78:79], v[108:109] op_sel:[0,1] op_sel_hi:[1,0]
	s_nop 0
	v_pk_fma_f32 v[106:107], v[108:109], v[74:75], v[106:107] op_sel_hi:[1,0,1]
	s_nop 0
	s_nop 0
	v_pk_mul_f32 v[108:109], v[156:157], v[106:107] op_sel:[1,1] op_sel_hi:[0,1] neg_hi:[0,1]
	s_nop 0
	v_pk_fma_f32 v[108:109], v[156:157], v[106:107], v[108:109] op_sel_hi:[1,0,1]
	ds_write_b64 v105, v[108:109] offset:2560
	v_pk_mul_f32 v[108:109], v[78:79], v[106:107] op_sel:[0,1] op_sel_hi:[1,0]
	s_nop 0
	v_pk_fma_f32 v[106:107], v[106:107], v[74:75], v[108:109] op_sel_hi:[1,0,1]
	s_nop 0
	s_nop 0
	v_pk_mul_f32 v[108:109], v[158:159], v[106:107] op_sel:[1,1] op_sel_hi:[0,1] neg_hi:[0,1]
	s_nop 0
	v_pk_fma_f32 v[108:109], v[158:159], v[106:107], v[108:109] op_sel_hi:[1,0,1]
	ds_write_b64 v103, v[108:109] offset:2816
	v_pk_mul_f32 v[108:109], v[78:79], v[106:107] op_sel:[0,1] op_sel_hi:[1,0]
	s_nop 0
	v_pk_fma_f32 v[106:107], v[106:107], v[74:75], v[108:109] op_sel_hi:[1,0,1]
	s_nop 0
	s_nop 0
	v_pk_mul_f32 v[108:109], v[160:161], v[106:107] op_sel:[1,1] op_sel_hi:[0,1] neg_hi:[0,1]
	s_nop 0
	v_pk_fma_f32 v[108:109], v[160:161], v[106:107], v[108:109] op_sel_hi:[1,0,1]
	ds_write_b64 v102, v[108:109] offset:3072
	v_pk_mul_f32 v[102:103], v[78:79], v[106:107] op_sel:[0,1] op_sel_hi:[1,0]
	s_nop 0
	v_pk_fma_f32 v[102:103], v[106:107], v[74:75], v[102:103] op_sel_hi:[1,0,1]
	s_nop 0
	s_nop 0
	v_pk_mul_f32 v[106:107], v[130:131], v[102:103] op_sel:[1,1] op_sel_hi:[0,1] neg_hi:[0,1]
	s_nop 0
	v_pk_fma_f32 v[106:107], v[130:131], v[102:103], v[106:107] op_sel_hi:[1,0,1]
	ds_write_b64 v101, v[106:107] offset:3328
	v_pk_mul_f32 v[106:107], v[78:79], v[102:103] op_sel:[0,1] op_sel_hi:[1,0]
	s_nop 0
	v_pk_fma_f32 v[102:103], v[102:103], v[74:75], v[106:107] op_sel_hi:[1,0,1]
	s_nop 0
	s_nop 0
	v_pk_mul_f32 v[106:107], v[150:151], v[102:103] op_sel:[1,1] op_sel_hi:[0,1] neg_hi:[0,1]
	v_pk_fma_f32 v[106:107], v[150:151], v[102:103], v[106:107] op_sel_hi:[1,0,1]
	ds_write_b64 v100, v[106:107] offset:3584
	v_pk_mul_f32 v[100:101], v[78:79], v[102:103] op_sel:[0,1] op_sel_hi:[1,0]
	s_nop 0
	v_pk_fma_f32 v[100:101], v[102:103], v[74:75], v[100:101] op_sel_hi:[1,0,1]
	s_nop 0
	s_nop 0
	v_pk_mul_f32 v[102:103], v[162:163], v[100:101] op_sel:[1,1] op_sel_hi:[0,1] neg_hi:[0,1]
	v_pk_fma_f32 v[102:103], v[162:163], v[100:101], v[102:103] op_sel_hi:[1,0,1]
	ds_write_b64 v99, v[102:103] offset:3840
	v_pk_mul_f32 v[102:103], v[78:79], v[100:101] op_sel:[0,1] op_sel_hi:[1,0]
	s_nop 0
	v_pk_fma_f32 v[100:101], v[100:101], v[74:75], v[102:103] op_sel_hi:[1,0,1]
	s_nop 0
	s_nop 0
	v_pk_mul_f32 v[102:103], v[118:119], v[100:101] op_sel:[1,1] op_sel_hi:[0,1] neg_hi:[0,1]
	v_pk_fma_f32 v[102:103], v[118:119], v[100:101], v[102:103] op_sel_hi:[1,0,1]
	ds_write_b64 v98, v[102:103] offset:4096
	v_pk_mul_f32 v[98:99], v[78:79], v[100:101] op_sel:[0,1] op_sel_hi:[1,0]
	s_nop 0
	v_pk_fma_f32 v[98:99], v[100:101], v[74:75], v[98:99] op_sel_hi:[1,0,1]
	s_nop 0
	s_nop 0
	v_pk_mul_f32 v[100:101], v[120:121], v[98:99] op_sel:[1,1] op_sel_hi:[0,1] neg_hi:[0,1]
	v_pk_fma_f32 v[100:101], v[120:121], v[98:99], v[100:101] op_sel_hi:[1,0,1]
	ds_write_b64 v97, v[100:101] offset:4352
	v_pk_mul_f32 v[100:101], v[78:79], v[98:99] op_sel:[0,1] op_sel_hi:[1,0]
	s_nop 0
	v_pk_fma_f32 v[98:99], v[98:99], v[74:75], v[100:101] op_sel_hi:[1,0,1]
	s_nop 0
	s_nop 0
	v_pk_mul_f32 v[100:101], v[142:143], v[98:99] op_sel:[1,1] op_sel_hi:[0,1] neg_hi:[0,1]
	v_pk_fma_f32 v[100:101], v[142:143], v[98:99], v[100:101] op_sel_hi:[1,0,1]
	ds_write_b64 v96, v[100:101] offset:4608
	v_pk_mul_f32 v[96:97], v[78:79], v[98:99] op_sel:[0,1] op_sel_hi:[1,0]
	s_nop 0
	v_pk_fma_f32 v[96:97], v[98:99], v[74:75], v[96:97] op_sel_hi:[1,0,1]
	s_nop 0
	s_nop 0
	v_pk_mul_f32 v[98:99], v[126:127], v[96:97] op_sel:[1,1] op_sel_hi:[0,1] neg_hi:[0,1]
	v_pk_fma_f32 v[98:99], v[126:127], v[96:97], v[98:99] op_sel_hi:[1,0,1]
	ds_write_b64 v95, v[98:99] offset:4864
	v_pk_mul_f32 v[98:99], v[78:79], v[96:97] op_sel:[0,1] op_sel_hi:[1,0]
	s_nop 0
	v_pk_fma_f32 v[96:97], v[96:97], v[74:75], v[98:99] op_sel_hi:[1,0,1]
	s_nop 0
	s_nop 0
	v_pk_mul_f32 v[98:99], v[136:137], v[96:97] op_sel:[1,1] op_sel_hi:[0,1] neg_hi:[0,1]
	v_pk_fma_f32 v[98:99], v[136:137], v[96:97], v[98:99] op_sel_hi:[1,0,1]
	ds_write_b64 v94, v[98:99] offset:5120
	v_pk_mul_f32 v[94:95], v[78:79], v[96:97] op_sel:[0,1] op_sel_hi:[1,0]
	s_nop 0
	v_pk_fma_f32 v[94:95], v[96:97], v[74:75], v[94:95] op_sel_hi:[1,0,1]
	s_nop 0
	s_nop 0
	v_pk_mul_f32 v[96:97], v[122:123], v[94:95] op_sel:[1,1] op_sel_hi:[0,1] neg_hi:[0,1]
	v_pk_fma_f32 v[96:97], v[122:123], v[94:95], v[96:97] op_sel_hi:[1,0,1]
	ds_write_b64 v93, v[96:97] offset:5376
	v_pk_mul_f32 v[96:97], v[78:79], v[94:95] op_sel:[0,1] op_sel_hi:[1,0]
	s_nop 0
	v_pk_fma_f32 v[94:95], v[94:95], v[74:75], v[96:97] op_sel_hi:[1,0,1]
	s_nop 0
	s_nop 0
	v_pk_mul_f32 v[96:97], v[138:139], v[94:95] op_sel:[1,1] op_sel_hi:[0,1] neg_hi:[0,1]
	v_pk_fma_f32 v[96:97], v[138:139], v[94:95], v[96:97] op_sel_hi:[1,0,1]
	ds_write_b64 v92, v[96:97] offset:5632
	v_pk_mul_f32 v[92:93], v[78:79], v[94:95] op_sel:[0,1] op_sel_hi:[1,0]
	s_nop 0
	v_pk_fma_f32 v[92:93], v[94:95], v[74:75], v[92:93] op_sel_hi:[1,0,1]
	s_nop 0
	s_nop 0
	v_pk_mul_f32 v[94:95], v[132:133], v[92:93] op_sel:[1,1] op_sel_hi:[0,1] neg_hi:[0,1]
	v_pk_fma_f32 v[94:95], v[132:133], v[92:93], v[94:95] op_sel_hi:[1,0,1]
	ds_write_b64 v91, v[94:95] offset:5888
	v_pk_mul_f32 v[94:95], v[78:79], v[92:93] op_sel:[0,1] op_sel_hi:[1,0]
	s_nop 0
	v_pk_fma_f32 v[92:93], v[92:93], v[74:75], v[94:95] op_sel_hi:[1,0,1]
	s_nop 0
	s_nop 0
	v_pk_mul_f32 v[94:95], v[82:83], v[92:93] op_sel:[1,1] op_sel_hi:[0,1] neg_hi:[0,1]
	v_pk_fma_f32 v[82:83], v[82:83], v[92:93], v[94:95] op_sel_hi:[1,0,1]
	ds_write_b64 v90, v[82:83] offset:6144
	v_pk_mul_f32 v[82:83], v[78:79], v[92:93] op_sel:[0,1] op_sel_hi:[1,0]
	s_nop 0
	v_pk_fma_f32 v[82:83], v[92:93], v[74:75], v[82:83] op_sel_hi:[1,0,1]
	s_nop 0
	s_nop 0
	v_pk_mul_f32 v[90:91], v[148:149], v[82:83] op_sel:[1,1] op_sel_hi:[0,1] neg_hi:[0,1]
	v_pk_fma_f32 v[90:91], v[148:149], v[82:83], v[90:91] op_sel_hi:[1,0,1]
	ds_write_b64 v89, v[90:91] offset:6400
	v_pk_mul_f32 v[90:91], v[78:79], v[82:83] op_sel:[0,1] op_sel_hi:[1,0]
	s_nop 0
	v_pk_fma_f32 v[82:83], v[82:83], v[74:75], v[90:91] op_sel_hi:[1,0,1]
	s_nop 0
	s_nop 0
	v_pk_mul_f32 v[90:91], v[76:77], v[82:83] op_sel:[1,1] op_sel_hi:[0,1] neg_hi:[0,1]
	v_pk_fma_f32 v[76:77], v[76:77], v[82:83], v[90:91] op_sel_hi:[1,0,1]
	ds_write_b64 v88, v[76:77] offset:6656
	v_pk_mul_f32 v[76:77], v[78:79], v[82:83] op_sel:[0,1] op_sel_hi:[1,0]
	s_nop 0
	v_pk_fma_f32 v[76:77], v[82:83], v[74:75], v[76:77] op_sel_hi:[1,0,1]
	s_nop 0
	s_nop 0
	v_pk_mul_f32 v[82:83], v[80:81], v[76:77] op_sel:[1,1] op_sel_hi:[0,1] neg_hi:[0,1]
	v_pk_fma_f32 v[80:81], v[80:81], v[76:77], v[82:83] op_sel_hi:[1,0,1]
	ds_write_b64 v87, v[80:81] offset:6912
	v_pk_mul_f32 v[80:81], v[78:79], v[76:77] op_sel:[0,1] op_sel_hi:[1,0]
	s_nop 0
	v_pk_fma_f32 v[76:77], v[76:77], v[74:75], v[80:81] op_sel_hi:[1,0,1]
	s_nop 0
	s_nop 0
	v_pk_mul_f32 v[80:81], v[68:69], v[76:77] op_sel:[1,1] op_sel_hi:[0,1] neg_hi:[0,1]
	v_pk_fma_f32 v[68:69], v[68:69], v[76:77], v[80:81] op_sel_hi:[1,0,1]
	ds_write_b64 v86, v[68:69] offset:7168
	v_pk_mul_f32 v[68:69], v[78:79], v[76:77] op_sel:[0,1] op_sel_hi:[1,0]
	s_nop 0
	v_pk_fma_f32 v[68:69], v[76:77], v[74:75], v[68:69] op_sel_hi:[1,0,1]
	s_nop 0
	s_nop 0
	v_pk_mul_f32 v[76:77], v[72:73], v[68:69] op_sel:[1,1] op_sel_hi:[0,1] neg_hi:[0,1]
	v_pk_fma_f32 v[72:73], v[72:73], v[68:69], v[76:77] op_sel_hi:[1,0,1]
	ds_write_b64 v85, v[72:73] offset:7424
	v_pk_mul_f32 v[72:73], v[78:79], v[68:69] op_sel:[0,1] op_sel_hi:[1,0]
	s_nop 0
	v_pk_fma_f32 v[68:69], v[68:69], v[74:75], v[72:73] op_sel_hi:[1,0,1]
	s_nop 0
	s_nop 0
	v_pk_mul_f32 v[72:73], v[66:67], v[68:69] op_sel:[1,1] op_sel_hi:[0,1] neg_hi:[0,1]
	v_pk_fma_f32 v[66:67], v[66:67], v[68:69], v[72:73] op_sel_hi:[1,0,1]
	ds_write_b64 v84, v[66:67] offset:7680
	v_pk_mul_f32 v[66:67], v[78:79], v[68:69] op_sel:[0,1] op_sel_hi:[1,0]
	s_nop 0
	v_pk_fma_f32 v[66:67], v[68:69], v[74:75], v[66:67] op_sel_hi:[1,0,1]
	s_nop 0
	s_nop 0
	v_pk_mul_f32 v[68:69], v[70:71], v[66:67] op_sel:[1,1] op_sel_hi:[0,1] neg_hi:[0,1]
	v_pk_fma_f32 v[66:67], v[70:71], v[66:67], v[68:69] op_sel_hi:[1,0,1]
	ds_write_b64 v0, v[66:67]
	s_waitcnt lgkmcnt(0)
	s_barrier
	ds_read2_b64 v[66:69], v104 offset1:1
	ds_read2_b64 v[70:73], v104 offset0:2 offset1:3
	ds_read2_b64 v[74:77], v104 offset0:4 offset1:5
	ds_read2_b64 v[78:81], v104 offset0:6 offset1:7
	ds_read2_b64 v[82:85], v104 offset0:8 offset1:9
	ds_read2_b64 v[86:89], v104 offset0:10 offset1:11
	ds_read2_b64 v[90:93], v104 offset0:12 offset1:13
	ds_read2_b64 v[94:97], v104 offset0:14 offset1:15
	ds_read2_b64 v[98:101], v104 offset0:16 offset1:17
	ds_read2_b64 v[106:109], v104 offset0:18 offset1:19
	ds_read2_b64 v[110:113], v104 offset0:20 offset1:21
	ds_read2_b64 v[114:117], v104 offset0:22 offset1:23
	ds_read2_b64 v[118:121], v104 offset0:24 offset1:25
	ds_read2_b64 v[122:125], v104 offset0:26 offset1:27
	ds_read2_b64 v[126:129], v104 offset0:28 offset1:29
	ds_read2_b64 v[130:133], v104 offset0:30 offset1:31
	s_waitcnt lgkmcnt(7)
	v_pk_add_f32 v[102:103], v[66:67], v[98:99]
	v_pk_add_f32 v[66:67], v[66:67], v[98:99] neg_lo:[0,1] neg_hi:[0,1]
	v_pk_add_f32 v[98:99], v[68:69], v[100:101]
	v_pk_add_f32 v[68:69], v[68:69], v[100:101] neg_lo:[0,1] neg_hi:[0,1]
	s_nop 0
	v_pk_mul_f32 v[100:101], v[68:69], s[18:19]
	s_nop 0
	v_pk_fma_f32 v[68:69], v[68:69], s[20:21], v[100:101] op_sel:[0,0,1] op_sel_hi:[1,0,0]
	s_waitcnt lgkmcnt(6)
	v_pk_add_f32 v[100:101], v[70:71], v[106:107]
	v_pk_add_f32 v[70:71], v[70:71], v[106:107] neg_lo:[0,1] neg_hi:[0,1]
	s_nop 0
	v_pk_mul_f32 v[106:107], v[70:71], s[4:5]
	s_nop 0
	v_pk_fma_f32 v[70:71], v[70:71], s[6:7], v[106:107] op_sel:[0,0,1] op_sel_hi:[1,0,0]
	v_pk_add_f32 v[106:107], v[72:73], v[108:109]
	v_pk_add_f32 v[72:73], v[72:73], v[108:109] neg_lo:[0,1] neg_hi:[0,1]
	s_nop 0
	v_pk_mul_f32 v[108:109], v[72:73], s[22:23]
	s_nop 0
	v_pk_fma_f32 v[72:73], v[72:73], s[24:25], v[108:109] op_sel:[0,0,1] op_sel_hi:[1,0,0]
	s_waitcnt lgkmcnt(5)
	v_pk_add_f32 v[108:109], v[74:75], v[110:111]
	v_pk_add_f32 v[74:75], v[74:75], v[110:111] neg_lo:[0,1] neg_hi:[0,1]
	s_nop 0
	v_pk_mul_f32 v[110:111], v[74:75], s[8:9]
	s_nop 0
	v_pk_fma_f32 v[74:75], v[74:75], s[10:11], v[110:111] op_sel:[0,0,1] op_sel_hi:[1,0,0]
	v_pk_add_f32 v[110:111], v[76:77], v[112:113]
	v_pk_add_f32 v[76:77], v[76:77], v[112:113] neg_lo:[0,1] neg_hi:[0,1]
	s_nop 0
	v_pk_mul_f32 v[112:113], v[76:77], s[26:27]
	s_nop 0
	v_pk_fma_f32 v[76:77], v[76:77], s[0:1], v[112:113] op_sel:[0,0,1] op_sel_hi:[1,0,0]
	s_waitcnt lgkmcnt(4)
	v_pk_add_f32 v[112:113], v[78:79], v[114:115]
	v_pk_add_f32 v[78:79], v[78:79], v[114:115] neg_lo:[0,1] neg_hi:[0,1]
	s_mov_b64 s[0:1], 0
	v_pk_mul_f32 v[114:115], v[78:79], s[12:13]
	s_nop 0
	v_pk_fma_f32 v[78:79], v[78:79], s[14:15], v[114:115] op_sel:[0,0,1] op_sel_hi:[1,0,0]
	v_pk_add_f32 v[114:115], v[80:81], v[116:117]
	v_pk_add_f32 v[80:81], v[80:81], v[116:117] neg_lo:[0,1] neg_hi:[0,1]
	s_nop 0
	v_pk_mul_f32 v[116:117], v[80:81], s[34:35]
	s_nop 0
	v_pk_fma_f32 v[80:81], v[80:81], s[44:45], v[116:117] op_sel:[0,0,1] op_sel_hi:[1,0,0]
	s_waitcnt lgkmcnt(3)
	v_pk_add_f32 v[116:117], v[82:83], v[118:119]
	v_pk_add_f32 v[118:119], v[82:83], v[118:119] op_sel:[1,1] op_sel_hi:[0,0] neg_lo:[0,1] neg_hi:[1,0]
	s_mov_b64 s[44:45], -1
	v_pk_add_f32 v[82:83], v[84:85], v[120:121]
	v_pk_add_f32 v[84:85], v[84:85], v[120:121] neg_lo:[0,1] neg_hi:[0,1]
	s_nop 0
	v_pk_mul_f32 v[120:121], v[84:85], s[34:35]
	s_nop 0
	v_pk_fma_f32 v[84:85], v[84:85], s[18:19], v[120:121] op_sel:[0,0,1] op_sel_hi:[1,0,0]
	s_waitcnt lgkmcnt(2)
	v_pk_add_f32 v[120:121], v[86:87], v[122:123]
	v_pk_add_f32 v[86:87], v[86:87], v[122:123] neg_lo:[0,1] neg_hi:[0,1]
	s_nop 0
	v_pk_mul_f32 v[122:123], v[86:87], s[12:13]
	s_nop 0
	v_pk_fma_f32 v[86:87], v[86:87], s[4:5], v[122:123] op_sel:[0,0,1] op_sel_hi:[1,0,0]
	v_pk_add_f32 v[122:123], v[88:89], v[124:125]
	v_pk_add_f32 v[88:89], v[88:89], v[124:125] neg_lo:[0,1] neg_hi:[0,1]
	s_nop 0
	v_pk_mul_f32 v[124:125], v[88:89], s[26:27]
	s_nop 0
	v_pk_fma_f32 v[88:89], v[88:89], s[22:23], v[124:125] op_sel:[0,0,1] op_sel_hi:[1,0,0]
	s_waitcnt lgkmcnt(1)
	v_pk_add_f32 v[124:125], v[90:91], v[126:127]
	v_pk_add_f32 v[90:91], v[90:91], v[126:127] neg_lo:[0,1] neg_hi:[0,1]
	s_nop 0
	v_pk_mul_f32 v[126:127], v[90:91], s[8:9]
	s_nop 0
	v_pk_fma_f32 v[90:91], v[90:91], s[8:9], v[126:127] op_sel:[0,0,1] op_sel_hi:[1,0,0]
	v_pk_add_f32 v[126:127], v[92:93], v[128:129]
	v_pk_add_f32 v[92:93], v[92:93], v[128:129] neg_lo:[0,1] neg_hi:[0,1]
	s_nop 0
	v_pk_mul_f32 v[128:129], v[92:93], s[22:23]
	s_nop 0
	v_pk_fma_f32 v[92:93], v[92:93], s[26:27], v[128:129] op_sel:[0,0,1] op_sel_hi:[1,0,0]
	s_waitcnt lgkmcnt(0)
	v_pk_add_f32 v[128:129], v[94:95], v[130:131]
	v_pk_add_f32 v[94:95], v[94:95], v[130:131] neg_lo:[0,1] neg_hi:[0,1]
	s_nop 0
	v_pk_mul_f32 v[130:131], v[94:95], s[4:5]
	s_nop 0
	v_pk_fma_f32 v[94:95], v[94:95], s[12:13], v[130:131] op_sel:[0,0,1] op_sel_hi:[1,0,0]
	v_pk_add_f32 v[130:131], v[96:97], v[132:133]
	v_pk_add_f32 v[96:97], v[96:97], v[132:133] neg_lo:[0,1] neg_hi:[0,1]
	s_nop 0
	v_pk_mul_f32 v[132:133], v[96:97], s[18:19]
	s_nop 0
	v_pk_fma_f32 v[96:97], v[96:97], s[34:35], v[132:133] op_sel:[0,0,1] op_sel_hi:[1,0,0]
	v_pk_add_f32 v[132:133], v[102:103], v[116:117]
	v_pk_add_f32 v[102:103], v[102:103], v[116:117] neg_lo:[0,1] neg_hi:[0,1]
	v_pk_add_f32 v[116:117], v[98:99], v[82:83]
	v_pk_add_f32 v[82:83], v[98:99], v[82:83] neg_lo:[0,1] neg_hi:[0,1]
	s_nop 0
	v_pk_mul_f32 v[98:99], v[82:83], s[4:5]
	s_nop 0
	v_pk_fma_f32 v[82:83], v[82:83], s[6:7], v[98:99] op_sel:[0,0,1] op_sel_hi:[1,0,0]
	v_pk_add_f32 v[98:99], v[100:101], v[120:121]
	v_pk_add_f32 v[100:101], v[100:101], v[120:121] neg_lo:[0,1] neg_hi:[0,1]
	s_nop 0
	v_pk_mul_f32 v[120:121], v[100:101], s[8:9]
	s_nop 0
	v_pk_fma_f32 v[100:101], v[100:101], s[10:11], v[120:121] op_sel:[0,0,1] op_sel_hi:[1,0,0]
	v_pk_add_f32 v[120:121], v[106:107], v[122:123]
	v_pk_add_f32 v[106:107], v[106:107], v[122:123] neg_lo:[0,1] neg_hi:[0,1]
	s_nop 0
	v_pk_mul_f32 v[122:123], v[106:107], s[12:13]
	s_nop 0
	v_pk_fma_f32 v[106:107], v[106:107], s[14:15], v[122:123] op_sel:[0,0,1] op_sel_hi:[1,0,0]
	v_pk_add_f32 v[122:123], v[108:109], v[124:125]
	v_pk_add_f32 v[124:125], v[108:109], v[124:125] op_sel:[1,1] op_sel_hi:[0,0] neg_lo:[0,1] neg_hi:[1,0]
	s_nop 0
	v_pk_add_f32 v[108:109], v[110:111], v[126:127]
	v_pk_add_f32 v[110:111], v[110:111], v[126:127] neg_lo:[0,1] neg_hi:[0,1]
	s_nop 0
	v_pk_mul_f32 v[126:127], v[110:111], s[12:13]
	s_nop 0
	v_pk_fma_f32 v[110:111], v[110:111], s[4:5], v[126:127] op_sel:[0,0,1] op_sel_hi:[1,0,0]
	v_pk_add_f32 v[126:127], v[112:113], v[128:129]
	v_pk_add_f32 v[112:113], v[112:113], v[128:129] neg_lo:[0,1] neg_hi:[0,1]
	s_nop 0
	v_pk_mul_f32 v[128:129], v[112:113], s[8:9]
	s_nop 0
	v_pk_fma_f32 v[112:113], v[112:113], s[8:9], v[128:129] op_sel:[0,0,1] op_sel_hi:[1,0,0]
	v_pk_add_f32 v[128:129], v[114:115], v[130:131]
	v_pk_add_f32 v[114:115], v[114:115], v[130:131] neg_lo:[0,1] neg_hi:[0,1]
	s_nop 0
	v_pk_mul_f32 v[130:131], v[114:115], s[4:5]
	s_nop 0
	v_pk_fma_f32 v[114:115], v[114:115], s[12:13], v[130:131] op_sel:[0,0,1] op_sel_hi:[1,0,0]
	v_pk_add_f32 v[130:131], v[66:67], v[118:119]
	v_pk_add_f32 v[66:67], v[66:67], v[118:119] neg_lo:[0,1] neg_hi:[0,1]
	v_pk_add_f32 v[118:119], v[68:69], v[84:85]
	v_pk_add_f32 v[68:69], v[68:69], v[84:85] neg_lo:[0,1] neg_hi:[0,1]
	s_nop 0
	v_pk_mul_f32 v[84:85], v[68:69], s[4:5]
	s_nop 0
	v_pk_fma_f32 v[68:69], v[68:69], s[6:7], v[84:85] op_sel:[0,0,1] op_sel_hi:[1,0,0]
	v_pk_add_f32 v[84:85], v[70:71], v[86:87]
	v_pk_add_f32 v[70:71], v[70:71], v[86:87] neg_lo:[0,1] neg_hi:[0,1]
	s_nop 0
	v_pk_mul_f32 v[86:87], v[70:71], s[8:9]
	s_nop 0
	v_pk_fma_f32 v[70:71], v[70:71], s[10:11], v[86:87] op_sel:[0,0,1] op_sel_hi:[1,0,0]
	v_pk_add_f32 v[86:87], v[72:73], v[88:89]
	v_pk_add_f32 v[72:73], v[72:73], v[88:89] neg_lo:[0,1] neg_hi:[0,1]
	s_nop 0
	v_pk_mul_f32 v[88:89], v[72:73], s[12:13]
	s_nop 0
	v_pk_fma_f32 v[72:73], v[72:73], s[14:15], v[88:89] op_sel:[0,0,1] op_sel_hi:[1,0,0]
	v_pk_add_f32 v[88:89], v[74:75], v[90:91]
	v_pk_add_f32 v[90:91], v[74:75], v[90:91] op_sel:[1,1] op_sel_hi:[0,0] neg_lo:[0,1] neg_hi:[1,0]
	s_nop 0
	v_pk_add_f32 v[74:75], v[76:77], v[92:93]
	v_pk_add_f32 v[76:77], v[76:77], v[92:93] neg_lo:[0,1] neg_hi:[0,1]
	s_nop 0
	v_pk_mul_f32 v[92:93], v[76:77], s[12:13]
	s_nop 0
	v_pk_fma_f32 v[76:77], v[76:77], s[4:5], v[92:93] op_sel:[0,0,1] op_sel_hi:[1,0,0]
	v_pk_add_f32 v[92:93], v[78:79], v[94:95]
	v_pk_add_f32 v[78:79], v[78:79], v[94:95] neg_lo:[0,1] neg_hi:[0,1]
	s_nop 0
	v_pk_mul_f32 v[94:95], v[78:79], s[8:9]
	s_nop 0
	v_pk_fma_f32 v[78:79], v[78:79], s[8:9], v[94:95] op_sel:[0,0,1] op_sel_hi:[1,0,0]
	v_pk_add_f32 v[94:95], v[80:81], v[96:97]
	v_pk_add_f32 v[80:81], v[80:81], v[96:97] neg_lo:[0,1] neg_hi:[0,1]
	s_nop 0
	v_pk_mul_f32 v[96:97], v[80:81], s[4:5]
	s_nop 0
	v_pk_fma_f32 v[80:81], v[80:81], s[12:13], v[96:97] op_sel:[0,0,1] op_sel_hi:[1,0,0]
	v_pk_add_f32 v[96:97], v[132:133], v[122:123]
	v_pk_add_f32 v[122:123], v[132:133], v[122:123] neg_lo:[0,1] neg_hi:[0,1]
	v_pk_add_f32 v[132:133], v[116:117], v[108:109]
	v_pk_add_f32 v[108:109], v[116:117], v[108:109] neg_lo:[0,1] neg_hi:[0,1]
	s_nop 0
	v_pk_mul_f32 v[116:117], v[108:109], s[8:9]
	s_nop 0
	v_pk_fma_f32 v[108:109], v[108:109], s[10:11], v[116:117] op_sel:[0,0,1] op_sel_hi:[1,0,0]
	v_pk_add_f32 v[116:117], v[98:99], v[126:127]
	v_pk_add_f32 v[126:127], v[98:99], v[126:127] op_sel:[1,1] op_sel_hi:[0,0] neg_lo:[0,1] neg_hi:[1,0]
	s_nop 0
	v_pk_add_f32 v[98:99], v[120:121], v[128:129]
	v_pk_add_f32 v[120:121], v[120:121], v[128:129] neg_lo:[0,1] neg_hi:[0,1]
	s_nop 0
	v_pk_mul_f32 v[128:129], v[120:121], s[8:9]
	s_nop 0
	v_pk_fma_f32 v[120:121], v[120:121], s[8:9], v[128:129] op_sel:[0,0,1] op_sel_hi:[1,0,0]
	v_pk_add_f32 v[128:129], v[102:103], v[124:125]
	v_pk_add_f32 v[102:103], v[102:103], v[124:125] neg_lo:[0,1] neg_hi:[0,1]
	v_pk_add_f32 v[124:125], v[82:83], v[110:111]
	v_pk_add_f32 v[82:83], v[82:83], v[110:111] neg_lo:[0,1] neg_hi:[0,1]
	s_nop 0
	v_pk_mul_f32 v[110:111], v[82:83], s[8:9]
	s_nop 0
	v_pk_fma_f32 v[82:83], v[82:83], s[10:11], v[110:111] op_sel:[0,0,1] op_sel_hi:[1,0,0]
	v_pk_add_f32 v[110:111], v[100:101], v[112:113]
	v_pk_add_f32 v[112:113], v[100:101], v[112:113] op_sel:[1,1] op_sel_hi:[0,0] neg_lo:[0,1] neg_hi:[1,0]
	s_nop 0
	v_pk_add_f32 v[100:101], v[106:107], v[114:115]
	v_pk_add_f32 v[106:107], v[106:107], v[114:115] neg_lo:[0,1] neg_hi:[0,1]
	s_nop 0
	v_pk_mul_f32 v[114:115], v[106:107], s[8:9]
	s_nop 0
	v_pk_fma_f32 v[106:107], v[106:107], s[8:9], v[114:115] op_sel:[0,0,1] op_sel_hi:[1,0,0]
	v_pk_add_f32 v[114:115], v[130:131], v[88:89]
	v_pk_add_f32 v[88:89], v[130:131], v[88:89] neg_lo:[0,1] neg_hi:[0,1]
	v_pk_add_f32 v[130:131], v[118:119], v[74:75]
	v_pk_add_f32 v[74:75], v[118:119], v[74:75] neg_lo:[0,1] neg_hi:[0,1]
	s_nop 0
	v_pk_mul_f32 v[118:119], v[74:75], s[8:9]
	s_nop 0
	v_pk_fma_f32 v[74:75], v[74:75], s[10:11], v[118:119] op_sel:[0,0,1] op_sel_hi:[1,0,0]
	v_pk_add_f32 v[118:119], v[84:85], v[92:93]
	v_pk_add_f32 v[92:93], v[84:85], v[92:93] op_sel:[1,1] op_sel_hi:[0,0] neg_lo:[0,1] neg_hi:[1,0]
	s_nop 0
	v_pk_add_f32 v[84:85], v[86:87], v[94:95]
	v_pk_add_f32 v[86:87], v[86:87], v[94:95] neg_lo:[0,1] neg_hi:[0,1]
	s_nop 0
	v_pk_mul_f32 v[94:95], v[86:87], s[8:9]
	s_nop 0
	v_pk_fma_f32 v[86:87], v[86:87], s[8:9], v[94:95] op_sel:[0,0,1] op_sel_hi:[1,0,0]
	v_pk_add_f32 v[94:95], v[66:67], v[90:91]
	v_pk_add_f32 v[66:67], v[66:67], v[90:91] neg_lo:[0,1] neg_hi:[0,1]
	v_pk_add_f32 v[90:91], v[68:69], v[76:77]
	v_pk_add_f32 v[68:69], v[68:69], v[76:77] neg_lo:[0,1] neg_hi:[0,1]
	s_nop 0
	v_pk_mul_f32 v[76:77], v[68:69], s[8:9]
	s_nop 0
	v_pk_fma_f32 v[68:69], v[68:69], s[10:11], v[76:77] op_sel:[0,0,1] op_sel_hi:[1,0,0]
	v_pk_add_f32 v[76:77], v[70:71], v[78:79]
	v_pk_add_f32 v[78:79], v[70:71], v[78:79] op_sel:[1,1] op_sel_hi:[0,0] neg_lo:[0,1] neg_hi:[1,0]
	s_nop 0
	v_pk_add_f32 v[70:71], v[72:73], v[80:81]
	v_pk_add_f32 v[72:73], v[72:73], v[80:81] neg_lo:[0,1] neg_hi:[0,1]
	s_nop 0
	v_pk_mul_f32 v[80:81], v[72:73], s[8:9]
	s_nop 0
	v_pk_fma_f32 v[72:73], v[72:73], s[8:9], v[80:81] op_sel:[0,0,1] op_sel_hi:[1,0,0]
	v_pk_add_f32 v[80:81], v[96:97], v[116:117]
	v_pk_add_f32 v[96:97], v[96:97], v[116:117] neg_lo:[0,1] neg_hi:[0,1]
	v_pk_add_f32 v[116:117], v[132:133], v[98:99]
	v_pk_add_f32 v[132:133], v[132:133], v[98:99] op_sel:[1,1] op_sel_hi:[0,0] neg_lo:[0,1] neg_hi:[1,0]
	s_nop 0
	v_pk_add_f32 v[98:99], v[122:123], v[126:127]
	v_pk_add_f32 v[122:123], v[122:123], v[126:127] neg_lo:[0,1] neg_hi:[0,1]
	v_pk_add_f32 v[126:127], v[108:109], v[120:121]
	v_pk_add_f32 v[120:121], v[108:109], v[120:121] op_sel:[1,1] op_sel_hi:[0,0] neg_lo:[0,1] neg_hi:[1,0]
	s_nop 0
	v_pk_add_f32 v[108:109], v[128:129], v[110:111]
	v_pk_add_f32 v[110:111], v[128:129], v[110:111] neg_lo:[0,1] neg_hi:[0,1]
	v_pk_add_f32 v[128:129], v[124:125], v[100:101]
	v_pk_add_f32 v[124:125], v[124:125], v[100:101] op_sel:[1,1] op_sel_hi:[0,0] neg_lo:[0,1] neg_hi:[1,0]
	s_nop 0
	v_pk_add_f32 v[100:101], v[102:103], v[112:113]
	v_pk_add_f32 v[102:103], v[102:103], v[112:113] neg_lo:[0,1] neg_hi:[0,1]
	v_pk_add_f32 v[112:113], v[82:83], v[106:107]
	v_pk_add_f32 v[106:107], v[82:83], v[106:107] op_sel:[1,1] op_sel_hi:[0,0] neg_lo:[0,1] neg_hi:[1,0]
	s_nop 0
	v_pk_add_f32 v[82:83], v[114:115], v[118:119]
	v_pk_add_f32 v[114:115], v[114:115], v[118:119] neg_lo:[0,1] neg_hi:[0,1]
	v_pk_add_f32 v[118:119], v[130:131], v[84:85]
	v_pk_add_f32 v[130:131], v[130:131], v[84:85] op_sel:[1,1] op_sel_hi:[0,0] neg_lo:[0,1] neg_hi:[1,0]
	s_nop 0
	v_pk_add_f32 v[84:85], v[88:89], v[92:93]
	v_pk_add_f32 v[88:89], v[88:89], v[92:93] neg_lo:[0,1] neg_hi:[0,1]
	v_pk_add_f32 v[92:93], v[74:75], v[86:87]
	v_pk_add_f32 v[86:87], v[74:75], v[86:87] op_sel:[1,1] op_sel_hi:[0,0] neg_lo:[0,1] neg_hi:[1,0]
	s_nop 0
	v_pk_add_f32 v[74:75], v[94:95], v[76:77]
	v_pk_add_f32 v[76:77], v[94:95], v[76:77] neg_lo:[0,1] neg_hi:[0,1]
	v_pk_add_f32 v[94:95], v[90:91], v[70:71]
	v_pk_add_f32 v[90:91], v[90:91], v[70:71] op_sel:[1,1] op_sel_hi:[0,0] neg_lo:[0,1] neg_hi:[1,0]
	s_nop 0
	v_pk_add_f32 v[70:71], v[66:67], v[78:79]
	v_pk_add_f32 v[66:67], v[66:67], v[78:79] neg_lo:[0,1] neg_hi:[0,1]
	v_pk_add_f32 v[78:79], v[68:69], v[72:73]
	v_pk_add_f32 v[72:73], v[68:69], v[72:73] op_sel:[1,1] op_sel_hi:[0,0] neg_lo:[0,1] neg_hi:[1,0]
	s_nop 0
	v_pk_add_f32 v[68:69], v[80:81], v[116:117]
	v_pk_add_f32 v[80:81], v[80:81], v[116:117] neg_lo:[0,1] neg_hi:[0,1]
	v_pk_add_f32 v[116:117], v[96:97], v[132:133]
	v_pk_add_f32 v[96:97], v[96:97], v[132:133] neg_lo:[0,1] neg_hi:[0,1]
	v_pk_add_f32 v[132:133], v[98:99], v[126:127]
	v_pk_add_f32 v[98:99], v[98:99], v[126:127] neg_lo:[0,1] neg_hi:[0,1]
	v_pk_add_f32 v[126:127], v[122:123], v[120:121]
	v_pk_add_f32 v[120:121], v[122:123], v[120:121] neg_lo:[0,1] neg_hi:[0,1]
	v_pk_add_f32 v[122:123], v[108:109], v[128:129]
	v_pk_add_f32 v[108:109], v[108:109], v[128:129] neg_lo:[0,1] neg_hi:[0,1]
	v_pk_add_f32 v[128:129], v[110:111], v[124:125]
	v_pk_add_f32 v[110:111], v[110:111], v[124:125] neg_lo:[0,1] neg_hi:[0,1]
	v_pk_add_f32 v[124:125], v[100:101], v[112:113]
	v_pk_add_f32 v[100:101], v[100:101], v[112:113] neg_lo:[0,1] neg_hi:[0,1]
	v_pk_add_f32 v[112:113], v[102:103], v[106:107]
	v_pk_add_f32 v[102:103], v[102:103], v[106:107] neg_lo:[0,1] neg_hi:[0,1]
	v_pk_add_f32 v[106:107], v[82:83], v[118:119]
	v_pk_mul_f32 v[68:69], v[68:69], s[2:3] op_sel_hi:[1,0]
	global_store_dwordx2 v[2:3], v[68:69], off
	v_pk_mul_f32 v[68:69], v[106:107], s[2:3] op_sel_hi:[1,0]
	v_pk_add_f32 v[82:83], v[82:83], v[118:119] neg_lo:[0,1] neg_hi:[0,1]
	v_pk_add_f32 v[118:119], v[114:115], v[130:131]
	v_pk_add_f32 v[114:115], v[114:115], v[130:131] neg_lo:[0,1] neg_hi:[0,1]
	v_pk_add_f32 v[130:131], v[84:85], v[92:93]
	v_pk_add_f32 v[84:85], v[84:85], v[92:93] neg_lo:[0,1] neg_hi:[0,1]
	v_pk_add_f32 v[92:93], v[88:89], v[86:87]
	v_pk_add_f32 v[86:87], v[88:89], v[86:87] neg_lo:[0,1] neg_hi:[0,1]
	v_pk_add_f32 v[88:89], v[74:75], v[94:95]
	global_store_dwordx2 v[4:5], v[68:69], off
	v_pk_mul_f32 v[68:69], v[122:123], s[2:3] op_sel_hi:[1,0]
	global_store_dwordx2 v[6:7], v[68:69], off
	v_pk_mul_f32 v[68:69], v[88:89], s[2:3] op_sel_hi:[1,0]
	global_store_dwordx2 v[8:9], v[68:69], off
	v_pk_mul_f32 v[68:69], v[132:133], s[2:3] op_sel_hi:[1,0]
	global_store_dwordx2 v[10:11], v[68:69], off
	v_pk_mul_f32 v[68:69], v[130:131], s[2:3] op_sel_hi:[1,0]
	v_pk_add_f32 v[74:75], v[74:75], v[94:95] neg_lo:[0,1] neg_hi:[0,1]
	v_pk_add_f32 v[94:95], v[76:77], v[90:91]
	v_pk_add_f32 v[76:77], v[76:77], v[90:91] neg_lo:[0,1] neg_hi:[0,1]
	v_pk_add_f32 v[90:91], v[70:71], v[78:79]
	global_store_dwordx2 v[12:13], v[68:69], off
	v_pk_mul_f32 v[68:69], v[124:125], s[2:3] op_sel_hi:[1,0]
	global_store_dwordx2 v[14:15], v[68:69], off
	v_pk_mul_f32 v[68:69], v[90:91], s[2:3] op_sel_hi:[1,0]
	global_store_dwordx2 v[16:17], v[68:69], off
	v_pk_mul_f32 v[68:69], v[116:117], s[2:3] op_sel_hi:[1,0]
	global_store_dwordx2 v[18:19], v[68:69], off
	v_pk_mul_f32 v[68:69], v[118:119], s[2:3] op_sel_hi:[1,0]
	global_store_dwordx2 v[20:21], v[68:69], off
	v_pk_mul_f32 v[68:69], v[128:129], s[2:3] op_sel_hi:[1,0]
	global_store_dwordx2 v[22:23], v[68:69], off
	v_pk_mul_f32 v[68:69], v[94:95], s[2:3] op_sel_hi:[1,0]
	global_store_dwordx2 v[24:25], v[68:69], off
	v_pk_mul_f32 v[68:69], v[126:127], s[2:3] op_sel_hi:[1,0]
	global_store_dwordx2 v[26:27], v[68:69], off
	v_pk_mul_f32 v[68:69], v[92:93], s[2:3] op_sel_hi:[1,0]
	v_pk_add_f32 v[70:71], v[70:71], v[78:79] neg_lo:[0,1] neg_hi:[0,1]
	v_pk_add_f32 v[78:79], v[66:67], v[72:73]
	global_store_dwordx2 v[28:29], v[68:69], off
	v_pk_mul_f32 v[68:69], v[112:113], s[2:3] op_sel_hi:[1,0]
	global_store_dwordx2 v[30:31], v[68:69], off
	v_pk_mul_f32 v[68:69], v[78:79], s[2:3] op_sel_hi:[1,0]
	global_store_dwordx2 v[32:33], v[68:69], off
	v_pk_mul_f32 v[68:69], v[80:81], s[2:3] op_sel_hi:[1,0]
	global_store_dwordx2 v[34:35], v[68:69], off
	v_pk_mul_f32 v[68:69], v[82:83], s[2:3] op_sel_hi:[1,0]
	global_store_dwordx2 v[36:37], v[68:69], off
	v_pk_mul_f32 v[68:69], v[108:109], s[2:3] op_sel_hi:[1,0]
	global_store_dwordx2 v[38:39], v[68:69], off
	v_pk_mul_f32 v[68:69], v[74:75], s[2:3] op_sel_hi:[1,0]
	global_store_dwordx2 v[40:41], v[68:69], off
	v_pk_mul_f32 v[68:69], v[98:99], s[2:3] op_sel_hi:[1,0]
	global_store_dwordx2 v[42:43], v[68:69], off
	v_pk_mul_f32 v[68:69], v[84:85], s[2:3] op_sel_hi:[1,0]
	global_store_dwordx2 v[44:45], v[68:69], off
	v_pk_mul_f32 v[68:69], v[100:101], s[2:3] op_sel_hi:[1,0]
	global_store_dwordx2 v[46:47], v[68:69], off
	v_pk_mul_f32 v[68:69], v[70:71], s[2:3] op_sel_hi:[1,0]
	global_store_dwordx2 v[48:49], v[68:69], off
	v_pk_mul_f32 v[68:69], v[96:97], s[2:3] op_sel_hi:[1,0]
	global_store_dwordx2 v[50:51], v[68:69], off
	v_pk_mul_f32 v[68:69], v[114:115], s[2:3] op_sel_hi:[1,0]
	global_store_dwordx2 v[52:53], v[68:69], off
	v_pk_mul_f32 v[68:69], v[110:111], s[2:3] op_sel_hi:[1,0]
	global_store_dwordx2 v[54:55], v[68:69], off
	v_pk_mul_f32 v[68:69], v[76:77], s[2:3] op_sel_hi:[1,0]
	global_store_dwordx2 v[56:57], v[68:69], off
	v_pk_mul_f32 v[68:69], v[120:121], s[2:3] op_sel_hi:[1,0]
	v_pk_add_f32 v[66:67], v[66:67], v[72:73] neg_lo:[0,1] neg_hi:[0,1]
	global_store_dwordx2 v[58:59], v[68:69], off
	v_pk_mul_f32 v[68:69], v[86:87], s[2:3] op_sel_hi:[1,0]
	global_store_dwordx2 v[60:61], v[68:69], off
	v_pk_mul_f32 v[68:69], v[102:103], s[2:3] op_sel_hi:[1,0]
	v_pk_mul_f32 v[66:67], v[66:67], s[2:3] op_sel_hi:[1,0]
	global_store_dwordx2 v[62:63], v[68:69], off
	global_store_dwordx2 v[64:65], v[66:67], off
	s_barrier

.Lmy_fft_hj:
	v_mov_b32 v66, 0
	s_movk_i32 s5, 0x200
	v_add_u32_e32 v0, v66, v0
	v_cvt_f32_i32_e32 v68, v0
	v_ashrrev_i32_e32 v66, 5, v0
	v_lshlrev_b32_e32 v67, 3, v0
	v_lshlrev_b32_e32 v66, 3, v66
	v_add3_u32 v171, 0, v66, v67
	v_add_u32_e32 v216, 0x10800, v171
	v_mul_f32_e32 v0, 0x38800000, v68
	v_sin_f32_e32 v67, v0
	v_cos_f32_e32 v66, v0
	v_xor_b32_e32 v68, 0x80000000, v67
	v_mov_b32_e32 v69, v67
	v_pk_mul_f32 v[70:71], v[68:69], v[66:67] op_sel:[0,1] op_sel_hi:[1,0]
	v_pk_fma_f32 v[70:71], v[66:67], v[66:67], v[70:71] op_sel_hi:[1,0,1]
	v_pk_mul_f32 v[74:75], v[68:69], v[70:71] op_sel:[0,1] op_sel_hi:[1,0]
	v_pk_fma_f32 v[74:75], v[70:71], v[66:67], v[74:75] op_sel_hi:[1,0,1]
	v_pk_mul_f32 v[78:79], v[68:69], v[74:75] op_sel:[0,1] op_sel_hi:[1,0]
	v_pk_fma_f32 v[78:79], v[74:75], v[66:67], v[78:79] op_sel_hi:[1,0,1]
	v_pk_mul_f32 v[82:83], v[68:69], v[78:79] op_sel:[0,1] op_sel_hi:[1,0]
	v_pk_fma_f32 v[82:83], v[78:79], v[66:67], v[82:83] op_sel_hi:[1,0,1]
	v_pk_mul_f32 v[86:87], v[68:69], v[82:83] op_sel:[0,1] op_sel_hi:[1,0]
	s_waitcnt vmcnt(31)
	v_lshlrev_b32_e32 v126, 16, v105
	v_pk_fma_f32 v[86:87], v[82:83], v[66:67], v[86:87] op_sel_hi:[1,0,1]
	s_waitcnt vmcnt(30)
	v_lshlrev_b32_e32 v127, 16, v127
	v_pk_mul_f32 v[90:91], v[68:69], v[86:87] op_sel:[0,1] op_sel_hi:[1,0]
	s_waitcnt vmcnt(29)
	v_lshlrev_b32_e32 v129, 16, v128
	v_pk_fma_f32 v[90:91], v[86:87], v[66:67], v[90:91] op_sel_hi:[1,0,1]
	s_waitcnt vmcnt(24)
	v_lshlrev_b32_e32 v128, 16, v134
	v_pk_mul_f32 v[94:95], v[68:69], v[90:91] op_sel:[0,1] op_sel_hi:[1,0]
	v_lshlrev_b32_e32 v130, 16, v130
	v_pk_fma_f32 v[94:95], v[90:91], v[66:67], v[94:95] op_sel_hi:[1,0,1]
	v_lshlrev_b32_e32 v131, 16, v131
	v_pk_mul_f32 v[98:99], v[68:69], v[94:95] op_sel:[0,1] op_sel_hi:[1,0]
	v_lshlrev_b32_e32 v132, 16, v132
	v_pk_fma_f32 v[98:99], v[94:95], v[66:67], v[98:99] op_sel_hi:[1,0,1]
	v_lshlrev_b32_e32 v133, 16, v133
	v_pk_mul_f32 v[102:103], v[68:69], v[98:99] op_sel:[0,1] op_sel_hi:[1,0]
	s_waitcnt vmcnt(22)
	v_lshlrev_b32_e32 v135, 16, v135
	v_pk_fma_f32 v[102:103], v[98:99], v[66:67], v[102:103] op_sel_hi:[1,0,1]
	v_lshlrev_b32_e32 v134, 16, v136
	v_pk_mul_f32 v[108:109], v[68:69], v[102:103] op_sel:[0,1] op_sel_hi:[1,0]
	s_waitcnt vmcnt(21)
	v_lshlrev_b32_e32 v136, 16, v137
	v_pk_fma_f32 v[108:109], v[102:103], v[66:67], v[108:109] op_sel_hi:[1,0,1]
	s_waitcnt vmcnt(20)
	v_lshlrev_b32_e32 v137, 16, v138
	v_pk_mul_f32 v[112:113], v[68:69], v[108:109] op_sel:[0,1] op_sel_hi:[1,0]
	s_waitcnt vmcnt(19)
	v_lshlrev_b32_e32 v138, 16, v139
	s_waitcnt vmcnt(18)
	v_lshlrev_b32_e32 v139, 16, v140
	s_waitcnt vmcnt(17)
	v_lshlrev_b32_e32 v140, 16, v141
	s_waitcnt vmcnt(16)
	v_lshlrev_b32_e32 v141, 16, v142
	v_pk_fma_f32 v[112:113], v[108:109], v[66:67], v[112:113] op_sel_hi:[1,0,1]
	v_pk_add_f32 v[142:143], v[126:127], 0 op_sel_hi:[1,0]
	v_pk_add_f32 v[144:145], v[128:129], 0 op_sel_hi:[1,0]
	v_pk_mul_f32 v[146:147], v[128:129], s[36:37]
	v_pk_add_f32 v[148:149], v[130:131], 0 op_sel_hi:[1,0]
	v_pk_mul_f32 v[150:151], v[130:131], s[16:17]
	v_pk_add_f32 v[152:153], v[132:133], 0 op_sel_hi:[1,0]
	v_pk_mul_f32 v[154:155], v[132:133], s[38:39]
	v_pk_add_f32 v[156:157], v[134:135], 0 op_sel_hi:[1,0]
	v_xor_b32_e32 v159, 0x80000000, v134
	v_mov_b32_e32 v158, v135
	v_pk_add_f32 v[134:135], v[136:137], 0 op_sel_hi:[1,0]
	v_pk_mul_f32 v[160:161], v[136:137], s[38:39]
	v_pk_add_f32 v[162:163], v[138:139], 0 op_sel_hi:[1,0]
	v_pk_mul_f32 v[164:165], v[138:139], s[16:17]
	v_pk_add_f32 v[166:167], v[140:141], 0 op_sel_hi:[1,0]
	v_pk_mul_f32 v[168:169], v[140:141], s[36:37]
	v_pk_mul_f32 v[116:117], v[68:69], v[112:113] op_sel:[0,1] op_sel_hi:[1,0]
	v_pk_fma_f32 v[128:129], v[128:129], s[6:7], v[146:147] op_sel:[0,0,1] op_sel_hi:[1,0,0]
	v_pk_fma_f32 v[130:131], v[130:131], s[10:11], v[150:151] op_sel:[0,0,1] op_sel_hi:[1,0,0]
	v_pk_fma_f32 v[132:133], v[132:133], s[14:15], v[154:155] op_sel:[0,0,1] op_sel_hi:[1,0,0]
	v_pk_fma_f32 v[136:137], v[136:137], s[4:5], v[160:161] op_sel:[0,0,1] op_sel_hi:[1,0,0]
	v_pk_fma_f32 v[138:139], v[138:139], s[8:9], v[164:165] op_sel:[0,0,1] op_sel_hi:[1,0,0]
	v_pk_fma_f32 v[140:141], v[140:141], s[12:13], v[168:169] op_sel:[0,0,1] op_sel_hi:[1,0,0]
	v_pk_add_f32 v[146:147], v[142:143], v[156:157]
	v_pk_add_f32 v[150:151], v[144:145], v[134:135]
	v_pk_add_f32 v[134:135], v[144:145], v[134:135] neg_lo:[0,1] neg_hi:[0,1]
	v_pk_add_f32 v[144:145], v[148:149], v[162:163]
	v_pk_add_f32 v[160:161], v[148:149], v[162:163] op_sel:[1,1] op_sel_hi:[0,0] neg_lo:[0,1] neg_hi:[1,0]
	v_pk_add_f32 v[154:155], v[152:153], v[166:167]
	v_pk_add_f32 v[152:153], v[152:153], v[166:167] neg_lo:[0,1] neg_hi:[0,1]
	v_pk_fma_f32 v[116:117], v[112:113], v[66:67], v[116:117] op_sel_hi:[1,0,1]
	v_pk_add_f32 v[142:143], v[142:143], v[156:157] neg_lo:[0,1] neg_hi:[0,1]
	v_pk_add_f32 v[156:157], v[158:159], v[126:127]
	v_pk_add_f32 v[126:127], v[126:127], v[158:159] neg_lo:[0,1] neg_hi:[0,1]
	v_pk_mul_f32 v[158:159], v[134:135], s[16:17]
	v_pk_mul_f32 v[148:149], v[152:153], s[16:17]
	v_pk_add_f32 v[162:163], v[128:129], v[136:137]
	v_pk_add_f32 v[128:129], v[128:129], v[136:137] neg_lo:[0,1] neg_hi:[0,1]
	v_pk_add_f32 v[136:137], v[130:131], v[138:139]
	v_pk_add_f32 v[130:131], v[130:131], v[138:139] neg_lo:[0,1] neg_hi:[0,1]
	v_pk_add_f32 v[138:139], v[132:133], v[140:141]
	v_pk_add_f32 v[132:133], v[132:133], v[140:141] neg_lo:[0,1] neg_hi:[0,1]
	v_pk_add_f32 v[140:141], v[146:147], v[144:145]
	v_pk_add_f32 v[144:145], v[146:147], v[144:145] neg_lo:[0,1] neg_hi:[0,1]
	v_pk_add_f32 v[146:147], v[150:151], v[154:155]
	v_pk_add_f32 v[150:151], v[150:151], v[154:155] neg_lo:[0,1] neg_hi:[0,1]
	v_pk_mul_f32 v[120:121], v[68:69], v[116:117] op_sel:[0,1] op_sel_hi:[1,0]
	v_pk_fma_f32 v[134:135], v[134:135], s[10:11], v[158:159] op_sel:[0,0,1] op_sel_hi:[1,0,0]
	v_pk_fma_f32 v[148:149], v[152:153], s[8:9], v[148:149] op_sel:[0,0,1] op_sel_hi:[1,0,0]
	v_pk_mul_f32 v[152:153], v[128:129], s[16:17]
	v_xor_b32_e32 v155, 0x80000000, v130
	v_mov_b32_e32 v154, v131
	v_pk_mul_f32 v[130:131], v[132:133], s[16:17]
	v_xor_b32_e32 v159, 0x80000000, v150
	v_mov_b32_e32 v158, v151
	v_pk_add_f32 v[150:151], v[142:143], v[160:161]
	v_pk_add_f32 v[142:143], v[142:143], v[160:161] neg_lo:[0,1] neg_hi:[0,1]
	v_pk_add_f32 v[160:161], v[156:157], v[136:137]
	v_pk_add_f32 v[136:137], v[156:157], v[136:137] neg_lo:[0,1] neg_hi:[0,1]
	v_pk_add_f32 v[156:157], v[162:163], v[138:139]
	v_pk_add_f32 v[138:139], v[162:163], v[138:139] neg_lo:[0,1] neg_hi:[0,1]
	v_mov_b32_e32 v0, v67
	v_pk_fma_f32 v[120:121], v[116:117], v[66:67], v[120:121] op_sel_hi:[1,0,1]
	v_pk_add_f32 v[162:163], v[140:141], v[146:147]
	v_pk_add_f32 v[140:141], v[140:141], v[146:147] neg_lo:[0,1] neg_hi:[0,1]
	v_pk_fma_f32 v[128:129], v[128:129], s[10:11], v[152:153] op_sel:[0,0,1] op_sel_hi:[1,0,0]
	v_pk_fma_f32 v[130:131], v[132:133], s[8:9], v[130:131] op_sel:[0,0,1] op_sel_hi:[1,0,0]
	v_pk_add_f32 v[132:133], v[134:135], v[148:149]
	v_pk_add_f32 v[134:135], v[134:135], v[148:149] neg_lo:[0,1] neg_hi:[0,1]
	v_xor_b32_e32 v147, 0x80000000, v138
	v_mov_b32_e32 v146, v139
	v_pk_add_f32 v[152:153], v[160:161], v[156:157]
	v_pk_mul_f32 v[68:69], v[68:69], v[120:121] op_sel:[0,1] op_sel_hi:[1,0]
	v_pk_add_f32 v[138:139], v[126:127], v[154:155]
	v_pk_add_f32 v[126:127], v[126:127], v[154:155] neg_lo:[0,1] neg_hi:[0,1]
	v_pk_add_f32 v[148:149], v[144:145], v[158:159]
	v_pk_add_f32 v[144:145], v[144:145], v[158:159] neg_lo:[0,1] neg_hi:[0,1]
	v_pk_add_f32 v[154:155], v[160:161], v[156:157] neg_lo:[0,1] neg_hi:[0,1]
	v_pk_mul_f32 v[96:97], v[140:141], v[94:95] op_sel:[1,1] op_sel_hi:[0,1] neg_hi:[0,1]
	v_xor_b32_e32 v157, 0x80000000, v134
	v_mov_b32_e32 v156, v135
	v_pk_add_f32 v[134:135], v[128:129], v[130:131]
	v_pk_add_f32 v[128:129], v[128:129], v[130:131] neg_lo:[0,1] neg_hi:[0,1]
	v_pk_add_f32 v[130:131], v[150:151], v[132:133]
	v_pk_add_f32 v[132:133], v[150:151], v[132:133] neg_lo:[0,1] neg_hi:[0,1]
	v_pk_add_f32 v[150:151], v[136:137], v[146:147]
	v_pk_add_f32 v[136:137], v[136:137], v[146:147] neg_lo:[0,1] neg_hi:[0,1]
	v_pk_mul_f32 v[146:147], v[0:1], v[152:153] op_sel:[0,1] op_sel_hi:[0,0] neg_hi:[1,0]
	v_pk_add_f32 v[92:93], v[90:91], 0 neg_lo:[1,1] neg_hi:[1,1]
	v_pk_fma_f32 v[68:69], v[120:121], v[66:67], v[68:69] op_sel_hi:[1,0,1]
	v_pk_mul_f32 v[80:81], v[148:149], v[78:79] op_sel:[1,1] op_sel_hi:[0,1] neg_hi:[0,1]
	v_pk_fma_f32 v[94:95], v[140:141], v[94:95], v[96:97] op_sel_hi:[1,0,1]
	v_pk_mul_f32 v[96:97], v[154:155], v[98:99] op_sel:[1,1] op_sel_hi:[0,1] neg_hi:[0,1]
	v_pk_mul_f32 v[100:101], v[144:145], v[112:113] op_sel:[1,1] op_sel_hi:[0,1] neg_hi:[0,1]
	v_xor_b32_e32 v115, 0x80000000, v128
	v_mov_b32_e32 v114, v129
	v_pk_add_f32 v[128:129], v[142:143], v[156:157]
	v_pk_add_f32 v[140:141], v[142:143], v[156:157] neg_lo:[0,1] neg_hi:[0,1]
	v_pk_add_f32 v[142:143], v[138:139], v[134:135]
	v_pk_fma_f32 v[66:67], v[152:153], v[66:67], v[146:147] op_sel_hi:[1,0,1]
	v_pk_mul_f32 v[72:73], v[130:131], v[70:71] op_sel:[1,1] op_sel_hi:[0,1] neg_hi:[0,1]
	v_mov_b32_e32 v92, v91
	v_pk_add_f32 v[110:111], v[108:109], 0 neg_lo:[1,1] neg_hi:[1,1]
	v_pk_add_f32 v[118:119], v[116:117], 0 neg_lo:[1,1] neg_hi:[1,1]
	v_pk_add_f32 v[122:123], v[120:121], 0 neg_lo:[1,1] neg_hi:[1,1]
	v_pk_add_f32 v[124:125], v[68:69], 0 neg_lo:[1,1] neg_hi:[1,1]
	ds_write_b64 v171, v[162:163]
	v_pk_fma_f32 v[78:79], v[148:149], v[78:79], v[80:81] op_sel_hi:[1,0,1]
	v_pk_mul_f32 v[80:81], v[150:151], v[82:83] op_sel:[1,1] op_sel_hi:[0,1] neg_hi:[0,1]
	v_pk_fma_f32 v[84:85], v[154:155], v[98:99], v[96:97] op_sel_hi:[1,0,1]
	v_pk_mul_f32 v[96:97], v[132:133], v[102:103] op_sel:[1,1] op_sel_hi:[0,1] neg_hi:[0,1]
	v_pk_add_f32 v[106:107], v[126:127], v[114:115]
	ds_write_b64 v171, v[66:67] offset:8448
	v_pk_fma_f32 v[66:67], v[130:131], v[70:71], v[72:73] op_sel_hi:[1,0,1]
	v_pk_mul_f32 v[70:71], v[142:143], v[74:75] op_sel:[1,1] op_sel_hi:[0,1] neg_hi:[0,1]
	v_mov_b32_e32 v110, v109
	v_mov_b32_e32 v118, v117
	v_mov_b32_e32 v122, v121
	v_mov_b32_e32 v124, v69
	v_pk_add_f32 v[134:135], v[138:139], v[134:135] neg_lo:[0,1] neg_hi:[0,1]
	v_pk_fma_f32 v[98:99], v[144:145], v[112:113], v[100:101] op_sel_hi:[1,0,1]
	v_pk_add_f32 v[112:113], v[126:127], v[114:115] neg_lo:[0,1] neg_hi:[0,1]
	v_pk_mul_f32 v[76:77], v[128:129], v[86:87] op_sel:[1,1] op_sel_hi:[0,1] neg_hi:[0,1]
	ds_write_b64 v171, v[66:67] offset:16896
	v_pk_fma_f32 v[66:67], v[142:143], v[74:75], v[70:71] op_sel_hi:[1,0,1]
	v_pk_mul_f32 v[74:75], v[106:107], v[92:93] op_sel:[1,0] op_sel_hi:[0,1]
	s_mov_b64 s[48:49], 0
	s_and_b64 vcc, exec, vcc
	v_pk_mul_f32 v[100:101], v[136:137], v[118:119] op_sel:[1,0] op_sel_hi:[0,1]
	v_pk_fma_f32 v[72:73], v[150:151], v[82:83], v[80:81] op_sel_hi:[1,0,1]
	v_pk_fma_f32 v[80:81], v[132:133], v[102:103], v[96:97] op_sel_hi:[1,0,1]
	v_pk_mul_f32 v[82:83], v[134:135], v[110:111] op_sel:[1,0] op_sel_hi:[0,1]
	v_pk_mul_f32 v[96:97], v[140:141], v[122:123] op_sel:[1,0] op_sel_hi:[0,1]
	v_pk_fma_f32 v[70:71], v[128:129], v[86:87], v[76:77] op_sel_hi:[1,0,1]
	v_pk_mul_f32 v[86:87], v[112:113], v[124:125] op_sel:[1,0] op_sel_hi:[0,1]
	ds_write_b64 v171, v[66:67] offset:25344
	ds_write_b64 v171, v[78:79] offset:33792
	ds_write_b64 v171, v[72:73] offset:42240
	ds_write_b64 v171, v[70:71] offset:50688
	v_pk_fma_f32 v[66:67], v[106:107], v[90:91], v[74:75] op_sel_hi:[1,0,1]
	v_pk_fma_f32 v[88:89], v[136:137], v[116:117], v[100:101] op_sel_hi:[1,0,1]
	v_pk_fma_f32 v[76:77], v[134:135], v[108:109], v[82:83] op_sel_hi:[1,0,1]
	v_pk_fma_f32 v[82:83], v[140:141], v[120:121], v[96:97] op_sel_hi:[1,0,1]
	v_pk_fma_f32 v[68:69], v[112:113], v[68:69], v[86:87] op_sel_hi:[1,0,1]
	ds_write_b64 v171, v[66:67] offset:59136
	ds_write_b64 v216, v[94:95]
	ds_write_b64 v216, v[84:85] offset:8448
	ds_write_b64 v216, v[80:81] offset:16896
	ds_write_b64 v216, v[76:77] offset:25344
	ds_write_b64 v216, v[98:99] offset:33792
	ds_write_b64 v216, v[88:89] offset:42240
	ds_write_b64 v216, v[82:83] offset:50688
	ds_write_b64 v216, v[68:69] offset:59136
	s_cbranch_vccz .LBB0_362
	s_waitcnt lgkmcnt(0)
	s_barrier
	v_mov_b32 v0, 0
	s_mov_b32 s5, s14
	v_add_u32_e32 v74, v0, v170
	v_lshlrev_b32_e32 v0, 5, v74
	v_and_b32_e32 v71, 0xfffffc00, v0
	v_or_b32_e32 v75, 0x80, v71
	v_and_b32_e32 v70, 31, v74
	v_ashrrev_i32_e32 v75, 2, v75
	v_lshlrev_b32_e32 v78, 3, v71
	v_lshlrev_b32_e32 v79, 3, v70
	v_add_u32_e32 v75, 0, v75
	v_add3_u32 v111, v75, v78, v79
	v_or_b32_e32 v75, 0xa0, v71
	v_ashrrev_i32_e32 v75, 2, v75
	v_add_u32_e32 v75, 0, v75
	v_add3_u32 v110, v75, v78, v79
	v_or_b32_e32 v75, 0xc0, v71
	v_ashrrev_i32_e32 v75, 2, v75
	v_add_u32_e32 v75, 0, v75
	v_add3_u32 v109, v75, v78, v79
	v_or_b32_e32 v75, 0xe0, v71
	v_ashrrev_i32_e32 v75, 2, v75
	v_add_u32_e32 v75, 0, v75
	v_add3_u32 v108, v75, v78, v79
	v_or_b32_e32 v75, 0x100, v71
	v_ashrrev_i32_e32 v75, 2, v75
	v_add_u32_e32 v75, 0, v75
	v_add3_u32 v107, v75, v78, v79
	v_or_b32_e32 v75, 0x120, v71
	v_ashrrev_i32_e32 v75, 2, v75
	v_add_u32_e32 v75, 0, v75
	v_add3_u32 v106, v75, v78, v79
	v_or_b32_e32 v75, 0x140, v71
	v_ashrrev_i32_e32 v75, 2, v75
	v_add_u32_e32 v75, 0, v75
	v_add3_u32 v105, v75, v78, v79
	v_or_b32_e32 v75, 0x160, v71
	v_ashrrev_i32_e32 v75, 2, v75
	v_add_u32_e32 v75, 0, v75
	v_add3_u32 v103, v75, v78, v79
	v_or_b32_e32 v75, 0x180, v71
	v_ashrrev_i32_e32 v75, 2, v75
	v_add_u32_e32 v75, 0, v75
	v_add3_u32 v102, v75, v78, v79
	v_or_b32_e32 v75, 0x1a0, v71
	v_ashrrev_i32_e32 v75, 2, v75
	v_add_u32_e32 v75, 0, v75
	v_add3_u32 v101, v75, v78, v79
	v_or_b32_e32 v75, 0x1c0, v71
	v_ashrrev_i32_e32 v75, 2, v75
	v_add_u32_e32 v75, 0, v75
	v_add3_u32 v100, v75, v78, v79
	v_or_b32_e32 v75, 0x1e0, v71
	v_ashrrev_i32_e32 v75, 2, v75
	v_add_u32_e32 v75, 0, v75
	v_add3_u32 v99, v75, v78, v79
	v_or_b32_e32 v75, 0x200, v71
	v_ashrrev_i32_e32 v75, 2, v75
	v_add_u32_e32 v75, 0, v75
	v_add3_u32 v98, v75, v78, v79
	v_or_b32_e32 v75, 0x220, v71
	v_ashrrev_i32_e32 v75, 2, v75
	v_add_u32_e32 v75, 0, v75
	v_add3_u32 v97, v75, v78, v79
	v_or_b32_e32 v75, 0x240, v71
	v_ashrrev_i32_e32 v75, 2, v75
	v_add_u32_e32 v75, 0, v75
	v_add3_u32 v96, v75, v78, v79
	v_or_b32_e32 v75, 0x260, v71
	v_ashrrev_i32_e32 v75, 2, v75
	v_add_u32_e32 v75, 0, v75
	v_add3_u32 v95, v75, v78, v79
	v_or_b32_e32 v75, 0x280, v71
	v_or_b32_e32 v67, 32, v71
	v_ashrrev_i32_e32 v75, 2, v75
	v_ashrrev_i32_e32 v67, 2, v67
	v_add_u32_e32 v75, 0, v75
	v_add_u32_e32 v67, 0, v67
	v_add3_u32 v94, v75, v78, v79
	v_or_b32_e32 v75, 0x2a0, v71
	v_add3_u32 v114, v67, v78, v79
	v_or_b32_e32 v67, 64, v71
	v_ashrrev_i32_e32 v75, 2, v75
	v_ashrrev_i32_e32 v67, 2, v67
	v_add_u32_e32 v75, 0, v75
	v_add_u32_e32 v67, 0, v67
	v_add3_u32 v93, v75, v78, v79
	v_or_b32_e32 v75, 0x2c0, v71
	v_ashrrev_i32_e32 v66, 2, v71
	v_add3_u32 v113, v67, v78, v79
	v_or_b32_e32 v67, 0x60, v71
	v_ashrrev_i32_e32 v75, 2, v75
	v_add_u32_e32 v66, 0, v66
	v_ashrrev_i32_e32 v67, 2, v67
	v_add_u32_e32 v75, 0, v75
	v_add3_u32 v66, v66, v78, v79
	v_add_u32_e32 v67, 0, v67
	v_add3_u32 v92, v75, v78, v79
	v_or_b32_e32 v75, 0x2e0, v71
	v_add3_u32 v112, v67, v78, v79
	ds_read_b64 v[66:67], v66
	ds_read_b64 v[68:69], v114 offset:256
	ds_read_b64 v[72:73], v113 offset:512
	ds_read_b64 v[76:77], v112 offset:768
	ds_read_b64 v[80:81], v111 offset:1024
	ds_read_b64 v[82:83], v110 offset:1280
	ds_read_b64 v[116:117], v109 offset:1536
	ds_read_b64 v[118:119], v108 offset:1792
	ds_read_b64 v[120:121], v107 offset:2048
	ds_read_b64 v[122:123], v106 offset:2304
	ds_read_b64 v[124:125], v105 offset:2560
	ds_read_b64 v[126:127], v103 offset:2816
	ds_read_b64 v[128:129], v102 offset:3072
	ds_read_b64 v[130:131], v101 offset:3328
	ds_read_b64 v[132:133], v100 offset:3584
	ds_read_b64 v[134:135], v99 offset:3840
	ds_read_b64 v[136:137], v98 offset:4096
	ds_read_b64 v[138:139], v97 offset:4352
	ds_read_b64 v[140:141], v96 offset:4608
	ds_read_b64 v[142:143], v95 offset:4864
	v_ashrrev_i32_e32 v75, 2, v75
	v_add_u32_e32 v75, 0, v75
	v_add3_u32 v91, v75, v78, v79
	v_or_b32_e32 v75, 0x300, v71
	v_ashrrev_i32_e32 v75, 2, v75
	s_waitcnt lgkmcnt(3)
	v_pk_add_f32 v[168:169], v[66:67], v[136:137]
	v_pk_add_f32 v[66:67], v[66:67], v[136:137] neg_lo:[0,1] neg_hi:[0,1]
	s_waitcnt lgkmcnt(2)
	v_pk_add_f32 v[136:137], v[68:69], v[138:139]
	v_pk_add_f32 v[68:69], v[68:69], v[138:139] neg_lo:[0,1] neg_hi:[0,1]
	v_add_u32_e32 v75, 0, v75
	v_pk_mul_f32 v[138:139], v[68:69], s[18:19]
	v_add3_u32 v90, v75, v78, v79
	v_or_b32_e32 v75, 0x320, v71
	v_pk_fma_f32 v[68:69], v[68:69], s[20:21], v[138:139] op_sel:[0,0,1] op_sel_hi:[1,0,0]
	s_waitcnt lgkmcnt(1)
	v_pk_add_f32 v[138:139], v[72:73], v[140:141]
	v_pk_add_f32 v[72:73], v[72:73], v[140:141] neg_lo:[0,1] neg_hi:[0,1]
	v_ashrrev_i32_e32 v75, 2, v75
	v_pk_mul_f32 v[140:141], v[72:73], s[4:5]
	ds_read_b64 v[144:145], v94 offset:5120
	ds_read_b64 v[146:147], v93 offset:5376
	ds_read_b64 v[148:149], v92 offset:5632
	ds_read_b64 v[150:151], v91 offset:5888
	v_add_u32_e32 v75, 0, v75
	v_pk_fma_f32 v[72:73], v[72:73], s[6:7], v[140:141] op_sel:[0,0,1] op_sel_hi:[1,0,0]
	s_waitcnt lgkmcnt(4)
	v_pk_add_f32 v[140:141], v[76:77], v[142:143]
	v_pk_add_f32 v[76:77], v[76:77], v[142:143] neg_lo:[0,1] neg_hi:[0,1]
	v_add3_u32 v89, v75, v78, v79
	v_or_b32_e32 v75, 0x340, v71
	v_pk_mul_f32 v[142:143], v[76:77], s[22:23]
	v_ashrrev_i32_e32 v75, 2, v75
	v_pk_fma_f32 v[76:77], v[76:77], s[24:25], v[142:143] op_sel:[0,0,1] op_sel_hi:[1,0,0]
	s_waitcnt lgkmcnt(3)
	v_pk_add_f32 v[142:143], v[80:81], v[144:145]
	v_pk_add_f32 v[80:81], v[80:81], v[144:145] neg_lo:[0,1] neg_hi:[0,1]
	s_mov_b32 s9, s10
	v_add_u32_e32 v75, 0, v75
	v_pk_mul_f32 v[144:145], v[80:81], s[8:9]
	v_add3_u32 v88, v75, v78, v79
	v_or_b32_e32 v75, 0x360, v71
	v_pk_fma_f32 v[80:81], v[80:81], s[10:11], v[144:145] op_sel:[0,0,1] op_sel_hi:[1,0,0]
	s_waitcnt lgkmcnt(2)
	v_pk_add_f32 v[144:145], v[82:83], v[146:147]
	v_pk_add_f32 v[82:83], v[82:83], v[146:147] neg_lo:[0,1] neg_hi:[0,1]
	s_mov_b32 s27, s24
	v_ashrrev_i32_e32 v75, 2, v75
	v_pk_mul_f32 v[146:147], v[82:83], s[26:27]
	s_mov_b32 s0, s23
	v_add_u32_e32 v75, 0, v75
	v_pk_fma_f32 v[82:83], v[82:83], s[0:1], v[146:147] op_sel:[0,0,1] op_sel_hi:[1,0,0]
	s_waitcnt lgkmcnt(1)
	v_pk_add_f32 v[146:147], v[116:117], v[148:149]
	v_pk_add_f32 v[116:117], v[116:117], v[148:149] neg_lo:[0,1] neg_hi:[0,1]
	s_mov_b32 s13, s6
	v_add3_u32 v87, v75, v78, v79
	v_or_b32_e32 v75, 0x380, v71
	v_pk_mul_f32 v[148:149], v[116:117], s[12:13]
	ds_read_b64 v[152:153], v90 offset:6144
	ds_read_b64 v[154:155], v89 offset:6400
	ds_read_b64 v[156:157], v88 offset:6656
	ds_read_b64 v[158:159], v87 offset:6912
	v_ashrrev_i32_e32 v75, 2, v75
	v_pk_fma_f32 v[116:117], v[116:117], s[14:15], v[148:149] op_sel:[0,0,1] op_sel_hi:[1,0,0]
	s_waitcnt lgkmcnt(4)
	v_pk_add_f32 v[148:149], v[118:119], v[150:151]
	v_pk_add_f32 v[118:119], v[118:119], v[150:151] neg_lo:[0,1] neg_hi:[0,1]
	s_mov_b32 s35, s20
	v_add_u32_e32 v75, 0, v75
	v_pk_mul_f32 v[150:151], v[118:119], s[34:35]
	s_mov_b32 s48, s19
	v_add3_u32 v86, v75, v78, v79
	v_or_b32_e32 v75, 0x3a0, v71
	v_or_b32_e32 v71, 0x3c0, v71
	v_pk_fma_f32 v[118:119], v[118:119], s[48:49], v[150:151] op_sel:[0,0,1] op_sel_hi:[1,0,0]
	s_waitcnt lgkmcnt(3)
	v_pk_add_f32 v[150:151], v[120:121], v[152:153]
	v_pk_add_f32 v[152:153], v[120:121], v[152:153] op_sel:[1,1] op_sel_hi:[0,0] neg_lo:[0,1] neg_hi:[1,0]
	v_ashrrev_i32_e32 v71, 2, v71
	s_waitcnt lgkmcnt(2)
	v_pk_add_f32 v[120:121], v[122:123], v[154:155]
	v_pk_add_f32 v[122:123], v[122:123], v[154:155] neg_lo:[0,1] neg_hi:[0,1]
	v_add_u32_e32 v71, 0, v71
	v_or_b32_e32 v0, 0x3e0, v0
	v_pk_mul_f32 v[154:155], v[122:123], s[34:35]
	v_ashrrev_i32_e32 v75, 2, v75
	v_add3_u32 v84, v71, v78, v79
	v_ashrrev_i32_e32 v71, 2, v0
	v_pk_fma_f32 v[122:123], v[122:123], s[18:19], v[154:155] op_sel:[0,0,1] op_sel_hi:[1,0,0]
	s_waitcnt lgkmcnt(1)
	v_pk_add_f32 v[154:155], v[124:125], v[156:157]
	v_pk_add_f32 v[124:125], v[124:125], v[156:157] neg_lo:[0,1] neg_hi:[0,1]
	v_add_u32_e32 v75, 0, v75
	v_add_u32_e32 v71, 0, v71
	v_lshlrev_b32_e32 v0, 3, v0
	v_pk_mul_f32 v[156:157], v[124:125], s[12:13]
	v_add3_u32 v85, v75, v78, v79
	v_add3_u32 v0, v71, v0, v79
	ds_read_b64 v[160:161], v86 offset:7168
	ds_read_b64 v[162:163], v85 offset:7424
	ds_read_b64 v[164:165], v84 offset:7680
	ds_read_b64 v[166:167], v0
	v_pk_fma_f32 v[124:125], v[124:125], s[4:5], v[156:157] op_sel:[0,0,1] op_sel_hi:[1,0,0]
	s_waitcnt lgkmcnt(4)
	v_pk_add_f32 v[156:157], v[126:127], v[158:159]
	v_pk_add_f32 v[126:127], v[126:127], v[158:159] neg_lo:[0,1] neg_hi:[0,1]
	v_lshlrev_b32_e32 v70, 4, v70
	v_pk_mul_f32 v[158:159], v[126:127], s[26:27]
	v_cvt_f32_u32_e32 v75, v70
	v_pk_fma_f32 v[126:127], v[126:127], s[22:23], v[158:159] op_sel:[0,0,1] op_sel_hi:[1,0,0]
	s_waitcnt lgkmcnt(3)
	v_pk_add_f32 v[158:159], v[128:129], v[160:161]
	v_pk_add_f32 v[128:129], v[128:129], v[160:161] neg_lo:[0,1] neg_hi:[0,1]
	v_and_b32_e32 v74, 0x1fffffe0, v74
	v_pk_mul_f32 v[160:161], v[128:129], s[8:9]
	v_mul_f32_e32 v115, 0x38800000, v75
	v_pk_fma_f32 v[128:129], v[128:129], s[8:9], v[160:161] op_sel:[0,0,1] op_sel_hi:[1,0,0]
	s_waitcnt lgkmcnt(2)
	v_pk_add_f32 v[160:161], v[130:131], v[162:163]
	v_pk_add_f32 v[130:131], v[130:131], v[162:163] neg_lo:[0,1] neg_hi:[0,1]
	v_lshl_add_u32 v74, v74, 3, 0
	v_pk_mul_f32 v[162:163], v[130:131], s[22:23]
	v_sin_f32_e32 v75, v115
	v_pk_fma_f32 v[130:131], v[130:131], s[26:27], v[162:163] op_sel:[0,0,1] op_sel_hi:[1,0,0]
	s_waitcnt lgkmcnt(1)
	v_pk_add_f32 v[162:163], v[132:133], v[164:165]
	v_pk_add_f32 v[132:133], v[132:133], v[164:165] neg_lo:[0,1] neg_hi:[0,1]
	v_add3_u32 v74, v74, v78, v79
	v_pk_mul_f32 v[164:165], v[132:133], s[4:5]
	v_xor_b32_e32 v78, 0x80000000, v75
	v_pk_fma_f32 v[132:133], v[132:133], s[12:13], v[164:165] op_sel:[0,0,1] op_sel_hi:[1,0,0]
	s_waitcnt lgkmcnt(0)
	v_pk_add_f32 v[164:165], v[134:135], v[166:167]
	v_pk_add_f32 v[134:135], v[134:135], v[166:167] neg_lo:[0,1] neg_hi:[0,1]
	v_mov_b32_e32 v79, v75
	v_pk_mul_f32 v[166:167], v[134:135], s[18:19]
	s_mov_b32 s50, s19
	v_pk_fma_f32 v[134:135], v[134:135], s[34:35], v[166:167] op_sel:[0,0,1] op_sel_hi:[1,0,0]
	v_pk_add_f32 v[166:167], v[168:169], v[150:151]
	v_pk_add_f32 v[150:151], v[168:169], v[150:151] neg_lo:[0,1] neg_hi:[0,1]
	v_pk_add_f32 v[168:169], v[136:137], v[120:121]
	v_pk_add_f32 v[120:121], v[136:137], v[120:121] neg_lo:[0,1] neg_hi:[0,1]
	s_mov_b32 s51, s18
	v_pk_mul_f32 v[136:137], v[120:121], s[4:5]
	s_mov_b32 s52, s23
	v_pk_fma_f32 v[120:121], v[120:121], s[6:7], v[136:137] op_sel:[0,0,1] op_sel_hi:[1,0,0]
	v_pk_add_f32 v[136:137], v[138:139], v[154:155]
	v_pk_add_f32 v[138:139], v[138:139], v[154:155] neg_lo:[0,1] neg_hi:[0,1]
	s_mov_b32 s53, s22
	v_pk_mul_f32 v[154:155], v[138:139], s[8:9]
	s_nop 0
	v_pk_fma_f32 v[138:139], v[138:139], s[10:11], v[154:155] op_sel:[0,0,1] op_sel_hi:[1,0,0]
	v_pk_add_f32 v[154:155], v[140:141], v[156:157]
	v_pk_add_f32 v[140:141], v[140:141], v[156:157] neg_lo:[0,1] neg_hi:[0,1]
	s_nop 0
	v_pk_mul_f32 v[156:157], v[140:141], s[12:13]
	s_nop 0
	v_pk_fma_f32 v[140:141], v[140:141], s[14:15], v[156:157] op_sel:[0,0,1] op_sel_hi:[1,0,0]
	v_pk_add_f32 v[156:157], v[142:143], v[158:159]
	v_pk_add_f32 v[158:159], v[142:143], v[158:159] op_sel:[1,1] op_sel_hi:[0,0] neg_lo:[0,1] neg_hi:[1,0]
	s_nop 0
	v_pk_add_f32 v[142:143], v[144:145], v[160:161]
	v_pk_add_f32 v[144:145], v[144:145], v[160:161] neg_lo:[0,1] neg_hi:[0,1]
	s_nop 0
	v_pk_mul_f32 v[160:161], v[144:145], s[12:13]
	s_nop 0
	v_pk_fma_f32 v[144:145], v[144:145], s[4:5], v[160:161] op_sel:[0,0,1] op_sel_hi:[1,0,0]
	v_pk_add_f32 v[160:161], v[146:147], v[162:163]
	v_pk_add_f32 v[146:147], v[146:147], v[162:163] neg_lo:[0,1] neg_hi:[0,1]
	s_nop 0
	v_pk_mul_f32 v[162:163], v[146:147], s[8:9]
	s_nop 0
	v_pk_fma_f32 v[146:147], v[146:147], s[8:9], v[162:163] op_sel:[0,0,1] op_sel_hi:[1,0,0]
	v_pk_add_f32 v[162:163], v[148:149], v[164:165]
	v_pk_add_f32 v[148:149], v[148:149], v[164:165] neg_lo:[0,1] neg_hi:[0,1]
	s_nop 0
	v_pk_mul_f32 v[164:165], v[148:149], s[4:5]
	s_nop 0
	v_pk_fma_f32 v[148:149], v[148:149], s[12:13], v[164:165] op_sel:[0,0,1] op_sel_hi:[1,0,0]
	v_pk_add_f32 v[164:165], v[66:67], v[152:153]
	v_pk_add_f32 v[66:67], v[66:67], v[152:153] neg_lo:[0,1] neg_hi:[0,1]
	v_pk_add_f32 v[152:153], v[68:69], v[122:123]
	v_pk_add_f32 v[68:69], v[68:69], v[122:123] neg_lo:[0,1] neg_hi:[0,1]
	s_nop 0
	v_pk_mul_f32 v[122:123], v[68:69], s[4:5]
	s_nop 0
	v_pk_fma_f32 v[68:69], v[68:69], s[6:7], v[122:123] op_sel:[0,0,1] op_sel_hi:[1,0,0]
	v_pk_add_f32 v[122:123], v[72:73], v[124:125]
	v_pk_add_f32 v[72:73], v[72:73], v[124:125] neg_lo:[0,1] neg_hi:[0,1]
	s_nop 0
	v_pk_mul_f32 v[124:125], v[72:73], s[8:9]
	s_nop 0
	v_pk_fma_f32 v[72:73], v[72:73], s[10:11], v[124:125] op_sel:[0,0,1] op_sel_hi:[1,0,0]
	v_pk_add_f32 v[124:125], v[76:77], v[126:127]
	v_pk_add_f32 v[76:77], v[76:77], v[126:127] neg_lo:[0,1] neg_hi:[0,1]
	s_nop 0
	v_pk_mul_f32 v[126:127], v[76:77], s[12:13]
	s_nop 0
	v_pk_fma_f32 v[76:77], v[76:77], s[14:15], v[126:127] op_sel:[0,0,1] op_sel_hi:[1,0,0]
	v_pk_add_f32 v[126:127], v[80:81], v[128:129]
	v_pk_add_f32 v[128:129], v[80:81], v[128:129] op_sel:[1,1] op_sel_hi:[0,0] neg_lo:[0,1] neg_hi:[1,0]
	s_nop 0
	v_pk_add_f32 v[80:81], v[82:83], v[130:131]
	v_pk_add_f32 v[82:83], v[82:83], v[130:131] neg_lo:[0,1] neg_hi:[0,1]
	s_nop 0
	v_pk_mul_f32 v[130:131], v[82:83], s[12:13]
	s_nop 0
	v_pk_fma_f32 v[82:83], v[82:83], s[4:5], v[130:131] op_sel:[0,0,1] op_sel_hi:[1,0,0]
	v_pk_add_f32 v[130:131], v[116:117], v[132:133]
	v_pk_add_f32 v[116:117], v[116:117], v[132:133] neg_lo:[0,1] neg_hi:[0,1]
	s_nop 0
	v_pk_mul_f32 v[132:133], v[116:117], s[8:9]
	s_nop 0
	v_pk_fma_f32 v[116:117], v[116:117], s[8:9], v[132:133] op_sel:[0,0,1] op_sel_hi:[1,0,0]
	v_pk_add_f32 v[132:133], v[118:119], v[134:135]
	v_pk_add_f32 v[118:119], v[118:119], v[134:135] neg_lo:[0,1] neg_hi:[0,1]
	s_nop 0
	v_pk_mul_f32 v[134:135], v[118:119], s[4:5]
	s_nop 0
	v_pk_fma_f32 v[118:119], v[118:119], s[12:13], v[134:135] op_sel:[0,0,1] op_sel_hi:[1,0,0]
	v_pk_add_f32 v[134:135], v[166:167], v[156:157]
	v_pk_add_f32 v[156:157], v[166:167], v[156:157] neg_lo:[0,1] neg_hi:[0,1]
	v_pk_add_f32 v[166:167], v[168:169], v[142:143]
	v_pk_add_f32 v[142:143], v[168:169], v[142:143] neg_lo:[0,1] neg_hi:[0,1]
	s_nop 0
	v_pk_mul_f32 v[168:169], v[142:143], s[8:9]
	s_nop 0
	v_pk_fma_f32 v[142:143], v[142:143], s[10:11], v[168:169] op_sel:[0,0,1] op_sel_hi:[1,0,0]
	v_pk_add_f32 v[168:169], v[136:137], v[160:161]
	v_pk_add_f32 v[160:161], v[136:137], v[160:161] op_sel:[1,1] op_sel_hi:[0,0] neg_lo:[0,1] neg_hi:[1,0]
	s_nop 0
	v_pk_add_f32 v[136:137], v[154:155], v[162:163]
	v_pk_add_f32 v[154:155], v[154:155], v[162:163] neg_lo:[0,1] neg_hi:[0,1]
	s_nop 0
	v_pk_mul_f32 v[162:163], v[154:155], s[8:9]
	s_nop 0
	v_pk_fma_f32 v[154:155], v[154:155], s[8:9], v[162:163] op_sel:[0,0,1] op_sel_hi:[1,0,0]
	v_pk_add_f32 v[162:163], v[150:151], v[158:159]
	v_pk_add_f32 v[150:151], v[150:151], v[158:159] neg_lo:[0,1] neg_hi:[0,1]
	v_pk_add_f32 v[158:159], v[120:121], v[144:145]
	v_pk_add_f32 v[120:121], v[120:121], v[144:145] neg_lo:[0,1] neg_hi:[0,1]
	s_nop 0
	v_pk_mul_f32 v[144:145], v[120:121], s[8:9]
	s_nop 0
	v_pk_fma_f32 v[120:121], v[120:121], s[10:11], v[144:145] op_sel:[0,0,1] op_sel_hi:[1,0,0]
	v_pk_add_f32 v[144:145], v[138:139], v[146:147]
	v_pk_add_f32 v[146:147], v[138:139], v[146:147] op_sel:[1,1] op_sel_hi:[0,0] neg_lo:[0,1] neg_hi:[1,0]
	s_nop 0
	v_pk_add_f32 v[138:139], v[140:141], v[148:149]
	v_pk_add_f32 v[140:141], v[140:141], v[148:149] neg_lo:[0,1] neg_hi:[0,1]
	s_nop 0
	v_pk_mul_f32 v[148:149], v[140:141], s[8:9]
	s_nop 0
	v_pk_fma_f32 v[140:141], v[140:141], s[8:9], v[148:149] op_sel:[0,0,1] op_sel_hi:[1,0,0]
	v_pk_add_f32 v[148:149], v[164:165], v[126:127]
	v_pk_add_f32 v[126:127], v[164:165], v[126:127] neg_lo:[0,1] neg_hi:[0,1]
	v_pk_add_f32 v[164:165], v[152:153], v[80:81]
	v_pk_add_f32 v[80:81], v[152:153], v[80:81] neg_lo:[0,1] neg_hi:[0,1]
	s_nop 0
	v_pk_mul_f32 v[152:153], v[80:81], s[8:9]
	s_nop 0
	v_pk_fma_f32 v[80:81], v[80:81], s[10:11], v[152:153] op_sel:[0,0,1] op_sel_hi:[1,0,0]
	v_pk_add_f32 v[152:153], v[122:123], v[130:131]
	v_pk_add_f32 v[130:131], v[122:123], v[130:131] op_sel:[1,1] op_sel_hi:[0,0] neg_lo:[0,1] neg_hi:[1,0]
	s_nop 0
	v_pk_add_f32 v[122:123], v[124:125], v[132:133]
	v_pk_add_f32 v[124:125], v[124:125], v[132:133] neg_lo:[0,1] neg_hi:[0,1]
	s_nop 0
	v_pk_mul_f32 v[132:133], v[124:125], s[8:9]
	s_nop 0
	v_pk_fma_f32 v[124:125], v[124:125], s[8:9], v[132:133] op_sel:[0,0,1] op_sel_hi:[1,0,0]
	v_pk_add_f32 v[132:133], v[66:67], v[128:129]
	v_pk_add_f32 v[66:67], v[66:67], v[128:129] neg_lo:[0,1] neg_hi:[0,1]
	v_pk_add_f32 v[128:129], v[68:69], v[82:83]
	v_pk_add_f32 v[68:69], v[68:69], v[82:83] neg_lo:[0,1] neg_hi:[0,1]
	s_nop 0
	v_pk_mul_f32 v[82:83], v[68:69], s[8:9]
	s_nop 0
	v_pk_fma_f32 v[68:69], v[68:69], s[10:11], v[82:83] op_sel:[0,0,1] op_sel_hi:[1,0,0]
	v_pk_add_f32 v[82:83], v[72:73], v[116:117]
	v_pk_add_f32 v[116:117], v[72:73], v[116:117] op_sel:[1,1] op_sel_hi:[0,0] neg_lo:[0,1] neg_hi:[1,0]
	s_nop 0
	v_pk_add_f32 v[72:73], v[76:77], v[118:119]
	v_pk_add_f32 v[76:77], v[76:77], v[118:119] neg_lo:[0,1] neg_hi:[0,1]
	v_pk_add_f32 v[174:175], v[66:67], v[116:117]
	v_pk_mul_f32 v[118:119], v[76:77], s[8:9]
	v_pk_add_f32 v[116:117], v[66:67], v[116:117] neg_lo:[0,1] neg_hi:[0,1]
	v_pk_fma_f32 v[76:77], v[76:77], s[8:9], v[118:119] op_sel:[0,0,1] op_sel_hi:[1,0,0]
	v_pk_add_f32 v[118:119], v[134:135], v[168:169]
	v_pk_add_f32 v[134:135], v[134:135], v[168:169] neg_lo:[0,1] neg_hi:[0,1]
	v_pk_add_f32 v[168:169], v[166:167], v[136:137]
	v_pk_add_f32 v[166:167], v[166:167], v[136:137] op_sel:[1,1] op_sel_hi:[0,0] neg_lo:[0,1] neg_hi:[1,0]
	v_pk_add_f32 v[180:181], v[118:119], v[168:169]
	v_pk_add_f32 v[136:137], v[156:157], v[160:161]
	v_pk_add_f32 v[156:157], v[156:157], v[160:161] neg_lo:[0,1] neg_hi:[0,1]
	v_pk_add_f32 v[160:161], v[142:143], v[154:155]
	v_pk_add_f32 v[154:155], v[142:143], v[154:155] op_sel:[1,1] op_sel_hi:[0,0] neg_lo:[0,1] neg_hi:[1,0]
	v_pk_add_f32 v[178:179], v[68:69], v[76:77] op_sel:[1,1] op_sel_hi:[0,0] neg_lo:[0,1] neg_hi:[1,0]
	v_pk_add_f32 v[142:143], v[162:163], v[144:145]
	v_pk_add_f32 v[144:145], v[162:163], v[144:145] neg_lo:[0,1] neg_hi:[0,1]
	v_pk_add_f32 v[162:163], v[158:159], v[138:139]
	v_pk_add_f32 v[158:159], v[158:159], v[138:139] op_sel:[1,1] op_sel_hi:[0,0] neg_lo:[0,1] neg_hi:[1,0]
	ds_write_b64 v74, v[180:181]
	v_pk_add_f32 v[138:139], v[150:151], v[146:147]
	v_pk_add_f32 v[146:147], v[150:151], v[146:147] neg_lo:[0,1] neg_hi:[0,1]
	v_pk_add_f32 v[150:151], v[120:121], v[140:141]
	v_pk_add_f32 v[140:141], v[120:121], v[140:141] op_sel:[1,1] op_sel_hi:[0,0] neg_lo:[0,1] neg_hi:[1,0]
	v_cos_f32_e32 v74, v115
	v_pk_add_f32 v[120:121], v[148:149], v[152:153]
	v_pk_add_f32 v[148:149], v[148:149], v[152:153] neg_lo:[0,1] neg_hi:[0,1]
	v_pk_add_f32 v[152:153], v[164:165], v[122:123]
	v_pk_add_f32 v[164:165], v[164:165], v[122:123] op_sel:[1,1] op_sel_hi:[0,0] neg_lo:[0,1] neg_hi:[1,0]
	v_pk_add_f32 v[122:123], v[126:127], v[130:131]
	v_pk_add_f32 v[126:127], v[126:127], v[130:131] neg_lo:[0,1] neg_hi:[0,1]
	v_pk_add_f32 v[130:131], v[80:81], v[124:125]
	v_pk_add_f32 v[124:125], v[80:81], v[124:125] op_sel:[1,1] op_sel_hi:[0,0] neg_lo:[0,1] neg_hi:[1,0]
	v_pk_add_f32 v[80:81], v[132:133], v[82:83]
	v_pk_add_f32 v[132:133], v[132:133], v[82:83] neg_lo:[0,1] neg_hi:[0,1]
	v_pk_add_f32 v[176:177], v[68:69], v[76:77]
	v_pk_add_f32 v[118:119], v[118:119], v[168:169] neg_lo:[0,1] neg_hi:[0,1]
	v_pk_add_f32 v[168:169], v[134:135], v[166:167]
	v_pk_add_f32 v[82:83], v[134:135], v[166:167] neg_lo:[0,1] neg_hi:[0,1]
	v_pk_add_f32 v[134:135], v[136:137], v[160:161]
	v_pk_add_f32 v[136:137], v[136:137], v[160:161] neg_lo:[0,1] neg_hi:[0,1]
	v_pk_add_f32 v[160:161], v[156:157], v[154:155]
	v_pk_add_f32 v[68:69], v[156:157], v[154:155] neg_lo:[0,1] neg_hi:[0,1]
	v_pk_add_f32 v[154:155], v[142:143], v[162:163]
	v_pk_add_f32 v[142:143], v[142:143], v[162:163] neg_lo:[0,1] neg_hi:[0,1]
	v_pk_add_f32 v[156:157], v[144:145], v[158:159]
	v_pk_add_f32 v[76:77], v[144:145], v[158:159] neg_lo:[0,1] neg_hi:[0,1]
	v_pk_add_f32 v[144:145], v[138:139], v[150:151]
	v_pk_add_f32 v[138:139], v[138:139], v[150:151] neg_lo:[0,1] neg_hi:[0,1]
	v_pk_add_f32 v[150:151], v[146:147], v[140:141]
	v_pk_add_f32 v[66:67], v[146:147], v[140:141] neg_lo:[0,1] neg_hi:[0,1]
	v_pk_add_f32 v[140:141], v[120:121], v[152:153]
	v_pk_add_f32 v[162:163], v[116:117], v[178:179]
	v_pk_add_f32 v[70:71], v[116:117], v[178:179] neg_lo:[0,1] neg_hi:[0,1]
	v_mov_b32_e32 v116, v75
	v_pk_mul_f32 v[116:117], v[116:117], v[140:141] op_sel:[0,1] op_sel_hi:[0,0] neg_hi:[1,0]
	v_pk_fma_f32 v[116:117], v[140:141], v[74:75], v[116:117] op_sel_hi:[1,0,1]
	ds_write_b64 v114, v[116:117] offset:256
	v_pk_mul_f32 v[114:115], v[78:79], v[74:75] op_sel:[0,1] op_sel_hi:[1,0]
	v_pk_add_f32 v[172:173], v[128:129], v[72:73]
	v_pk_fma_f32 v[114:115], v[74:75], v[74:75], v[114:115] op_sel_hi:[1,0,1]
	v_pk_add_f32 v[128:129], v[128:129], v[72:73] op_sel:[1,1] op_sel_hi:[0,0] neg_lo:[0,1] neg_hi:[1,0]
	v_pk_mul_f32 v[116:117], v[154:155], v[114:115] op_sel:[1,1] op_sel_hi:[0,1] neg_hi:[0,1]
	v_pk_fma_f32 v[116:117], v[154:155], v[114:115], v[116:117] op_sel_hi:[1,0,1]
	ds_write_b64 v113, v[116:117] offset:512
	v_pk_mul_f32 v[116:117], v[78:79], v[114:115] op_sel:[0,1] op_sel_hi:[1,0]
	v_pk_add_f32 v[120:121], v[120:121], v[152:153] neg_lo:[0,1] neg_hi:[0,1]
	v_pk_fma_f32 v[114:115], v[114:115], v[74:75], v[116:117] op_sel_hi:[1,0,1]
	v_pk_add_f32 v[152:153], v[122:123], v[130:131]
	v_pk_add_f32 v[122:123], v[122:123], v[130:131] neg_lo:[0,1] neg_hi:[0,1]
	v_pk_add_f32 v[130:131], v[126:127], v[124:125]
	v_pk_add_f32 v[72:73], v[126:127], v[124:125] neg_lo:[0,1] neg_hi:[0,1]
	v_pk_add_f32 v[124:125], v[80:81], v[172:173]
	v_pk_mul_f32 v[116:117], v[124:125], v[114:115] op_sel:[1,1] op_sel_hi:[0,1] neg_hi:[0,1]
	v_pk_add_f32 v[126:127], v[80:81], v[172:173] neg_lo:[0,1] neg_hi:[0,1]
	v_pk_fma_f32 v[116:117], v[124:125], v[114:115], v[116:117] op_sel_hi:[1,0,1]
	ds_write_b64 v112, v[116:117] offset:768
	v_pk_mul_f32 v[112:113], v[78:79], v[114:115] op_sel:[0,1] op_sel_hi:[1,0]
	v_pk_add_f32 v[158:159], v[132:133], v[128:129]
	v_pk_fma_f32 v[112:113], v[114:115], v[74:75], v[112:113] op_sel_hi:[1,0,1]
	v_pk_add_f32 v[80:81], v[132:133], v[128:129] neg_lo:[0,1] neg_hi:[0,1]
	v_pk_add_f32 v[128:129], v[174:175], v[176:177]
	v_pk_mul_f32 v[114:115], v[134:135], v[112:113] op_sel:[1,1] op_sel_hi:[0,1] neg_hi:[0,1]
	v_pk_add_f32 v[146:147], v[148:149], v[164:165]
	v_pk_fma_f32 v[114:115], v[134:135], v[112:113], v[114:115] op_sel_hi:[1,0,1]
	ds_write_b64 v111, v[114:115] offset:1024
	v_pk_mul_f32 v[114:115], v[78:79], v[112:113] op_sel:[0,1] op_sel_hi:[1,0]
	v_pk_add_f32 v[132:133], v[174:175], v[176:177] neg_lo:[0,1] neg_hi:[0,1]
	v_pk_fma_f32 v[112:113], v[112:113], v[74:75], v[114:115] op_sel_hi:[1,0,1]
	v_pk_add_f32 v[148:149], v[148:149], v[164:165] neg_lo:[0,1] neg_hi:[0,1]
	s_nop 0
	v_pk_mul_f32 v[114:115], v[152:153], v[112:113] op_sel:[1,1] op_sel_hi:[0,1] neg_hi:[0,1]
	s_nop 0
	v_pk_fma_f32 v[114:115], v[152:153], v[112:113], v[114:115] op_sel_hi:[1,0,1]
	ds_write_b64 v110, v[114:115] offset:1280
	v_pk_mul_f32 v[110:111], v[78:79], v[112:113] op_sel:[0,1] op_sel_hi:[1,0]
	s_nop 0
	v_pk_fma_f32 v[110:111], v[112:113], v[74:75], v[110:111] op_sel_hi:[1,0,1]
	s_nop 0
	s_nop 0
	v_pk_mul_f32 v[112:113], v[144:145], v[110:111] op_sel:[1,1] op_sel_hi:[0,1] neg_hi:[0,1]
	s_nop 0
	v_pk_fma_f32 v[112:113], v[144:145], v[110:111], v[112:113] op_sel_hi:[1,0,1]
	ds_write_b64 v109, v[112:113] offset:1536
	v_pk_mul_f32 v[112:113], v[78:79], v[110:111] op_sel:[0,1] op_sel_hi:[1,0]
	s_nop 0
	v_pk_fma_f32 v[110:111], v[110:111], v[74:75], v[112:113] op_sel_hi:[1,0,1]
	s_nop 0
	s_nop 0
	v_pk_mul_f32 v[112:113], v[128:129], v[110:111] op_sel:[1,1] op_sel_hi:[0,1] neg_hi:[0,1]
	s_nop 0
	v_pk_fma_f32 v[112:113], v[128:129], v[110:111], v[112:113] op_sel_hi:[1,0,1]
	ds_write_b64 v108, v[112:113] offset:1792
	v_pk_mul_f32 v[108:109], v[78:79], v[110:111] op_sel:[0,1] op_sel_hi:[1,0]
	s_nop 0
	v_pk_fma_f32 v[108:109], v[110:111], v[74:75], v[108:109] op_sel_hi:[1,0,1]
	s_nop 0
	s_nop 0
	v_pk_mul_f32 v[110:111], v[168:169], v[108:109] op_sel:[1,1] op_sel_hi:[0,1] neg_hi:[0,1]
	s_nop 0
	v_pk_fma_f32 v[110:111], v[168:169], v[108:109], v[110:111] op_sel_hi:[1,0,1]
	ds_write_b64 v107, v[110:111] offset:2048
	v_pk_mul_f32 v[110:111], v[78:79], v[108:109] op_sel:[0,1] op_sel_hi:[1,0]
	s_nop 0
	v_pk_fma_f32 v[108:109], v[108:109], v[74:75], v[110:111] op_sel_hi:[1,0,1]
	s_nop 0
	s_nop 0
	v_pk_mul_f32 v[110:111], v[146:147], v[108:109] op_sel:[1,1] op_sel_hi:[0,1] neg_hi:[0,1]
	s_nop 0
	v_pk_fma_f32 v[110:111], v[146:147], v[108:109], v[110:111] op_sel_hi:[1,0,1]
	ds_write_b64 v106, v[110:111] offset:2304
	v_pk_mul_f32 v[106:107], v[78:79], v[108:109] op_sel:[0,1] op_sel_hi:[1,0]
	s_nop 0
	v_pk_fma_f32 v[106:107], v[108:109], v[74:75], v[106:107] op_sel_hi:[1,0,1]
	s_nop 0
	s_nop 0
	v_pk_mul_f32 v[108:109], v[156:157], v[106:107] op_sel:[1,1] op_sel_hi:[0,1] neg_hi:[0,1]
	s_nop 0
	v_pk_fma_f32 v[108:109], v[156:157], v[106:107], v[108:109] op_sel_hi:[1,0,1]
	ds_write_b64 v105, v[108:109] offset:2560
	v_pk_mul_f32 v[108:109], v[78:79], v[106:107] op_sel:[0,1] op_sel_hi:[1,0]
	s_nop 0
	v_pk_fma_f32 v[106:107], v[106:107], v[74:75], v[108:109] op_sel_hi:[1,0,1]
	s_nop 0
	s_nop 0
	v_pk_mul_f32 v[108:109], v[158:159], v[106:107] op_sel:[1,1] op_sel_hi:[0,1] neg_hi:[0,1]
	s_nop 0
	v_pk_fma_f32 v[108:109], v[158:159], v[106:107], v[108:109] op_sel_hi:[1,0,1]
	ds_write_b64 v103, v[108:109] offset:2816
	v_pk_mul_f32 v[108:109], v[78:79], v[106:107] op_sel:[0,1] op_sel_hi:[1,0]
	s_nop 0
	v_pk_fma_f32 v[106:107], v[106:107], v[74:75], v[108:109] op_sel_hi:[1,0,1]
	s_nop 0
	s_nop 0
	v_pk_mul_f32 v[108:109], v[160:161], v[106:107] op_sel:[1,1] op_sel_hi:[0,1] neg_hi:[0,1]
	s_nop 0
	v_pk_fma_f32 v[108:109], v[160:161], v[106:107], v[108:109] op_sel_hi:[1,0,1]
	ds_write_b64 v102, v[108:109] offset:3072
	v_pk_mul_f32 v[102:103], v[78:79], v[106:107] op_sel:[0,1] op_sel_hi:[1,0]
	s_nop 0
	v_pk_fma_f32 v[102:103], v[106:107], v[74:75], v[102:103] op_sel_hi:[1,0,1]
	s_nop 0
	s_nop 0
	v_pk_mul_f32 v[106:107], v[130:131], v[102:103] op_sel:[1,1] op_sel_hi:[0,1] neg_hi:[0,1]
	s_nop 0
	v_pk_fma_f32 v[106:107], v[130:131], v[102:103], v[106:107] op_sel_hi:[1,0,1]
	ds_write_b64 v101, v[106:107] offset:3328
	v_pk_mul_f32 v[106:107], v[78:79], v[102:103] op_sel:[0,1] op_sel_hi:[1,0]
	s_nop 0
	v_pk_fma_f32 v[102:103], v[102:103], v[74:75], v[106:107] op_sel_hi:[1,0,1]
	s_nop 0
	s_nop 0
	v_pk_mul_f32 v[106:107], v[150:151], v[102:103] op_sel:[1,1] op_sel_hi:[0,1] neg_hi:[0,1]
	v_pk_fma_f32 v[106:107], v[150:151], v[102:103], v[106:107] op_sel_hi:[1,0,1]
	ds_write_b64 v100, v[106:107] offset:3584
	v_pk_mul_f32 v[100:101], v[78:79], v[102:103] op_sel:[0,1] op_sel_hi:[1,0]
	s_nop 0
	v_pk_fma_f32 v[100:101], v[102:103], v[74:75], v[100:101] op_sel_hi:[1,0,1]
	s_nop 0
	s_nop 0
	v_pk_mul_f32 v[102:103], v[162:163], v[100:101] op_sel:[1,1] op_sel_hi:[0,1] neg_hi:[0,1]
	v_pk_fma_f32 v[102:103], v[162:163], v[100:101], v[102:103] op_sel_hi:[1,0,1]
	ds_write_b64 v99, v[102:103] offset:3840
	v_pk_mul_f32 v[102:103], v[78:79], v[100:101] op_sel:[0,1] op_sel_hi:[1,0]
	s_nop 0
	v_pk_fma_f32 v[100:101], v[100:101], v[74:75], v[102:103] op_sel_hi:[1,0,1]
	s_nop 0
	s_nop 0
	v_pk_mul_f32 v[102:103], v[118:119], v[100:101] op_sel:[1,1] op_sel_hi:[0,1] neg_hi:[0,1]
	v_pk_fma_f32 v[102:103], v[118:119], v[100:101], v[102:103] op_sel_hi:[1,0,1]
	ds_write_b64 v98, v[102:103] offset:4096
	v_pk_mul_f32 v[98:99], v[78:79], v[100:101] op_sel:[0,1] op_sel_hi:[1,0]
	s_nop 0
	v_pk_fma_f32 v[98:99], v[100:101], v[74:75], v[98:99] op_sel_hi:[1,0,1]
	s_nop 0
	s_nop 0
	v_pk_mul_f32 v[100:101], v[120:121], v[98:99] op_sel:[1,1] op_sel_hi:[0,1] neg_hi:[0,1]
	v_pk_fma_f32 v[100:101], v[120:121], v[98:99], v[100:101] op_sel_hi:[1,0,1]
	ds_write_b64 v97, v[100:101] offset:4352
	v_pk_mul_f32 v[100:101], v[78:79], v[98:99] op_sel:[0,1] op_sel_hi:[1,0]
	s_nop 0
	v_pk_fma_f32 v[98:99], v[98:99], v[74:75], v[100:101] op_sel_hi:[1,0,1]
	s_nop 0
	s_nop 0
	v_pk_mul_f32 v[100:101], v[142:143], v[98:99] op_sel:[1,1] op_sel_hi:[0,1] neg_hi:[0,1]
	v_pk_fma_f32 v[100:101], v[142:143], v[98:99], v[100:101] op_sel_hi:[1,0,1]
	ds_write_b64 v96, v[100:101] offset:4608
	v_pk_mul_f32 v[96:97], v[78:79], v[98:99] op_sel:[0,1] op_sel_hi:[1,0]
	s_nop 0
	v_pk_fma_f32 v[96:97], v[98:99], v[74:75], v[96:97] op_sel_hi:[1,0,1]
	s_nop 0
	s_nop 0
	v_pk_mul_f32 v[98:99], v[126:127], v[96:97] op_sel:[1,1] op_sel_hi:[0,1] neg_hi:[0,1]
	v_pk_fma_f32 v[98:99], v[126:127], v[96:97], v[98:99] op_sel_hi:[1,0,1]
	ds_write_b64 v95, v[98:99] offset:4864
	v_pk_mul_f32 v[98:99], v[78:79], v[96:97] op_sel:[0,1] op_sel_hi:[1,0]
	s_nop 0
	v_pk_fma_f32 v[96:97], v[96:97], v[74:75], v[98:99] op_sel_hi:[1,0,1]
	s_nop 0
	s_nop 0
	v_pk_mul_f32 v[98:99], v[136:137], v[96:97] op_sel:[1,1] op_sel_hi:[0,1] neg_hi:[0,1]
	v_pk_fma_f32 v[98:99], v[136:137], v[96:97], v[98:99] op_sel_hi:[1,0,1]
	ds_write_b64 v94, v[98:99] offset:5120
	v_pk_mul_f32 v[94:95], v[78:79], v[96:97] op_sel:[0,1] op_sel_hi:[1,0]
	s_nop 0
	v_pk_fma_f32 v[94:95], v[96:97], v[74:75], v[94:95] op_sel_hi:[1,0,1]
	s_nop 0
	s_nop 0
	v_pk_mul_f32 v[96:97], v[122:123], v[94:95] op_sel:[1,1] op_sel_hi:[0,1] neg_hi:[0,1]
	v_pk_fma_f32 v[96:97], v[122:123], v[94:95], v[96:97] op_sel_hi:[1,0,1]
	ds_write_b64 v93, v[96:97] offset:5376
	v_pk_mul_f32 v[96:97], v[78:79], v[94:95] op_sel:[0,1] op_sel_hi:[1,0]
	s_nop 0
	v_pk_fma_f32 v[94:95], v[94:95], v[74:75], v[96:97] op_sel_hi:[1,0,1]
	s_nop 0
	s_nop 0
	v_pk_mul_f32 v[96:97], v[138:139], v[94:95] op_sel:[1,1] op_sel_hi:[0,1] neg_hi:[0,1]
	v_pk_fma_f32 v[96:97], v[138:139], v[94:95], v[96:97] op_sel_hi:[1,0,1]
	ds_write_b64 v92, v[96:97] offset:5632
	v_pk_mul_f32 v[92:93], v[78:79], v[94:95] op_sel:[0,1] op_sel_hi:[1,0]
	s_nop 0
	v_pk_fma_f32 v[92:93], v[94:95], v[74:75], v[92:93] op_sel_hi:[1,0,1]
	s_nop 0
	s_nop 0
	v_pk_mul_f32 v[94:95], v[132:133], v[92:93] op_sel:[1,1] op_sel_hi:[0,1] neg_hi:[0,1]
	v_pk_fma_f32 v[94:95], v[132:133], v[92:93], v[94:95] op_sel_hi:[1,0,1]
	ds_write_b64 v91, v[94:95] offset:5888
	v_pk_mul_f32 v[94:95], v[78:79], v[92:93] op_sel:[0,1] op_sel_hi:[1,0]
	s_nop 0
	v_pk_fma_f32 v[92:93], v[92:93], v[74:75], v[94:95] op_sel_hi:[1,0,1]
	s_nop 0
	s_nop 0
	v_pk_mul_f32 v[94:95], v[82:83], v[92:93] op_sel:[1,1] op_sel_hi:[0,1] neg_hi:[0,1]
	v_pk_fma_f32 v[82:83], v[82:83], v[92:93], v[94:95] op_sel_hi:[1,0,1]
	ds_write_b64 v90, v[82:83] offset:6144
	v_pk_mul_f32 v[82:83], v[78:79], v[92:93] op_sel:[0,1] op_sel_hi:[1,0]
	s_nop 0
	v_pk_fma_f32 v[82:83], v[92:93], v[74:75], v[82:83] op_sel_hi:[1,0,1]
	s_nop 0
	s_nop 0
	v_pk_mul_f32 v[90:91], v[148:149], v[82:83] op_sel:[1,1] op_sel_hi:[0,1] neg_hi:[0,1]
	v_pk_fma_f32 v[90:91], v[148:149], v[82:83], v[90:91] op_sel_hi:[1,0,1]
	ds_write_b64 v89, v[90:91] offset:6400
	v_pk_mul_f32 v[90:91], v[78:79], v[82:83] op_sel:[0,1] op_sel_hi:[1,0]
	s_nop 0
	v_pk_fma_f32 v[82:83], v[82:83], v[74:75], v[90:91] op_sel_hi:[1,0,1]
	s_nop 0
	s_nop 0
	v_pk_mul_f32 v[90:91], v[76:77], v[82:83] op_sel:[1,1] op_sel_hi:[0,1] neg_hi:[0,1]
	v_pk_fma_f32 v[76:77], v[76:77], v[82:83], v[90:91] op_sel_hi:[1,0,1]
	ds_write_b64 v88, v[76:77] offset:6656
	v_pk_mul_f32 v[76:77], v[78:79], v[82:83] op_sel:[0,1] op_sel_hi:[1,0]
	s_nop 0
	v_pk_fma_f32 v[76:77], v[82:83], v[74:75], v[76:77] op_sel_hi:[1,0,1]
	s_nop 0
	s_nop 0
	v_pk_mul_f32 v[82:83], v[80:81], v[76:77] op_sel:[1,1] op_sel_hi:[0,1] neg_hi:[0,1]
	v_pk_fma_f32 v[80:81], v[80:81], v[76:77], v[82:83] op_sel_hi:[1,0,1]
	ds_write_b64 v87, v[80:81] offset:6912
	v_pk_mul_f32 v[80:81], v[78:79], v[76:77] op_sel:[0,1] op_sel_hi:[1,0]
	s_nop 0
	v_pk_fma_f32 v[76:77], v[76:77], v[74:75], v[80:81] op_sel_hi:[1,0,1]
	s_nop 0
	s_nop 0
	v_pk_mul_f32 v[80:81], v[68:69], v[76:77] op_sel:[1,1] op_sel_hi:[0,1] neg_hi:[0,1]
	v_pk_fma_f32 v[68:69], v[68:69], v[76:77], v[80:81] op_sel_hi:[1,0,1]
	ds_write_b64 v86, v[68:69] offset:7168
	v_pk_mul_f32 v[68:69], v[78:79], v[76:77] op_sel:[0,1] op_sel_hi:[1,0]
	s_nop 0
	v_pk_fma_f32 v[68:69], v[76:77], v[74:75], v[68:69] op_sel_hi:[1,0,1]
	s_nop 0
	s_nop 0
	v_pk_mul_f32 v[76:77], v[72:73], v[68:69] op_sel:[1,1] op_sel_hi:[0,1] neg_hi:[0,1]
	v_pk_fma_f32 v[72:73], v[72:73], v[68:69], v[76:77] op_sel_hi:[1,0,1]
	ds_write_b64 v85, v[72:73] offset:7424
	v_pk_mul_f32 v[72:73], v[78:79], v[68:69] op_sel:[0,1] op_sel_hi:[1,0]
	s_nop 0
	v_pk_fma_f32 v[68:69], v[68:69], v[74:75], v[72:73] op_sel_hi:[1,0,1]
	s_nop 0
	s_nop 0
	v_pk_mul_f32 v[72:73], v[66:67], v[68:69] op_sel:[1,1] op_sel_hi:[0,1] neg_hi:[0,1]
	v_pk_fma_f32 v[66:67], v[66:67], v[68:69], v[72:73] op_sel_hi:[1,0,1]
	ds_write_b64 v84, v[66:67] offset:7680
	v_pk_mul_f32 v[66:67], v[78:79], v[68:69] op_sel:[0,1] op_sel_hi:[1,0]
	s_nop 0
	v_pk_fma_f32 v[66:67], v[68:69], v[74:75], v[66:67] op_sel_hi:[1,0,1]
	s_nop 0
	s_nop 0
	v_pk_mul_f32 v[68:69], v[70:71], v[66:67] op_sel:[1,1] op_sel_hi:[0,1] neg_hi:[0,1]
	v_pk_fma_f32 v[66:67], v[70:71], v[66:67], v[68:69] op_sel_hi:[1,0,1]
	ds_write_b64 v0, v[66:67]
	s_waitcnt lgkmcnt(0)
	s_barrier
	ds_read2_b64 v[66:69], v104 offset1:1
	ds_read2_b64 v[70:73], v104 offset0:2 offset1:3
	ds_read2_b64 v[74:77], v104 offset0:4 offset1:5
	ds_read2_b64 v[78:81], v104 offset0:6 offset1:7
	ds_read2_b64 v[82:85], v104 offset0:8 offset1:9
	ds_read2_b64 v[86:89], v104 offset0:10 offset1:11
	ds_read2_b64 v[90:93], v104 offset0:12 offset1:13
	ds_read2_b64 v[94:97], v104 offset0:14 offset1:15
	ds_read2_b64 v[98:101], v104 offset0:16 offset1:17
	ds_read2_b64 v[106:109], v104 offset0:18 offset1:19
	ds_read2_b64 v[110:113], v104 offset0:20 offset1:21
	ds_read2_b64 v[114:117], v104 offset0:22 offset1:23
	ds_read2_b64 v[118:121], v104 offset0:24 offset1:25
	ds_read2_b64 v[122:125], v104 offset0:26 offset1:27
	ds_read2_b64 v[126:129], v104 offset0:28 offset1:29
	ds_read2_b64 v[130:133], v104 offset0:30 offset1:31
	s_waitcnt lgkmcnt(7)
	v_pk_add_f32 v[102:103], v[66:67], v[98:99]
	v_pk_add_f32 v[66:67], v[66:67], v[98:99] neg_lo:[0,1] neg_hi:[0,1]
	v_pk_add_f32 v[98:99], v[68:69], v[100:101]
	v_pk_add_f32 v[68:69], v[68:69], v[100:101] neg_lo:[0,1] neg_hi:[0,1]
	global_load_dwordx2 v[134:135], v[2:3], off
	global_load_dwordx2 v[136:137], v[4:5], off
	global_load_dwordx2 v[138:139], v[6:7], off
	v_pk_mul_f32 v[100:101], v[68:69], s[18:19]
	global_load_dwordx2 v[148:149], v[14:15], off
	global_load_dwordx2 v[154:155], v[16:17], off
	v_pk_fma_f32 v[68:69], v[68:69], s[20:21], v[100:101] op_sel:[0,0,1] op_sel_hi:[1,0,0]
	s_waitcnt lgkmcnt(6)
	v_pk_add_f32 v[100:101], v[70:71], v[106:107]
	v_pk_add_f32 v[70:71], v[70:71], v[106:107] neg_lo:[0,1] neg_hi:[0,1]
	global_load_dwordx2 v[158:159], v[18:19], off
	v_pk_mul_f32 v[106:107], v[70:71], s[4:5]
	global_load_dwordx2 v[160:161], v[28:29], off
	global_load_dwordx2 v[164:165], v[32:33], off
	v_pk_fma_f32 v[70:71], v[70:71], s[6:7], v[106:107] op_sel:[0,0,1] op_sel_hi:[1,0,0]
	v_pk_add_f32 v[106:107], v[72:73], v[108:109]
	v_pk_add_f32 v[72:73], v[72:73], v[108:109] neg_lo:[0,1] neg_hi:[0,1]
	global_load_dwordx2 v[168:169], v[36:37], off
	v_pk_mul_f32 v[108:109], v[72:73], s[22:23]
	global_load_dwordx2 v[172:173], v[44:45], off
	v_pk_fma_f32 v[72:73], v[72:73], s[24:25], v[108:109] op_sel:[0,0,1] op_sel_hi:[1,0,0]
	s_waitcnt lgkmcnt(5)
	v_pk_add_f32 v[108:109], v[74:75], v[110:111]
	v_pk_add_f32 v[74:75], v[74:75], v[110:111] neg_lo:[0,1] neg_hi:[0,1]
	global_load_dwordx2 v[174:175], v[52:53], off
	v_pk_mul_f32 v[110:111], v[74:75], s[8:9]
	global_load_dwordx2 v[176:177], v[60:61], off
	v_pk_fma_f32 v[74:75], v[74:75], s[10:11], v[110:111] op_sel:[0,0,1] op_sel_hi:[1,0,0]
	v_pk_add_f32 v[110:111], v[76:77], v[112:113]
	v_pk_add_f32 v[76:77], v[76:77], v[112:113] neg_lo:[0,1] neg_hi:[0,1]
	s_nop 0
	v_pk_mul_f32 v[112:113], v[76:77], s[26:27]
	s_nop 0
	v_pk_fma_f32 v[76:77], v[76:77], s[0:1], v[112:113] op_sel:[0,0,1] op_sel_hi:[1,0,0]
	s_waitcnt lgkmcnt(4)
	v_pk_add_f32 v[112:113], v[78:79], v[114:115]
	v_pk_add_f32 v[78:79], v[78:79], v[114:115] neg_lo:[0,1] neg_hi:[0,1]
	s_nop 0
	v_pk_mul_f32 v[114:115], v[78:79], s[12:13]
	s_nop 0
	v_pk_fma_f32 v[78:79], v[78:79], s[14:15], v[114:115] op_sel:[0,0,1] op_sel_hi:[1,0,0]
	v_pk_add_f32 v[114:115], v[80:81], v[116:117]
	v_pk_add_f32 v[80:81], v[80:81], v[116:117] neg_lo:[0,1] neg_hi:[0,1]
	s_nop 0
	v_pk_mul_f32 v[116:117], v[80:81], s[34:35]
	s_nop 0
	v_pk_fma_f32 v[80:81], v[80:81], s[48:49], v[116:117] op_sel:[0,0,1] op_sel_hi:[1,0,0]
	s_waitcnt lgkmcnt(3)
	v_pk_add_f32 v[116:117], v[82:83], v[118:119]
	v_pk_add_f32 v[118:119], v[82:83], v[118:119] op_sel:[1,1] op_sel_hi:[0,0] neg_lo:[0,1] neg_hi:[1,0]
	s_nop 0
	v_pk_add_f32 v[82:83], v[84:85], v[120:121]
	v_pk_add_f32 v[84:85], v[84:85], v[120:121] neg_lo:[0,1] neg_hi:[0,1]
	s_nop 0
	v_pk_mul_f32 v[120:121], v[84:85], s[34:35]
	s_nop 0
	v_pk_fma_f32 v[84:85], v[84:85], s[18:19], v[120:121] op_sel:[0,0,1] op_sel_hi:[1,0,0]
	s_waitcnt lgkmcnt(2)
	v_pk_add_f32 v[120:121], v[86:87], v[122:123]
	v_pk_add_f32 v[86:87], v[86:87], v[122:123] neg_lo:[0,1] neg_hi:[0,1]
	s_nop 0
	v_pk_mul_f32 v[122:123], v[86:87], s[12:13]
	s_nop 0
	v_pk_fma_f32 v[86:87], v[86:87], s[4:5], v[122:123] op_sel:[0,0,1] op_sel_hi:[1,0,0]
	v_pk_add_f32 v[122:123], v[88:89], v[124:125]
	v_pk_add_f32 v[88:89], v[88:89], v[124:125] neg_lo:[0,1] neg_hi:[0,1]
	s_nop 0
	v_pk_mul_f32 v[124:125], v[88:89], s[26:27]
	s_nop 0
	v_pk_fma_f32 v[88:89], v[88:89], s[22:23], v[124:125] op_sel:[0,0,1] op_sel_hi:[1,0,0]
	s_waitcnt lgkmcnt(1)
	v_pk_add_f32 v[124:125], v[90:91], v[126:127]
	v_pk_add_f32 v[90:91], v[90:91], v[126:127] neg_lo:[0,1] neg_hi:[0,1]
	s_nop 0
	v_pk_mul_f32 v[126:127], v[90:91], s[8:9]
	s_nop 0
	v_pk_fma_f32 v[90:91], v[90:91], s[8:9], v[126:127] op_sel:[0,0,1] op_sel_hi:[1,0,0]
	v_pk_add_f32 v[126:127], v[92:93], v[128:129]
	v_pk_add_f32 v[92:93], v[92:93], v[128:129] neg_lo:[0,1] neg_hi:[0,1]
	s_nop 0
	v_pk_mul_f32 v[128:129], v[92:93], s[22:23]
	s_nop 0
	v_pk_fma_f32 v[92:93], v[92:93], s[26:27], v[128:129] op_sel:[0,0,1] op_sel_hi:[1,0,0]
	s_waitcnt lgkmcnt(0)
	v_pk_add_f32 v[128:129], v[94:95], v[130:131]
	v_pk_add_f32 v[94:95], v[94:95], v[130:131] neg_lo:[0,1] neg_hi:[0,1]
	s_nop 0
	v_pk_mul_f32 v[130:131], v[94:95], s[4:5]
	s_nop 0
	v_pk_fma_f32 v[94:95], v[94:95], s[12:13], v[130:131] op_sel:[0,0,1] op_sel_hi:[1,0,0]
	v_pk_add_f32 v[130:131], v[96:97], v[132:133]
	v_pk_add_f32 v[96:97], v[96:97], v[132:133] neg_lo:[0,1] neg_hi:[0,1]
	s_nop 0
	v_pk_mul_f32 v[132:133], v[96:97], s[18:19]
	s_nop 0
	v_pk_fma_f32 v[96:97], v[96:97], s[34:35], v[132:133] op_sel:[0,0,1] op_sel_hi:[1,0,0]
	v_pk_add_f32 v[132:133], v[102:103], v[116:117]
	v_pk_add_f32 v[102:103], v[102:103], v[116:117] neg_lo:[0,1] neg_hi:[0,1]
	v_pk_add_f32 v[116:117], v[98:99], v[82:83]
	v_pk_add_f32 v[82:83], v[98:99], v[82:83] neg_lo:[0,1] neg_hi:[0,1]
	s_nop 0
	v_pk_mul_f32 v[98:99], v[82:83], s[4:5]
	s_nop 0
	v_pk_fma_f32 v[82:83], v[82:83], s[6:7], v[98:99] op_sel:[0,0,1] op_sel_hi:[1,0,0]
	v_pk_add_f32 v[98:99], v[100:101], v[120:121]
	v_pk_add_f32 v[100:101], v[100:101], v[120:121] neg_lo:[0,1] neg_hi:[0,1]
	s_nop 0
	v_pk_mul_f32 v[120:121], v[100:101], s[8:9]
	s_nop 0
	v_pk_fma_f32 v[100:101], v[100:101], s[10:11], v[120:121] op_sel:[0,0,1] op_sel_hi:[1,0,0]
	v_pk_add_f32 v[120:121], v[106:107], v[122:123]
	v_pk_add_f32 v[106:107], v[106:107], v[122:123] neg_lo:[0,1] neg_hi:[0,1]
	s_nop 0
	v_pk_mul_f32 v[122:123], v[106:107], s[12:13]
	s_nop 0
	v_pk_fma_f32 v[106:107], v[106:107], s[14:15], v[122:123] op_sel:[0,0,1] op_sel_hi:[1,0,0]
	v_pk_add_f32 v[122:123], v[108:109], v[124:125]
	v_pk_add_f32 v[124:125], v[108:109], v[124:125] op_sel:[1,1] op_sel_hi:[0,0] neg_lo:[0,1] neg_hi:[1,0]
	s_nop 0
	v_pk_add_f32 v[108:109], v[110:111], v[126:127]
	v_pk_add_f32 v[110:111], v[110:111], v[126:127] neg_lo:[0,1] neg_hi:[0,1]
	s_nop 0
	v_pk_mul_f32 v[126:127], v[110:111], s[12:13]
	s_nop 0
	v_pk_fma_f32 v[110:111], v[110:111], s[4:5], v[126:127] op_sel:[0,0,1] op_sel_hi:[1,0,0]
	v_pk_add_f32 v[126:127], v[112:113], v[128:129]
	v_pk_add_f32 v[112:113], v[112:113], v[128:129] neg_lo:[0,1] neg_hi:[0,1]
	s_nop 0
	v_pk_mul_f32 v[128:129], v[112:113], s[8:9]
	s_nop 0
	v_pk_fma_f32 v[112:113], v[112:113], s[8:9], v[128:129] op_sel:[0,0,1] op_sel_hi:[1,0,0]
	v_pk_add_f32 v[128:129], v[114:115], v[130:131]
	v_pk_add_f32 v[114:115], v[114:115], v[130:131] neg_lo:[0,1] neg_hi:[0,1]
	s_nop 0
	v_pk_mul_f32 v[130:131], v[114:115], s[4:5]
	s_nop 0
	v_pk_fma_f32 v[114:115], v[114:115], s[12:13], v[130:131] op_sel:[0,0,1] op_sel_hi:[1,0,0]
	v_pk_add_f32 v[130:131], v[66:67], v[118:119]
	v_pk_add_f32 v[66:67], v[66:67], v[118:119] neg_lo:[0,1] neg_hi:[0,1]
	v_pk_add_f32 v[118:119], v[68:69], v[84:85]
	v_pk_add_f32 v[68:69], v[68:69], v[84:85] neg_lo:[0,1] neg_hi:[0,1]
	s_nop 0
	v_pk_mul_f32 v[84:85], v[68:69], s[4:5]
	s_nop 0
	v_pk_fma_f32 v[68:69], v[68:69], s[6:7], v[84:85] op_sel:[0,0,1] op_sel_hi:[1,0,0]
	v_pk_add_f32 v[84:85], v[70:71], v[86:87]
	v_pk_add_f32 v[70:71], v[70:71], v[86:87] neg_lo:[0,1] neg_hi:[0,1]
	s_nop 0
	v_pk_mul_f32 v[86:87], v[70:71], s[8:9]
	s_nop 0
	v_pk_fma_f32 v[70:71], v[70:71], s[10:11], v[86:87] op_sel:[0,0,1] op_sel_hi:[1,0,0]
	v_pk_add_f32 v[86:87], v[72:73], v[88:89]
	v_pk_add_f32 v[72:73], v[72:73], v[88:89] neg_lo:[0,1] neg_hi:[0,1]
	s_nop 0
	v_pk_mul_f32 v[88:89], v[72:73], s[12:13]
	s_nop 0
	v_pk_fma_f32 v[72:73], v[72:73], s[14:15], v[88:89] op_sel:[0,0,1] op_sel_hi:[1,0,0]
	v_pk_add_f32 v[88:89], v[74:75], v[90:91]
	v_pk_add_f32 v[90:91], v[74:75], v[90:91] op_sel:[1,1] op_sel_hi:[0,0] neg_lo:[0,1] neg_hi:[1,0]
	s_mov_b32 s15, s4
	v_pk_add_f32 v[74:75], v[76:77], v[92:93]
	v_pk_add_f32 v[76:77], v[76:77], v[92:93] neg_lo:[0,1] neg_hi:[0,1]
	s_nop 0
	v_pk_mul_f32 v[92:93], v[76:77], s[12:13]
	s_nop 0
	v_pk_fma_f32 v[76:77], v[76:77], s[4:5], v[92:93] op_sel:[0,0,1] op_sel_hi:[1,0,0]
	v_pk_add_f32 v[92:93], v[78:79], v[94:95]
	v_pk_add_f32 v[78:79], v[78:79], v[94:95] neg_lo:[0,1] neg_hi:[0,1]
	s_nop 0
	v_pk_mul_f32 v[94:95], v[78:79], s[8:9]
	s_nop 0
	v_pk_fma_f32 v[78:79], v[78:79], s[8:9], v[94:95] op_sel:[0,0,1] op_sel_hi:[1,0,0]
	v_pk_add_f32 v[94:95], v[80:81], v[96:97]
	v_pk_add_f32 v[80:81], v[80:81], v[96:97] neg_lo:[0,1] neg_hi:[0,1]
	s_nop 0
	v_pk_mul_f32 v[96:97], v[80:81], s[4:5]
	s_nop 0
	v_pk_fma_f32 v[80:81], v[80:81], s[12:13], v[96:97] op_sel:[0,0,1] op_sel_hi:[1,0,0]
	v_pk_add_f32 v[96:97], v[132:133], v[122:123]
	v_pk_add_f32 v[122:123], v[132:133], v[122:123] neg_lo:[0,1] neg_hi:[0,1]
	v_pk_add_f32 v[132:133], v[116:117], v[108:109]
	v_pk_add_f32 v[108:109], v[116:117], v[108:109] neg_lo:[0,1] neg_hi:[0,1]
	s_nop 0
	v_pk_mul_f32 v[116:117], v[108:109], s[8:9]
	s_nop 0
	v_pk_fma_f32 v[108:109], v[108:109], s[10:11], v[116:117] op_sel:[0,0,1] op_sel_hi:[1,0,0]
	v_pk_add_f32 v[116:117], v[98:99], v[126:127]
	v_pk_add_f32 v[126:127], v[98:99], v[126:127] op_sel:[1,1] op_sel_hi:[0,0] neg_lo:[0,1] neg_hi:[1,0]
	s_nop 0
	v_pk_add_f32 v[98:99], v[120:121], v[128:129]
	v_pk_add_f32 v[120:121], v[120:121], v[128:129] neg_lo:[0,1] neg_hi:[0,1]
	s_nop 0
	v_pk_mul_f32 v[128:129], v[120:121], s[8:9]
	s_nop 0
	v_pk_fma_f32 v[120:121], v[120:121], s[8:9], v[128:129] op_sel:[0,0,1] op_sel_hi:[1,0,0]
	v_pk_add_f32 v[128:129], v[102:103], v[124:125]
	v_pk_add_f32 v[102:103], v[102:103], v[124:125] neg_lo:[0,1] neg_hi:[0,1]
	v_pk_add_f32 v[124:125], v[82:83], v[110:111]
	v_pk_add_f32 v[82:83], v[82:83], v[110:111] neg_lo:[0,1] neg_hi:[0,1]
	s_nop 0
	v_pk_mul_f32 v[110:111], v[82:83], s[8:9]
	s_nop 0
	v_pk_fma_f32 v[82:83], v[82:83], s[10:11], v[110:111] op_sel:[0,0,1] op_sel_hi:[1,0,0]
	v_pk_add_f32 v[110:111], v[100:101], v[112:113]
	v_pk_add_f32 v[112:113], v[100:101], v[112:113] op_sel:[1,1] op_sel_hi:[0,0] neg_lo:[0,1] neg_hi:[1,0]
	s_nop 0
	v_pk_add_f32 v[100:101], v[106:107], v[114:115]
	v_pk_add_f32 v[106:107], v[106:107], v[114:115] neg_lo:[0,1] neg_hi:[0,1]
	s_nop 0
	v_pk_mul_f32 v[114:115], v[106:107], s[8:9]
	s_nop 0
	v_pk_fma_f32 v[106:107], v[106:107], s[8:9], v[114:115] op_sel:[0,0,1] op_sel_hi:[1,0,0]
	v_pk_add_f32 v[114:115], v[130:131], v[88:89]
	v_pk_add_f32 v[88:89], v[130:131], v[88:89] neg_lo:[0,1] neg_hi:[0,1]
	v_pk_add_f32 v[130:131], v[118:119], v[74:75]
	v_pk_add_f32 v[74:75], v[118:119], v[74:75] neg_lo:[0,1] neg_hi:[0,1]
	s_nop 0
	v_pk_mul_f32 v[118:119], v[74:75], s[8:9]
	s_nop 0
	v_pk_fma_f32 v[74:75], v[74:75], s[10:11], v[118:119] op_sel:[0,0,1] op_sel_hi:[1,0,0]
	v_pk_add_f32 v[118:119], v[84:85], v[92:93]
	v_pk_add_f32 v[92:93], v[84:85], v[92:93] op_sel:[1,1] op_sel_hi:[0,0] neg_lo:[0,1] neg_hi:[1,0]
	s_nop 0
	v_pk_add_f32 v[84:85], v[86:87], v[94:95]
	v_pk_add_f32 v[86:87], v[86:87], v[94:95] neg_lo:[0,1] neg_hi:[0,1]
	v_pk_add_f32 v[140:141], v[88:89], v[92:93]
	v_pk_mul_f32 v[94:95], v[86:87], s[8:9]
	v_pk_add_f32 v[88:89], v[88:89], v[92:93] neg_lo:[0,1] neg_hi:[0,1]
	v_pk_fma_f32 v[86:87], v[86:87], s[8:9], v[94:95] op_sel:[0,0,1] op_sel_hi:[1,0,0]
	v_pk_add_f32 v[94:95], v[66:67], v[90:91]
	v_pk_add_f32 v[66:67], v[66:67], v[90:91] neg_lo:[0,1] neg_hi:[0,1]
	v_pk_add_f32 v[90:91], v[68:69], v[76:77]
	v_pk_add_f32 v[68:69], v[68:69], v[76:77] neg_lo:[0,1] neg_hi:[0,1]
	v_pk_add_f32 v[92:93], v[74:75], v[86:87]
	v_pk_mul_f32 v[76:77], v[68:69], s[8:9]
	v_pk_add_f32 v[142:143], v[74:75], v[86:87] op_sel:[1,1] op_sel_hi:[0,0] neg_lo:[0,1] neg_hi:[1,0]
	v_pk_fma_f32 v[68:69], v[68:69], s[10:11], v[76:77] op_sel:[0,0,1] op_sel_hi:[1,0,0]
	v_pk_add_f32 v[76:77], v[70:71], v[78:79]
	v_pk_add_f32 v[78:79], v[70:71], v[78:79] op_sel:[1,1] op_sel_hi:[0,0] neg_lo:[0,1] neg_hi:[1,0]
	global_load_dwordx2 v[86:87], v[10:11], off
	v_pk_add_f32 v[70:71], v[72:73], v[80:81]
	v_pk_add_f32 v[72:73], v[72:73], v[80:81] neg_lo:[0,1] neg_hi:[0,1]
	v_pk_mul_f32 v[80:81], v[72:73], s[8:9]
	v_pk_fma_f32 v[72:73], v[72:73], s[8:9], v[80:81] op_sel:[0,0,1] op_sel_hi:[1,0,0]
	v_pk_add_f32 v[80:81], v[96:97], v[116:117]
	v_pk_add_f32 v[96:97], v[96:97], v[116:117] neg_lo:[0,1] neg_hi:[0,1]
	v_pk_add_f32 v[116:117], v[132:133], v[98:99]
	v_pk_add_f32 v[132:133], v[132:133], v[98:99] op_sel:[1,1] op_sel_hi:[0,0] neg_lo:[0,1] neg_hi:[1,0]
	v_pk_add_f32 v[74:75], v[94:95], v[76:77]
	v_pk_add_f32 v[98:99], v[122:123], v[126:127]
	v_pk_add_f32 v[122:123], v[122:123], v[126:127] neg_lo:[0,1] neg_hi:[0,1]
	v_pk_add_f32 v[126:127], v[108:109], v[120:121]
	v_pk_add_f32 v[120:121], v[108:109], v[120:121] op_sel:[1,1] op_sel_hi:[0,0] neg_lo:[0,1] neg_hi:[1,0]
	v_pk_add_f32 v[76:77], v[94:95], v[76:77] neg_lo:[0,1] neg_hi:[0,1]
	v_pk_add_f32 v[108:109], v[128:129], v[110:111]
	v_pk_add_f32 v[110:111], v[128:129], v[110:111] neg_lo:[0,1] neg_hi:[0,1]
	v_pk_add_f32 v[128:129], v[124:125], v[100:101]
	v_pk_add_f32 v[124:125], v[124:125], v[100:101] op_sel:[1,1] op_sel_hi:[0,0] neg_lo:[0,1] neg_hi:[1,0]
	global_load_dwordx2 v[94:95], v[12:13], off
	v_pk_add_f32 v[100:101], v[102:103], v[112:113]
	v_pk_add_f32 v[102:103], v[102:103], v[112:113] neg_lo:[0,1] neg_hi:[0,1]
	v_pk_add_f32 v[112:113], v[82:83], v[106:107]
	v_pk_add_f32 v[106:107], v[82:83], v[106:107] op_sel:[1,1] op_sel_hi:[0,0] neg_lo:[0,1] neg_hi:[1,0]
	v_pk_add_f32 v[146:147], v[66:67], v[78:79]
	v_pk_add_f32 v[82:83], v[114:115], v[118:119]
	v_pk_add_f32 v[114:115], v[114:115], v[118:119] neg_lo:[0,1] neg_hi:[0,1]
	v_pk_add_f32 v[118:119], v[130:131], v[84:85]
	v_pk_add_f32 v[130:131], v[130:131], v[84:85] op_sel:[1,1] op_sel_hi:[0,0] neg_lo:[0,1] neg_hi:[1,0]
	v_pk_add_f32 v[78:79], v[66:67], v[78:79] neg_lo:[0,1] neg_hi:[0,1]
	global_load_dwordx2 v[84:85], v[8:9], off
	v_pk_add_f32 v[152:153], v[68:69], v[72:73] op_sel:[1,1] op_sel_hi:[0,0] neg_lo:[0,1] neg_hi:[1,0]
	v_pk_add_f32 v[150:151], v[68:69], v[72:73]
	v_pk_add_f32 v[156:157], v[80:81], v[116:117]
	v_pk_add_f32 v[80:81], v[80:81], v[116:117] neg_lo:[0,1] neg_hi:[0,1]
	v_pk_add_f32 v[116:117], v[96:97], v[132:133]
	v_pk_add_f32 v[68:69], v[96:97], v[132:133] neg_lo:[0,1] neg_hi:[0,1]
	v_pk_add_f32 v[96:97], v[98:99], v[126:127]
	v_pk_add_f32 v[98:99], v[98:99], v[126:127] neg_lo:[0,1] neg_hi:[0,1]
	v_pk_add_f32 v[126:127], v[122:123], v[120:121]
	v_pk_add_f32 v[66:67], v[122:123], v[120:121] neg_lo:[0,1] neg_hi:[0,1]
	global_load_dwordx2 v[120:121], v[20:21], off
	v_pk_add_f32 v[122:123], v[108:109], v[128:129]
	v_pk_add_f32 v[108:109], v[108:109], v[128:129] neg_lo:[0,1] neg_hi:[0,1]
	v_pk_add_f32 v[128:129], v[110:111], v[124:125]
	v_pk_add_f32 v[72:73], v[110:111], v[124:125] neg_lo:[0,1] neg_hi:[0,1]
	global_load_dwordx2 v[110:111], v[22:23], off
	v_pk_add_f32 v[144:145], v[90:91], v[70:71]
	v_pk_add_f32 v[90:91], v[90:91], v[70:71] op_sel:[1,1] op_sel_hi:[0,0] neg_lo:[0,1] neg_hi:[1,0]
	v_pk_add_f32 v[124:125], v[100:101], v[112:113]
	v_pk_add_f32 v[100:101], v[100:101], v[112:113] neg_lo:[0,1] neg_hi:[0,1]
	v_pk_add_f32 v[112:113], v[102:103], v[106:107]
	v_pk_add_f32 v[70:71], v[102:103], v[106:107] neg_lo:[0,1] neg_hi:[0,1]
	global_load_dwordx2 v[102:103], v[24:25], off
	v_pk_add_f32 v[106:107], v[82:83], v[118:119]
	v_pk_add_f32 v[82:83], v[82:83], v[118:119] neg_lo:[0,1] neg_hi:[0,1]
	v_pk_add_f32 v[118:119], v[114:115], v[130:131]
	v_pk_add_f32 v[114:115], v[114:115], v[130:131] neg_lo:[0,1] neg_hi:[0,1]
	global_load_dwordx2 v[130:131], v[26:27], off
	v_pk_add_f32 v[162:163], v[76:77], v[90:91]
	v_pk_add_f32 v[76:77], v[76:77], v[90:91] neg_lo:[0,1] neg_hi:[0,1]
	v_pk_add_f32 v[90:91], v[146:147], v[150:151]
	v_pk_add_f32 v[146:147], v[146:147], v[150:151] neg_lo:[0,1] neg_hi:[0,1]
	v_pk_add_f32 v[150:151], v[78:79], v[152:153]
	v_pk_add_f32 v[78:79], v[78:79], v[152:153] neg_lo:[0,1] neg_hi:[0,1]
	global_load_dwordx2 v[152:153], v[34:35], off
	s_waitcnt vmcnt(19)
	v_pk_mul_f32 v[166:167], v[156:157], v[134:135] op_sel:[1,1] op_sel_hi:[0,1] neg_lo:[0,1]
	v_pk_add_f32 v[132:133], v[140:141], v[92:93]
	v_pk_fma_f32 v[134:135], v[156:157], v[134:135], v[166:167] op_sel_hi:[1,0,1]
	s_waitcnt vmcnt(18)
	global_load_dwordx2 v[166:167], v[38:39], off
	v_pk_mul_f32 v[156:157], v[106:107], v[136:137] op_sel:[1,1] op_sel_hi:[0,1] neg_lo:[0,1]
	v_pk_add_f32 v[92:93], v[140:141], v[92:93] neg_lo:[0,1] neg_hi:[0,1]
	v_pk_fma_f32 v[106:107], v[106:107], v[136:137], v[156:157] op_sel_hi:[1,0,1]
	s_waitcnt vmcnt(18)
	global_load_dwordx2 v[156:157], v[40:41], off
	v_pk_mul_f32 v[136:137], v[122:123], v[138:139] op_sel:[1,1] op_sel_hi:[0,1] neg_lo:[0,1]
	v_pk_add_f32 v[140:141], v[88:89], v[142:143]
	v_pk_fma_f32 v[122:123], v[122:123], v[138:139], v[136:137] op_sel_hi:[1,0,1]
	global_load_dwordx2 v[136:137], v[42:43], off
	v_pk_add_f32 v[88:89], v[88:89], v[142:143] neg_lo:[0,1] neg_hi:[0,1]
	v_pk_add_f32 v[142:143], v[74:75], v[144:145]
	v_pk_add_f32 v[74:75], v[74:75], v[144:145] neg_lo:[0,1] neg_hi:[0,1]
	global_load_dwordx2 v[144:145], v[30:31], off
	s_mov_b32 s11, s8
	s_waitcnt vmcnt(9)
	v_pk_mul_f32 v[138:139], v[142:143], v[84:85] op_sel:[1,1] op_sel_hi:[0,1] neg_lo:[0,1]
	s_nop 0
	v_pk_fma_f32 v[84:85], v[142:143], v[84:85], v[138:139] op_sel_hi:[1,0,1]
	global_load_dwordx2 v[142:143], v[46:47], off
	v_pk_mul_f32 v[138:139], v[96:97], v[86:87] op_sel:[1,1] op_sel_hi:[0,1] neg_lo:[0,1]
	s_nop 0
	v_pk_fma_f32 v[86:87], v[96:97], v[86:87], v[138:139] op_sel_hi:[1,0,1]
	global_load_dwordx2 v[138:139], v[48:49], off
	v_pk_mul_f32 v[96:97], v[132:133], v[94:95] op_sel:[1,1] op_sel_hi:[0,1] neg_lo:[0,1]
	s_nop 0
	v_pk_fma_f32 v[94:95], v[132:133], v[94:95], v[96:97] op_sel_hi:[1,0,1]
	global_load_dwordx2 v[96:97], v[50:51], off
	v_pk_mul_f32 v[132:133], v[124:125], v[148:149] op_sel:[1,1] op_sel_hi:[0,1] neg_lo:[0,1]
	s_nop 0
	v_pk_fma_f32 v[124:125], v[124:125], v[148:149], v[132:133] op_sel_hi:[1,0,1]
	global_load_dwordx2 v[148:149], v[54:55], off
	v_pk_mul_f32 v[132:133], v[90:91], v[154:155] op_sel:[1,1] op_sel_hi:[0,1] neg_lo:[0,1]
	s_nop 0
	v_pk_fma_f32 v[90:91], v[90:91], v[154:155], v[132:133] op_sel_hi:[1,0,1]
	global_load_dwordx2 v[154:155], v[56:57], off
	v_pk_mul_f32 v[132:133], v[116:117], v[158:159] op_sel:[1,1] op_sel_hi:[0,1] neg_lo:[0,1]
	v_pk_fma_f32 v[116:117], v[116:117], v[158:159], v[132:133] op_sel_hi:[1,0,1]
	global_load_dwordx2 v[132:133], v[58:59], off
	s_waitcnt vmcnt(14)
	v_pk_mul_f32 v[158:159], v[118:119], v[120:121] op_sel:[1,1] op_sel_hi:[0,1] neg_lo:[0,1]
	v_pk_fma_f32 v[118:119], v[118:119], v[120:121], v[158:159] op_sel_hi:[1,0,1]
	s_waitcnt vmcnt(13)
	global_load_dwordx2 v[158:159], v[62:63], off
	v_pk_mul_f32 v[120:121], v[128:129], v[110:111] op_sel:[1,1] op_sel_hi:[0,1] neg_lo:[0,1]
	v_pk_fma_f32 v[110:111], v[128:129], v[110:111], v[120:121] op_sel_hi:[1,0,1]
	global_load_dwordx2 v[128:129], v[64:65], off
	s_waitcnt vmcnt(14)
	v_pk_mul_f32 v[120:121], v[162:163], v[102:103] op_sel:[1,1] op_sel_hi:[0,1] neg_lo:[0,1]
	v_mov_b32 v0, 0
	s_nop 0
	v_pk_fma_f32 v[102:103], v[162:163], v[102:103], v[120:121] op_sel_hi:[1,0,1]
	s_waitcnt vmcnt(13)
	v_pk_mul_f32 v[120:121], v[126:127], v[130:131] op_sel:[1,1] op_sel_hi:[0,1] neg_lo:[0,1]
	v_pk_fma_f32 v[120:121], v[126:127], v[130:131], v[120:121] op_sel_hi:[1,0,1]
	v_pk_mul_f32 v[126:127], v[140:141], v[160:161] op_sel:[1,1] op_sel_hi:[0,1] neg_lo:[0,1]
	v_pk_fma_f32 v[126:127], v[140:141], v[160:161], v[126:127] op_sel_hi:[1,0,1]
	s_waitcnt vmcnt(12)
	v_pk_mul_f32 v[140:141], v[80:81], v[152:153] op_sel:[1,1] op_sel_hi:[0,1] neg_lo:[0,1]
	v_pk_fma_f32 v[80:81], v[80:81], v[152:153], v[140:141] op_sel_hi:[1,0,1]
	v_pk_mul_f32 v[140:141], v[82:83], v[168:169] op_sel:[1,1] op_sel_hi:[0,1] neg_lo:[0,1]
	v_pk_fma_f32 v[82:83], v[82:83], v[168:169], v[140:141] op_sel_hi:[1,0,1]
	s_waitcnt vmcnt(11)
	v_pk_mul_f32 v[140:141], v[108:109], v[166:167] op_sel:[1,1] op_sel_hi:[0,1] neg_lo:[0,1]
	v_pk_fma_f32 v[108:109], v[108:109], v[166:167], v[140:141] op_sel_hi:[1,0,1]
	s_waitcnt vmcnt(10)
	v_pk_mul_f32 v[140:141], v[74:75], v[156:157] op_sel:[1,1] op_sel_hi:[0,1] neg_lo:[0,1]
	v_pk_fma_f32 v[74:75], v[74:75], v[156:157], v[140:141] op_sel_hi:[1,0,1]
	s_waitcnt vmcnt(9)
	v_pk_mul_f32 v[140:141], v[98:99], v[136:137] op_sel:[1,1] op_sel_hi:[0,1] neg_lo:[0,1]
	v_pk_fma_f32 v[98:99], v[98:99], v[136:137], v[140:141] op_sel_hi:[1,0,1]
	v_pk_mul_f32 v[136:137], v[92:93], v[172:173] op_sel:[1,1] op_sel_hi:[0,1] neg_lo:[0,1]
	v_pk_fma_f32 v[92:93], v[92:93], v[172:173], v[136:137] op_sel_hi:[1,0,1]
	s_waitcnt vmcnt(8)
	v_pk_mul_f32 v[130:131], v[112:113], v[144:145] op_sel:[1,1] op_sel_hi:[0,1] neg_lo:[0,1]
	v_pk_fma_f32 v[112:113], v[112:113], v[144:145], v[130:131] op_sel_hi:[1,0,1]
	s_waitcnt vmcnt(7)
	v_pk_mul_f32 v[136:137], v[100:101], v[142:143] op_sel:[1,1] op_sel_hi:[0,1] neg_lo:[0,1]
	v_pk_fma_f32 v[100:101], v[100:101], v[142:143], v[136:137] op_sel_hi:[1,0,1]
	s_waitcnt vmcnt(6)
	v_pk_mul_f32 v[136:137], v[146:147], v[138:139] op_sel:[1,1] op_sel_hi:[0,1] neg_lo:[0,1]
	v_pk_fma_f32 v[136:137], v[146:147], v[138:139], v[136:137] op_sel_hi:[1,0,1]
	s_waitcnt vmcnt(5)
	v_pk_mul_f32 v[138:139], v[68:69], v[96:97] op_sel:[1,1] op_sel_hi:[0,1] neg_lo:[0,1]
	v_pk_fma_f32 v[68:69], v[68:69], v[96:97], v[138:139] op_sel_hi:[1,0,1]
	v_pk_mul_f32 v[96:97], v[114:115], v[174:175] op_sel:[1,1] op_sel_hi:[0,1] neg_lo:[0,1]
	v_pk_fma_f32 v[96:97], v[114:115], v[174:175], v[96:97] op_sel_hi:[1,0,1]
	s_waitcnt vmcnt(4)
	v_pk_mul_f32 v[114:115], v[72:73], v[148:149] op_sel:[1,1] op_sel_hi:[0,1] neg_lo:[0,1]
	v_pk_fma_f32 v[72:73], v[72:73], v[148:149], v[114:115] op_sel_hi:[1,0,1]
	v_pk_mul_f32 v[130:131], v[150:151], v[164:165] op_sel:[1,1] op_sel_hi:[0,1] neg_lo:[0,1]
	s_waitcnt vmcnt(3)
	v_pk_mul_f32 v[114:115], v[76:77], v[154:155] op_sel:[1,1] op_sel_hi:[0,1] neg_lo:[0,1]
	v_pk_fma_f32 v[76:77], v[76:77], v[154:155], v[114:115] op_sel_hi:[1,0,1]
	s_waitcnt vmcnt(2)
	v_pk_mul_f32 v[114:115], v[66:67], v[132:133] op_sel:[1,1] op_sel_hi:[0,1] neg_lo:[0,1]
	v_pk_fma_f32 v[66:67], v[66:67], v[132:133], v[114:115] op_sel_hi:[1,0,1]
	v_pk_mul_f32 v[114:115], v[88:89], v[176:177] op_sel:[1,1] op_sel_hi:[0,1] neg_lo:[0,1]
	v_pk_fma_f32 v[88:89], v[88:89], v[176:177], v[114:115] op_sel_hi:[1,0,1]
	s_waitcnt vmcnt(1)
	v_pk_mul_f32 v[114:115], v[70:71], v[158:159] op_sel:[1,1] op_sel_hi:[0,1] neg_lo:[0,1]
	v_pk_fma_f32 v[70:71], v[70:71], v[158:159], v[114:115] op_sel_hi:[1,0,1]
	s_waitcnt vmcnt(0)
	v_pk_mul_f32 v[114:115], v[78:79], v[128:129] op_sel:[1,1] op_sel_hi:[0,1] neg_lo:[0,1]
	v_pk_fma_f32 v[78:79], v[78:79], v[128:129], v[114:115] op_sel_hi:[1,0,1]
	v_pk_add_f32 v[128:129], v[106:107], v[82:83]
	v_pk_add_f32 v[82:83], v[106:107], v[82:83] neg_lo:[0,1] neg_hi:[0,1]
	v_pk_fma_f32 v[130:131], v[150:151], v[164:165], v[130:131] op_sel_hi:[1,0,1]
	v_pk_mul_f32 v[106:107], v[82:83], s[50:51]
	v_pk_add_f32 v[114:115], v[134:135], v[80:81]
	v_pk_fma_f32 v[82:83], v[82:83], s[20:21], v[106:107] op_sel:[0,0,1] op_sel_hi:[1,0,0]
	v_pk_add_f32 v[106:107], v[122:123], v[108:109]
	v_pk_add_f32 v[108:109], v[122:123], v[108:109] neg_lo:[0,1] neg_hi:[0,1]
	s_mov_b32 s21, s34
	v_pk_mul_f32 v[122:123], v[108:109], s[14:15]
	v_pk_add_f32 v[80:81], v[134:135], v[80:81] neg_lo:[0,1] neg_hi:[0,1]
	v_pk_fma_f32 v[108:109], v[108:109], s[6:7], v[122:123] op_sel:[0,0,1] op_sel_hi:[1,0,0]
	v_pk_add_f32 v[122:123], v[84:85], v[74:75]
	v_pk_add_f32 v[74:75], v[84:85], v[74:75] neg_lo:[0,1] neg_hi:[0,1]
	s_mov_b32 s7, s12
	v_pk_mul_f32 v[84:85], v[74:75], s[52:53]
	v_add_u32_e32 v0, v0, v170
	v_pk_fma_f32 v[74:75], v[74:75], s[24:25], v[84:85] op_sel:[0,0,1] op_sel_hi:[1,0,0]
	v_pk_add_f32 v[84:85], v[86:87], v[98:99]
	v_pk_add_f32 v[86:87], v[86:87], v[98:99] neg_lo:[0,1] neg_hi:[0,1]
	s_mov_b32 s25, s26
	v_pk_mul_f32 v[98:99], v[86:87], s[10:11]
	v_lshlrev_b32_e32 v105, 5, v0
	v_pk_fma_f32 v[86:87], v[86:87], s[10:11], v[98:99] op_sel:[0,0,1] op_sel_hi:[1,0,0]
	v_pk_add_f32 v[98:99], v[94:95], v[92:93]
	v_pk_add_f32 v[92:93], v[94:95], v[92:93] neg_lo:[0,1] neg_hi:[0,1]
	s_nop 0
	v_pk_mul_f32 v[94:95], v[92:93], s[24:25]
	s_nop 0
	v_pk_fma_f32 v[92:93], v[92:93], s[0:1], v[94:95] op_sel:[0,0,1] op_sel_hi:[1,0,0]
	v_pk_add_f32 v[94:95], v[124:125], v[100:101]
	v_pk_add_f32 v[100:101], v[124:125], v[100:101] neg_lo:[0,1] neg_hi:[0,1]
	s_nop 0
	v_pk_mul_f32 v[124:125], v[100:101], s[6:7]
	s_nop 0
	v_pk_fma_f32 v[100:101], v[100:101], s[14:15], v[124:125] op_sel:[0,0,1] op_sel_hi:[1,0,0]
	v_pk_add_f32 v[124:125], v[90:91], v[136:137]
	v_pk_add_f32 v[90:91], v[90:91], v[136:137] neg_lo:[0,1] neg_hi:[0,1]
	s_nop 0
	v_pk_mul_f32 v[132:133], v[90:91], s[20:21]
	s_nop 0
	v_pk_fma_f32 v[90:91], v[90:91], s[48:49], v[132:133] op_sel:[0,0,1] op_sel_hi:[1,0,0]
	v_pk_add_f32 v[132:133], v[116:117], v[68:69]
	v_pk_add_f32 v[116:117], v[116:117], v[68:69] op_sel:[1,1] op_sel_hi:[0,0] neg_lo:[1,0] neg_hi:[0,1]
	s_nop 0
	v_pk_add_f32 v[68:69], v[118:119], v[96:97]
	v_pk_add_f32 v[96:97], v[118:119], v[96:97] neg_lo:[0,1] neg_hi:[0,1]
	s_nop 0
	v_pk_mul_f32 v[118:119], v[96:97], s[20:21]
	s_nop 0
	v_pk_fma_f32 v[96:97], v[96:97], s[18:19], v[118:119] op_sel:[0,0,1] op_sel_hi:[1,0,0]
	v_pk_add_f32 v[118:119], v[110:111], v[72:73]
	v_pk_add_f32 v[72:73], v[110:111], v[72:73] neg_lo:[0,1] neg_hi:[0,1]
	s_nop 0
	v_pk_mul_f32 v[110:111], v[72:73], s[6:7]
	s_nop 0
	v_pk_fma_f32 v[72:73], v[72:73], s[4:5], v[110:111] op_sel:[0,0,1] op_sel_hi:[1,0,0]
	v_pk_add_f32 v[110:111], v[102:103], v[76:77]
	v_pk_add_f32 v[76:77], v[102:103], v[76:77] neg_lo:[0,1] neg_hi:[0,1]
	s_nop 0
	v_pk_mul_f32 v[102:103], v[76:77], s[24:25]
	s_nop 0
	v_pk_fma_f32 v[76:77], v[76:77], s[22:23], v[102:103] op_sel:[0,0,1] op_sel_hi:[1,0,0]
	v_pk_add_f32 v[102:103], v[120:121], v[66:67]
	v_pk_add_f32 v[66:67], v[120:121], v[66:67] neg_lo:[0,1] neg_hi:[0,1]
	s_nop 0
	v_pk_mul_f32 v[120:121], v[66:67], s[10:11]
	s_nop 0
	v_pk_fma_f32 v[66:67], v[66:67], s[8:9], v[120:121] op_sel:[0,0,1] op_sel_hi:[1,0,0]
	v_pk_add_f32 v[120:121], v[126:127], v[88:89]
	v_pk_add_f32 v[88:89], v[126:127], v[88:89] neg_lo:[0,1] neg_hi:[0,1]
	s_nop 0
	v_pk_mul_f32 v[126:127], v[88:89], s[52:53]
	s_nop 0
	v_pk_fma_f32 v[88:89], v[88:89], s[26:27], v[126:127] op_sel:[0,0,1] op_sel_hi:[1,0,0]
	v_pk_add_f32 v[126:127], v[112:113], v[70:71]
	v_pk_add_f32 v[70:71], v[112:113], v[70:71] neg_lo:[0,1] neg_hi:[0,1]
	s_nop 0
	v_pk_mul_f32 v[112:113], v[70:71], s[14:15]
	s_nop 0
	v_pk_fma_f32 v[70:71], v[70:71], s[12:13], v[112:113] op_sel:[0,0,1] op_sel_hi:[1,0,0]
	v_pk_add_f32 v[112:113], v[130:131], v[78:79]
	v_pk_add_f32 v[78:79], v[130:131], v[78:79] neg_lo:[0,1] neg_hi:[0,1]
	s_nop 0
	v_pk_mul_f32 v[130:131], v[78:79], s[50:51]
	s_nop 0
	v_pk_fma_f32 v[78:79], v[78:79], s[34:35], v[130:131] op_sel:[0,0,1] op_sel_hi:[1,0,0]
	v_pk_add_f32 v[130:131], v[114:115], v[132:133]
	v_pk_add_f32 v[114:115], v[114:115], v[132:133] neg_lo:[0,1] neg_hi:[0,1]
	v_pk_add_f32 v[132:133], v[128:129], v[68:69]
	v_pk_add_f32 v[68:69], v[128:129], v[68:69] neg_lo:[0,1] neg_hi:[0,1]
	s_nop 0
	v_pk_mul_f32 v[128:129], v[68:69], s[14:15]
	s_nop 0
	v_pk_fma_f32 v[68:69], v[68:69], s[6:7], v[128:129] op_sel:[0,0,1] op_sel_hi:[1,0,0]
	v_pk_add_f32 v[128:129], v[106:107], v[118:119]
	v_pk_add_f32 v[106:107], v[106:107], v[118:119] neg_lo:[0,1] neg_hi:[0,1]
	s_nop 0
	v_pk_mul_f32 v[118:119], v[106:107], s[10:11]
	s_nop 0
	v_pk_fma_f32 v[106:107], v[106:107], s[10:11], v[118:119] op_sel:[0,0,1] op_sel_hi:[1,0,0]
	v_pk_add_f32 v[118:119], v[122:123], v[110:111]
	v_pk_add_f32 v[110:111], v[122:123], v[110:111] neg_lo:[0,1] neg_hi:[0,1]
	s_nop 0
	v_pk_mul_f32 v[122:123], v[110:111], s[6:7]
	s_nop 0
	v_pk_fma_f32 v[110:111], v[110:111], s[14:15], v[122:123] op_sel:[0,0,1] op_sel_hi:[1,0,0]
	v_pk_add_f32 v[122:123], v[84:85], v[102:103]
	v_pk_add_f32 v[102:103], v[84:85], v[102:103] op_sel:[1,1] op_sel_hi:[0,0] neg_lo:[1,0] neg_hi:[0,1]
	s_nop 0
	v_pk_add_f32 v[84:85], v[98:99], v[120:121]
	v_pk_add_f32 v[98:99], v[98:99], v[120:121] neg_lo:[0,1] neg_hi:[0,1]
	s_nop 0
	v_pk_mul_f32 v[120:121], v[98:99], s[6:7]
	s_nop 0
	v_pk_fma_f32 v[98:99], v[98:99], s[4:5], v[120:121] op_sel:[0,0,1] op_sel_hi:[1,0,0]
	v_pk_add_f32 v[120:121], v[94:95], v[126:127]
	v_pk_add_f32 v[94:95], v[94:95], v[126:127] neg_lo:[0,1] neg_hi:[0,1]
	s_nop 0
	v_pk_mul_f32 v[126:127], v[94:95], s[10:11]
	s_nop 0
	v_pk_fma_f32 v[94:95], v[94:95], s[8:9], v[126:127] op_sel:[0,0,1] op_sel_hi:[1,0,0]
	v_pk_add_f32 v[126:127], v[124:125], v[112:113]
	v_pk_add_f32 v[112:113], v[124:125], v[112:113] neg_lo:[0,1] neg_hi:[0,1]
	s_nop 0
	v_pk_mul_f32 v[124:125], v[112:113], s[14:15]
	s_nop 0
	v_pk_fma_f32 v[112:113], v[112:113], s[12:13], v[124:125] op_sel:[0,0,1] op_sel_hi:[1,0,0]
	v_pk_add_f32 v[124:125], v[80:81], v[116:117]
	v_pk_add_f32 v[80:81], v[80:81], v[116:117] neg_lo:[0,1] neg_hi:[0,1]
	v_pk_add_f32 v[116:117], v[82:83], v[96:97]
	v_pk_add_f32 v[82:83], v[82:83], v[96:97] neg_lo:[0,1] neg_hi:[0,1]
	s_nop 0
	v_pk_mul_f32 v[96:97], v[82:83], s[14:15]
	s_nop 0
	v_pk_fma_f32 v[82:83], v[82:83], s[6:7], v[96:97] op_sel:[0,0,1] op_sel_hi:[1,0,0]
	v_pk_add_f32 v[96:97], v[108:109], v[72:73]
	v_pk_add_f32 v[72:73], v[108:109], v[72:73] neg_lo:[0,1] neg_hi:[0,1]
	s_nop 0
	v_pk_mul_f32 v[108:109], v[72:73], s[10:11]
	s_nop 0
	v_pk_fma_f32 v[72:73], v[72:73], s[10:11], v[108:109] op_sel:[0,0,1] op_sel_hi:[1,0,0]
	v_pk_add_f32 v[108:109], v[74:75], v[76:77]
	v_pk_add_f32 v[74:75], v[74:75], v[76:77] neg_lo:[0,1] neg_hi:[0,1]
	s_nop 0
	v_pk_mul_f32 v[76:77], v[74:75], s[6:7]
	s_nop 0
	v_pk_fma_f32 v[74:75], v[74:75], s[14:15], v[76:77] op_sel:[0,0,1] op_sel_hi:[1,0,0]
	v_pk_add_f32 v[76:77], v[86:87], v[66:67]
	v_pk_add_f32 v[86:87], v[86:87], v[66:67] op_sel:[1,1] op_sel_hi:[0,0] neg_lo:[1,0] neg_hi:[0,1]
	s_nop 0
	v_pk_add_f32 v[66:67], v[92:93], v[88:89]
	v_pk_add_f32 v[88:89], v[92:93], v[88:89] neg_lo:[0,1] neg_hi:[0,1]
	s_nop 0
	v_pk_mul_f32 v[92:93], v[88:89], s[6:7]
	s_nop 0
	v_pk_fma_f32 v[88:89], v[88:89], s[4:5], v[92:93] op_sel:[0,0,1] op_sel_hi:[1,0,0]
	v_pk_add_f32 v[92:93], v[100:101], v[70:71]
	v_pk_add_f32 v[70:71], v[100:101], v[70:71] neg_lo:[0,1] neg_hi:[0,1]
	s_nop 0
	v_pk_mul_f32 v[100:101], v[70:71], s[10:11]
	s_nop 0
	v_pk_fma_f32 v[70:71], v[70:71], s[8:9], v[100:101] op_sel:[0,0,1] op_sel_hi:[1,0,0]
	v_pk_add_f32 v[100:101], v[90:91], v[78:79]
	v_pk_add_f32 v[78:79], v[90:91], v[78:79] neg_lo:[0,1] neg_hi:[0,1]
	s_nop 0
	v_pk_mul_f32 v[90:91], v[78:79], s[14:15]
	s_nop 0
	v_pk_fma_f32 v[78:79], v[78:79], s[12:13], v[90:91] op_sel:[0,0,1] op_sel_hi:[1,0,0]
	v_pk_add_f32 v[90:91], v[130:131], v[122:123]
	v_pk_add_f32 v[122:123], v[130:131], v[122:123] neg_lo:[0,1] neg_hi:[0,1]
	v_pk_add_f32 v[130:131], v[132:133], v[84:85]
	v_pk_add_f32 v[84:85], v[132:133], v[84:85] neg_lo:[0,1] neg_hi:[0,1]
	s_nop 0
	v_pk_mul_f32 v[132:133], v[84:85], s[10:11]
	s_nop 0
	v_pk_fma_f32 v[84:85], v[84:85], s[10:11], v[132:133] op_sel:[0,0,1] op_sel_hi:[1,0,0]
	v_pk_add_f32 v[132:133], v[128:129], v[120:121]
	v_pk_add_f32 v[128:129], v[128:129], v[120:121] op_sel:[1,1] op_sel_hi:[0,0] neg_lo:[1,0] neg_hi:[0,1]
	s_nop 0
	v_pk_add_f32 v[120:121], v[118:119], v[126:127]
	v_pk_add_f32 v[118:119], v[118:119], v[126:127] neg_lo:[0,1] neg_hi:[0,1]
	s_nop 0
	v_pk_mul_f32 v[126:127], v[118:119], s[10:11]
	s_nop 0
	v_pk_fma_f32 v[118:119], v[118:119], s[8:9], v[126:127] op_sel:[0,0,1] op_sel_hi:[1,0,0]
	v_pk_add_f32 v[126:127], v[114:115], v[102:103]
	v_pk_add_f32 v[102:103], v[114:115], v[102:103] neg_lo:[0,1] neg_hi:[0,1]
	v_pk_add_f32 v[114:115], v[68:69], v[98:99]
	v_pk_add_f32 v[68:69], v[68:69], v[98:99] neg_lo:[0,1] neg_hi:[0,1]
	s_nop 0
	v_pk_mul_f32 v[98:99], v[68:69], s[10:11]
	s_nop 0
	v_pk_fma_f32 v[68:69], v[68:69], s[10:11], v[98:99] op_sel:[0,0,1] op_sel_hi:[1,0,0]
	v_pk_add_f32 v[98:99], v[106:107], v[94:95]
	v_pk_add_f32 v[106:107], v[106:107], v[94:95] op_sel:[1,1] op_sel_hi:[0,0] neg_lo:[1,0] neg_hi:[0,1]
	s_nop 0
	v_pk_add_f32 v[94:95], v[110:111], v[112:113]
	v_pk_add_f32 v[110:111], v[110:111], v[112:113] neg_lo:[0,1] neg_hi:[0,1]
	s_nop 0
	v_pk_mul_f32 v[112:113], v[110:111], s[10:11]
	s_nop 0
	v_pk_fma_f32 v[110:111], v[110:111], s[8:9], v[112:113] op_sel:[0,0,1] op_sel_hi:[1,0,0]
	v_pk_add_f32 v[112:113], v[124:125], v[76:77]
	v_pk_add_f32 v[76:77], v[124:125], v[76:77] neg_lo:[0,1] neg_hi:[0,1]
	v_pk_add_f32 v[124:125], v[116:117], v[66:67]
	v_pk_add_f32 v[66:67], v[116:117], v[66:67] neg_lo:[0,1] neg_hi:[0,1]
	s_nop 0
	v_pk_mul_f32 v[116:117], v[66:67], s[10:11]
	s_nop 0
	v_pk_fma_f32 v[66:67], v[66:67], s[10:11], v[116:117] op_sel:[0,0,1] op_sel_hi:[1,0,0]
	v_pk_add_f32 v[116:117], v[96:97], v[92:93]
	v_pk_add_f32 v[96:97], v[96:97], v[92:93] op_sel:[1,1] op_sel_hi:[0,0] neg_lo:[1,0] neg_hi:[0,1]
	v_pk_add_f32 v[134:135], v[112:113], v[116:117]
	v_pk_add_f32 v[92:93], v[108:109], v[100:101]
	v_pk_add_f32 v[100:101], v[108:109], v[100:101] neg_lo:[0,1] neg_hi:[0,1]
	v_pk_add_f32 v[112:113], v[112:113], v[116:117] neg_lo:[0,1] neg_hi:[0,1]
	v_pk_mul_f32 v[108:109], v[100:101], s[10:11]
	v_pk_add_f32 v[116:117], v[124:125], v[92:93]
	v_pk_fma_f32 v[100:101], v[100:101], s[8:9], v[108:109] op_sel:[0,0,1] op_sel_hi:[1,0,0]
	v_pk_add_f32 v[108:109], v[80:81], v[86:87]
	v_pk_add_f32 v[80:81], v[80:81], v[86:87] neg_lo:[0,1] neg_hi:[0,1]
	v_pk_add_f32 v[86:87], v[82:83], v[88:89]
	v_pk_add_f32 v[82:83], v[82:83], v[88:89] neg_lo:[0,1] neg_hi:[0,1]
	s_nop 0
	v_pk_mul_f32 v[88:89], v[82:83], s[10:11]
	s_nop 0
	v_pk_fma_f32 v[82:83], v[82:83], s[10:11], v[88:89] op_sel:[0,0,1] op_sel_hi:[1,0,0]
	v_pk_add_f32 v[88:89], v[72:73], v[70:71]
	v_pk_add_f32 v[72:73], v[72:73], v[70:71] op_sel:[1,1] op_sel_hi:[0,0] neg_lo:[1,0] neg_hi:[0,1]
	v_pk_add_f32 v[136:137], v[108:109], v[88:89]
	v_pk_add_f32 v[70:71], v[74:75], v[78:79]
	v_pk_add_f32 v[74:75], v[74:75], v[78:79] neg_lo:[0,1] neg_hi:[0,1]
	v_pk_add_f32 v[88:89], v[108:109], v[88:89] neg_lo:[0,1] neg_hi:[0,1]
	v_pk_mul_f32 v[78:79], v[74:75], s[10:11]
	v_pk_add_f32 v[108:109], v[86:87], v[70:71]
	v_pk_fma_f32 v[74:75], v[74:75], s[8:9], v[78:79] op_sel:[0,0,1] op_sel_hi:[1,0,0]
	v_pk_add_f32 v[78:79], v[90:91], v[132:133]
	v_pk_add_f32 v[90:91], v[90:91], v[132:133] neg_lo:[0,1] neg_hi:[0,1]
	v_pk_add_f32 v[132:133], v[130:131], v[120:121]
	v_pk_add_f32 v[130:131], v[130:131], v[120:121] op_sel:[1,1] op_sel_hi:[0,0] neg_lo:[1,0] neg_hi:[0,1]
	v_pk_add_f32 v[138:139], v[80:81], v[72:73] neg_lo:[0,1] neg_hi:[0,1]
	v_pk_add_f32 v[120:121], v[122:123], v[128:129]
	v_pk_add_f32 v[122:123], v[122:123], v[128:129] neg_lo:[0,1] neg_hi:[0,1]
	v_pk_add_f32 v[128:129], v[84:85], v[118:119]
	v_pk_add_f32 v[118:119], v[84:85], v[118:119] op_sel:[1,1] op_sel_hi:[0,0] neg_lo:[1,0] neg_hi:[0,1]
	v_pk_add_f32 v[140:141], v[82:83], v[74:75]
	v_pk_add_f32 v[84:85], v[126:127], v[98:99]
	v_pk_add_f32 v[98:99], v[126:127], v[98:99] neg_lo:[0,1] neg_hi:[0,1]
	v_pk_add_f32 v[126:127], v[114:115], v[94:95]
	v_pk_add_f32 v[114:115], v[114:115], v[94:95] op_sel:[1,1] op_sel_hi:[0,0] neg_lo:[1,0] neg_hi:[0,1]
	v_pk_add_f32 v[142:143], v[78:79], v[132:133]
	v_pk_add_f32 v[94:95], v[102:103], v[106:107]
	v_pk_add_f32 v[102:103], v[102:103], v[106:107] neg_lo:[0,1] neg_hi:[0,1]
	v_pk_add_f32 v[106:107], v[68:69], v[110:111]
	v_pk_add_f32 v[110:111], v[68:69], v[110:111] op_sel:[1,1] op_sel_hi:[0,0] neg_lo:[1,0] neg_hi:[0,1]
	v_pk_add_f32 v[132:133], v[78:79], v[132:133] neg_lo:[0,1] neg_hi:[0,1]
	v_pk_add_f32 v[92:93], v[124:125], v[92:93] op_sel:[1,1] op_sel_hi:[0,0] neg_lo:[1,0] neg_hi:[0,1]
	v_pk_add_f32 v[124:125], v[76:77], v[96:97]
	v_pk_add_f32 v[76:77], v[76:77], v[96:97] neg_lo:[0,1] neg_hi:[0,1]
	v_pk_add_f32 v[96:97], v[66:67], v[100:101]
	v_pk_add_f32 v[100:101], v[66:67], v[100:101] op_sel:[1,1] op_sel_hi:[0,0] neg_lo:[1,0] neg_hi:[0,1]
	v_pk_add_f32 v[70:71], v[86:87], v[70:71] op_sel:[1,1] op_sel_hi:[0,0] neg_lo:[1,0] neg_hi:[0,1]
	v_pk_add_f32 v[74:75], v[82:83], v[74:75] op_sel:[1,1] op_sel_hi:[0,0] neg_lo:[1,0] neg_hi:[0,1]
	v_pk_add_f32 v[86:87], v[80:81], v[72:73]
	v_pk_add_f32 v[144:145], v[90:91], v[130:131]
	v_pk_add_f32 v[82:83], v[90:91], v[130:131] neg_lo:[0,1] neg_hi:[0,1]
	v_pk_add_f32 v[90:91], v[120:121], v[128:129]
	v_pk_add_f32 v[120:121], v[120:121], v[128:129] neg_lo:[0,1] neg_hi:[0,1]
	v_pk_add_f32 v[128:129], v[122:123], v[118:119]
	v_pk_add_f32 v[68:69], v[122:123], v[118:119] neg_lo:[0,1] neg_hi:[0,1]
	v_pk_add_f32 v[118:119], v[84:85], v[126:127]
	v_pk_add_f32 v[122:123], v[84:85], v[126:127] neg_lo:[0,1] neg_hi:[0,1]
	v_pk_add_f32 v[126:127], v[98:99], v[114:115]
	v_pk_add_f32 v[78:79], v[98:99], v[114:115] neg_lo:[0,1] neg_hi:[0,1]
	v_pk_add_f32 v[98:99], v[94:95], v[106:107]
	v_pk_add_f32 v[94:95], v[94:95], v[106:107] neg_lo:[0,1] neg_hi:[0,1]
	v_pk_add_f32 v[106:107], v[102:103], v[110:111]
	v_pk_add_f32 v[66:67], v[102:103], v[110:111] neg_lo:[0,1] neg_hi:[0,1]
	v_pk_add_f32 v[102:103], v[134:135], v[116:117]
	v_pk_add_f32 v[110:111], v[134:135], v[116:117] neg_lo:[0,1] neg_hi:[0,1]
	v_pk_add_f32 v[116:117], v[88:89], v[70:71]
	v_pk_add_f32 v[80:81], v[88:89], v[70:71] neg_lo:[0,1] neg_hi:[0,1]
	v_lshlrev_b32_e32 v70, 4, v0
	v_and_b32_e32 v70, 0x1f0, v70
	v_pk_add_f32 v[114:115], v[112:113], v[92:93]
	v_pk_add_f32 v[84:85], v[112:113], v[92:93] neg_lo:[0,1] neg_hi:[0,1]
	v_pk_add_f32 v[112:113], v[76:77], v[100:101]
	v_pk_add_f32 v[72:73], v[76:77], v[100:101] neg_lo:[0,1] neg_hi:[0,1]
	v_cvt_f32_u32_e32 v76, v70
	v_pk_add_f32 v[92:93], v[124:125], v[96:97]
	v_pk_add_f32 v[96:97], v[124:125], v[96:97] neg_lo:[0,1] neg_hi:[0,1]
	v_pk_add_f32 v[124:125], v[138:139], v[74:75]
	v_mul_f32_e32 v76, 0x38800000, v76
	v_pk_add_f32 v[70:71], v[138:139], v[74:75] neg_lo:[0,1] neg_hi:[0,1]
	v_sin_f32_e32 v75, v76
	v_ashrrev_i32_e32 v74, 2, v105
	v_lshlrev_b32_e32 v0, 8, v0
	v_add3_u32 v0, 0, v74, v0
	v_cos_f32_e32 v74, v76
	v_xor_b32_e32 v76, 0x80000000, v75
	v_mov_b32_e32 v77, v75
	v_pk_mul_f32 v[130:131], v[76:77], v[102:103] op_sel:[0,1] op_sel_hi:[1,0]
	v_pk_add_f32 v[100:101], v[136:137], v[108:109]
	v_pk_fma_f32 v[102:103], v[102:103], v[74:75], v[130:131] op_sel_hi:[1,0,1]
	ds_write2_b64 v0, v[142:143], v[102:103] offset1:1
	v_pk_mul_f32 v[102:103], v[76:77], v[74:75] op_sel:[0,1] op_sel_hi:[1,0]
	v_pk_add_f32 v[88:89], v[86:87], v[140:141]
	v_pk_fma_f32 v[102:103], v[74:75], v[74:75], v[102:103] op_sel_hi:[1,0,1]
	v_pk_add_f32 v[108:109], v[136:137], v[108:109] neg_lo:[0,1] neg_hi:[0,1]
	v_pk_mul_f32 v[130:131], v[118:119], v[102:103] op_sel:[1,1] op_sel_hi:[0,1] neg_lo:[0,1]
	v_pk_fma_f32 v[118:119], v[118:119], v[102:103], v[130:131] op_sel_hi:[1,0,1]
	v_pk_mul_f32 v[130:131], v[76:77], v[102:103] op_sel:[0,1] op_sel_hi:[1,0]
	v_pk_add_f32 v[86:87], v[86:87], v[140:141] neg_lo:[0,1] neg_hi:[0,1]
	v_pk_fma_f32 v[102:103], v[102:103], v[74:75], v[130:131] op_sel_hi:[1,0,1]
	s_nop 0
	v_pk_mul_f32 v[130:131], v[100:101], v[102:103] op_sel:[1,1] op_sel_hi:[0,1] neg_lo:[0,1]
	v_pk_fma_f32 v[100:101], v[100:101], v[102:103], v[130:131] op_sel_hi:[1,0,1]
	ds_write2_b64 v0, v[118:119], v[100:101] offset0:2 offset1:3
	v_pk_mul_f32 v[100:101], v[76:77], v[102:103] op_sel:[0,1] op_sel_hi:[1,0]
	s_nop 0
	v_pk_fma_f32 v[100:101], v[102:103], v[74:75], v[100:101] op_sel_hi:[1,0,1]
	s_nop 0
	v_pk_mul_f32 v[102:103], v[90:91], v[100:101] op_sel:[1,1] op_sel_hi:[0,1] neg_lo:[0,1]
	v_pk_fma_f32 v[90:91], v[90:91], v[100:101], v[102:103] op_sel_hi:[1,0,1]
	v_pk_mul_f32 v[102:103], v[76:77], v[100:101] op_sel:[0,1] op_sel_hi:[1,0]
	s_nop 0
	v_pk_fma_f32 v[100:101], v[100:101], v[74:75], v[102:103] op_sel_hi:[1,0,1]
	s_nop 0
	v_pk_mul_f32 v[102:103], v[92:93], v[100:101] op_sel:[1,1] op_sel_hi:[0,1] neg_lo:[0,1]
	v_pk_fma_f32 v[92:93], v[92:93], v[100:101], v[102:103] op_sel_hi:[1,0,1]
	ds_write2_b64 v0, v[90:91], v[92:93] offset0:4 offset1:5
	v_pk_mul_f32 v[90:91], v[76:77], v[100:101] op_sel:[0,1] op_sel_hi:[1,0]
	s_nop 0
	v_pk_fma_f32 v[90:91], v[100:101], v[74:75], v[90:91] op_sel_hi:[1,0,1]
	s_nop 0
	v_pk_mul_f32 v[92:93], v[98:99], v[90:91] op_sel:[1,1] op_sel_hi:[0,1] neg_lo:[0,1]
	v_pk_fma_f32 v[92:93], v[98:99], v[90:91], v[92:93] op_sel_hi:[1,0,1]
	v_pk_mul_f32 v[98:99], v[76:77], v[90:91] op_sel:[0,1] op_sel_hi:[1,0]
	s_nop 0
	v_pk_fma_f32 v[90:91], v[90:91], v[74:75], v[98:99] op_sel_hi:[1,0,1]
	s_nop 0
	v_pk_mul_f32 v[98:99], v[88:89], v[90:91] op_sel:[1,1] op_sel_hi:[0,1] neg_lo:[0,1]
	v_pk_fma_f32 v[88:89], v[88:89], v[90:91], v[98:99] op_sel_hi:[1,0,1]
	ds_write2_b64 v0, v[92:93], v[88:89] offset0:6 offset1:7
	v_pk_mul_f32 v[88:89], v[76:77], v[90:91] op_sel:[0,1] op_sel_hi:[1,0]
	s_nop 0
	v_pk_fma_f32 v[88:89], v[90:91], v[74:75], v[88:89] op_sel_hi:[1,0,1]
	s_nop 0
	v_pk_mul_f32 v[90:91], v[144:145], v[88:89] op_sel:[1,1] op_sel_hi:[0,1] neg_lo:[0,1]
	v_pk_mul_f32 v[92:93], v[76:77], v[88:89] op_sel:[0,1] op_sel_hi:[1,0]
	v_pk_fma_f32 v[90:91], v[144:145], v[88:89], v[90:91] op_sel_hi:[1,0,1]
	v_pk_fma_f32 v[88:89], v[88:89], v[74:75], v[92:93] op_sel_hi:[1,0,1]
	s_nop 0
	v_pk_mul_f32 v[92:93], v[114:115], v[88:89] op_sel:[1,1] op_sel_hi:[0,1] neg_lo:[0,1]
	v_pk_fma_f32 v[92:93], v[114:115], v[88:89], v[92:93] op_sel_hi:[1,0,1]
	ds_write2_b64 v0, v[90:91], v[92:93] offset0:8 offset1:9
	v_pk_mul_f32 v[90:91], v[76:77], v[88:89] op_sel:[0,1] op_sel_hi:[1,0]
	s_nop 0
	v_pk_fma_f32 v[88:89], v[88:89], v[74:75], v[90:91] op_sel_hi:[1,0,1]
	s_nop 0
	v_pk_mul_f32 v[90:91], v[126:127], v[88:89] op_sel:[1,1] op_sel_hi:[0,1] neg_lo:[0,1]
	v_pk_mul_f32 v[92:93], v[76:77], v[88:89] op_sel:[0,1] op_sel_hi:[1,0]
	v_pk_fma_f32 v[90:91], v[126:127], v[88:89], v[90:91] op_sel_hi:[1,0,1]
	v_pk_fma_f32 v[88:89], v[88:89], v[74:75], v[92:93] op_sel_hi:[1,0,1]
	s_nop 0
	v_pk_mul_f32 v[92:93], v[116:117], v[88:89] op_sel:[1,1] op_sel_hi:[0,1] neg_lo:[0,1]
	v_pk_fma_f32 v[92:93], v[116:117], v[88:89], v[92:93] op_sel_hi:[1,0,1]
	ds_write2_b64 v0, v[90:91], v[92:93] offset0:10 offset1:11
	v_pk_mul_f32 v[90:91], v[76:77], v[88:89] op_sel:[0,1] op_sel_hi:[1,0]
	s_nop 0
	v_pk_fma_f32 v[88:89], v[88:89], v[74:75], v[90:91] op_sel_hi:[1,0,1]
	s_nop 0
	v_pk_mul_f32 v[90:91], v[128:129], v[88:89] op_sel:[1,1] op_sel_hi:[0,1] neg_lo:[0,1]
	v_pk_mul_f32 v[92:93], v[76:77], v[88:89] op_sel:[0,1] op_sel_hi:[1,0]
	v_pk_fma_f32 v[90:91], v[128:129], v[88:89], v[90:91] op_sel_hi:[1,0,1]
	v_pk_fma_f32 v[88:89], v[88:89], v[74:75], v[92:93] op_sel_hi:[1,0,1]
	s_nop 0
	v_pk_mul_f32 v[92:93], v[112:113], v[88:89] op_sel:[1,1] op_sel_hi:[0,1] neg_lo:[0,1]
	v_pk_fma_f32 v[92:93], v[112:113], v[88:89], v[92:93] op_sel_hi:[1,0,1]
	ds_write2_b64 v0, v[90:91], v[92:93] offset0:12 offset1:13
	v_pk_mul_f32 v[90:91], v[76:77], v[88:89] op_sel:[0,1] op_sel_hi:[1,0]
	s_nop 0
	v_pk_fma_f32 v[88:89], v[88:89], v[74:75], v[90:91] op_sel_hi:[1,0,1]
	s_nop 0
	v_pk_mul_f32 v[90:91], v[106:107], v[88:89] op_sel:[1,1] op_sel_hi:[0,1] neg_lo:[0,1]
	v_pk_mul_f32 v[92:93], v[76:77], v[88:89] op_sel:[0,1] op_sel_hi:[1,0]
	v_pk_fma_f32 v[90:91], v[106:107], v[88:89], v[90:91] op_sel_hi:[1,0,1]
	v_pk_fma_f32 v[88:89], v[88:89], v[74:75], v[92:93] op_sel_hi:[1,0,1]
	s_nop 0
	v_pk_mul_f32 v[92:93], v[124:125], v[88:89] op_sel:[1,1] op_sel_hi:[0,1] neg_lo:[0,1]
	v_pk_fma_f32 v[92:93], v[124:125], v[88:89], v[92:93] op_sel_hi:[1,0,1]
	ds_write2_b64 v0, v[90:91], v[92:93] offset0:14 offset1:15
	v_pk_mul_f32 v[90:91], v[76:77], v[88:89] op_sel:[0,1] op_sel_hi:[1,0]
	s_nop 0
	v_pk_fma_f32 v[88:89], v[88:89], v[74:75], v[90:91] op_sel_hi:[1,0,1]
	s_nop 0
	v_pk_mul_f32 v[90:91], v[132:133], v[88:89] op_sel:[1,1] op_sel_hi:[0,1] neg_lo:[0,1]
	v_pk_mul_f32 v[92:93], v[76:77], v[88:89] op_sel:[0,1] op_sel_hi:[1,0]
	v_pk_fma_f32 v[90:91], v[132:133], v[88:89], v[90:91] op_sel_hi:[1,0,1]
	v_pk_fma_f32 v[88:89], v[88:89], v[74:75], v[92:93] op_sel_hi:[1,0,1]
	s_nop 0
	v_pk_mul_f32 v[92:93], v[110:111], v[88:89] op_sel:[1,1] op_sel_hi:[0,1] neg_lo:[0,1]
	v_pk_fma_f32 v[92:93], v[110:111], v[88:89], v[92:93] op_sel_hi:[1,0,1]
	ds_write2_b64 v0, v[90:91], v[92:93] offset0:16 offset1:17
	v_pk_mul_f32 v[90:91], v[76:77], v[88:89] op_sel:[0,1] op_sel_hi:[1,0]
	s_nop 0
	v_pk_fma_f32 v[88:89], v[88:89], v[74:75], v[90:91] op_sel_hi:[1,0,1]
	s_nop 0
	v_pk_mul_f32 v[90:91], v[122:123], v[88:89] op_sel:[1,1] op_sel_hi:[0,1] neg_lo:[0,1]
	v_pk_mul_f32 v[92:93], v[76:77], v[88:89] op_sel:[0,1] op_sel_hi:[1,0]
	v_pk_fma_f32 v[90:91], v[122:123], v[88:89], v[90:91] op_sel_hi:[1,0,1]
	v_pk_fma_f32 v[88:89], v[88:89], v[74:75], v[92:93] op_sel_hi:[1,0,1]
	s_nop 0
	v_pk_mul_f32 v[92:93], v[108:109], v[88:89] op_sel:[1,1] op_sel_hi:[0,1] neg_lo:[0,1]
	v_pk_fma_f32 v[92:93], v[108:109], v[88:89], v[92:93] op_sel_hi:[1,0,1]
	ds_write2_b64 v0, v[90:91], v[92:93] offset0:18 offset1:19
	v_pk_mul_f32 v[90:91], v[76:77], v[88:89] op_sel:[0,1] op_sel_hi:[1,0]
	s_nop 0
	v_pk_fma_f32 v[88:89], v[88:89], v[74:75], v[90:91] op_sel_hi:[1,0,1]
	s_nop 0
	v_pk_mul_f32 v[90:91], v[120:121], v[88:89] op_sel:[1,1] op_sel_hi:[0,1] neg_lo:[0,1]
	v_pk_mul_f32 v[92:93], v[76:77], v[88:89] op_sel:[0,1] op_sel_hi:[1,0]
	v_pk_fma_f32 v[90:91], v[120:121], v[88:89], v[90:91] op_sel_hi:[1,0,1]
	v_pk_fma_f32 v[88:89], v[88:89], v[74:75], v[92:93] op_sel_hi:[1,0,1]
	s_nop 0
	v_pk_mul_f32 v[92:93], v[96:97], v[88:89] op_sel:[1,1] op_sel_hi:[0,1] neg_lo:[0,1]
	v_pk_fma_f32 v[92:93], v[96:97], v[88:89], v[92:93] op_sel_hi:[1,0,1]
	ds_write2_b64 v0, v[90:91], v[92:93] offset0:20 offset1:21
	v_pk_mul_f32 v[90:91], v[76:77], v[88:89] op_sel:[0,1] op_sel_hi:[1,0]
	s_nop 0
	v_pk_fma_f32 v[88:89], v[88:89], v[74:75], v[90:91] op_sel_hi:[1,0,1]
	s_nop 0
	v_pk_mul_f32 v[90:91], v[94:95], v[88:89] op_sel:[1,1] op_sel_hi:[0,1] neg_lo:[0,1]
	v_pk_mul_f32 v[92:93], v[76:77], v[88:89] op_sel:[0,1] op_sel_hi:[1,0]
	v_pk_fma_f32 v[90:91], v[94:95], v[88:89], v[90:91] op_sel_hi:[1,0,1]
	v_pk_fma_f32 v[88:89], v[88:89], v[74:75], v[92:93] op_sel_hi:[1,0,1]
	s_nop 0
	v_pk_mul_f32 v[92:93], v[86:87], v[88:89] op_sel:[1,1] op_sel_hi:[0,1] neg_lo:[0,1]
	v_pk_fma_f32 v[86:87], v[86:87], v[88:89], v[92:93] op_sel_hi:[1,0,1]
	ds_write2_b64 v0, v[90:91], v[86:87] offset0:22 offset1:23
	v_pk_mul_f32 v[86:87], v[76:77], v[88:89] op_sel:[0,1] op_sel_hi:[1,0]
	s_nop 0
	v_pk_fma_f32 v[86:87], v[88:89], v[74:75], v[86:87] op_sel_hi:[1,0,1]
	s_nop 0
	v_pk_mul_f32 v[88:89], v[82:83], v[86:87] op_sel:[1,1] op_sel_hi:[0,1] neg_lo:[0,1]
	v_pk_fma_f32 v[82:83], v[82:83], v[86:87], v[88:89] op_sel_hi:[1,0,1]
	v_pk_mul_f32 v[88:89], v[76:77], v[86:87] op_sel:[0,1] op_sel_hi:[1,0]
	s_nop 0
	v_pk_fma_f32 v[86:87], v[86:87], v[74:75], v[88:89] op_sel_hi:[1,0,1]
	s_nop 0
	v_pk_mul_f32 v[88:89], v[84:85], v[86:87] op_sel:[1,1] op_sel_hi:[0,1] neg_lo:[0,1]
	v_pk_fma_f32 v[84:85], v[84:85], v[86:87], v[88:89] op_sel_hi:[1,0,1]
	ds_write2_b64 v0, v[82:83], v[84:85] offset0:24 offset1:25
	v_pk_mul_f32 v[82:83], v[76:77], v[86:87] op_sel:[0,1] op_sel_hi:[1,0]
	s_nop 0
	v_pk_fma_f32 v[82:83], v[86:87], v[74:75], v[82:83] op_sel_hi:[1,0,1]
	s_nop 0
	v_pk_mul_f32 v[84:85], v[78:79], v[82:83] op_sel:[1,1] op_sel_hi:[0,1] neg_lo:[0,1]
	v_pk_fma_f32 v[78:79], v[78:79], v[82:83], v[84:85] op_sel_hi:[1,0,1]
	v_pk_mul_f32 v[84:85], v[76:77], v[82:83] op_sel:[0,1] op_sel_hi:[1,0]
	s_nop 0
	v_pk_fma_f32 v[82:83], v[82:83], v[74:75], v[84:85] op_sel_hi:[1,0,1]
	s_nop 0
	v_pk_mul_f32 v[84:85], v[80:81], v[82:83] op_sel:[1,1] op_sel_hi:[0,1] neg_lo:[0,1]
	v_pk_fma_f32 v[80:81], v[80:81], v[82:83], v[84:85] op_sel_hi:[1,0,1]
	ds_write2_b64 v0, v[78:79], v[80:81] offset0:26 offset1:27
	v_pk_mul_f32 v[78:79], v[76:77], v[82:83] op_sel:[0,1] op_sel_hi:[1,0]
	s_nop 0
	v_pk_fma_f32 v[78:79], v[82:83], v[74:75], v[78:79] op_sel_hi:[1,0,1]
	s_nop 0
	v_pk_mul_f32 v[80:81], v[68:69], v[78:79] op_sel:[1,1] op_sel_hi:[0,1] neg_lo:[0,1]
	v_pk_fma_f32 v[68:69], v[68:69], v[78:79], v[80:81] op_sel_hi:[1,0,1]
	v_pk_mul_f32 v[80:81], v[76:77], v[78:79] op_sel:[0,1] op_sel_hi:[1,0]
	s_nop 0
	v_pk_fma_f32 v[78:79], v[78:79], v[74:75], v[80:81] op_sel_hi:[1,0,1]
	s_nop 0
	v_pk_mul_f32 v[80:81], v[72:73], v[78:79] op_sel:[1,1] op_sel_hi:[0,1] neg_lo:[0,1]
	v_pk_fma_f32 v[72:73], v[72:73], v[78:79], v[80:81] op_sel_hi:[1,0,1]
	ds_write2_b64 v0, v[68:69], v[72:73] offset0:28 offset1:29
	v_pk_mul_f32 v[68:69], v[76:77], v[78:79] op_sel:[0,1] op_sel_hi:[1,0]
	s_nop 0
	v_pk_fma_f32 v[68:69], v[78:79], v[74:75], v[68:69] op_sel_hi:[1,0,1]
	s_nop 0
	v_pk_mul_f32 v[72:73], v[66:67], v[68:69] op_sel:[1,1] op_sel_hi:[0,1] neg_lo:[0,1]
	v_pk_fma_f32 v[66:67], v[66:67], v[68:69], v[72:73] op_sel_hi:[1,0,1]
	v_pk_mul_f32 v[72:73], v[76:77], v[68:69] op_sel:[0,1] op_sel_hi:[1,0]
	s_nop 0
	v_pk_fma_f32 v[68:69], v[68:69], v[74:75], v[72:73] op_sel_hi:[1,0,1]
	s_nop 0
	v_pk_mul_f32 v[72:73], v[70:71], v[68:69] op_sel:[1,1] op_sel_hi:[0,1] neg_lo:[0,1]
	v_pk_fma_f32 v[68:69], v[70:71], v[68:69], v[72:73] op_sel_hi:[1,0,1]
	ds_write2_b64 v0, v[66:67], v[68:69] offset0:30 offset1:31
	s_waitcnt lgkmcnt(0)
	s_barrier
	v_mov_b32 v0, 0
	s_nop 0
	v_add_u32_e32 v71, v0, v170
	v_ashrrev_i32_e32 v105, 5, v71
	v_lshlrev_b32_e32 v0, 10, v105
	v_and_b32_e32 v140, 31, v71
	v_ashrrev_i32_e32 v0, 2, v0
	v_lshlrev_b32_e32 v67, 13, v105
	v_lshlrev_b32_e32 v68, 3, v140
	v_add_u32_e32 v0, 0, v0
	v_lshl_add_u32 v66, v105, 8, 0
	v_add3_u32 v0, v0, v67, v68
	v_add3_u32 v142, v66, v67, v68
	v_add_u32_e32 v143, 0x400, v0
	v_add_u32_e32 v144, 0x800, v0
	v_add_u32_e32 v145, 0xc00, v0
	ds_read_b64 v[130:131], v142
	ds_read2_b64 v[66:69], v0 offset0:33 offset1:66
	ds_read2_b64 v[72:75], v0 offset0:99 offset1:132
	ds_read2_b64 v[76:79], v0 offset0:165 offset1:198
	ds_read2_b64 v[80:83], v143 offset0:103 offset1:136
	ds_read2_b64 v[84:87], v144 offset0:41 offset1:74
	ds_read2_b64 v[88:91], v144 offset0:107 offset1:140
	ds_read2_b64 v[92:95], v144 offset0:173 offset1:206
	ds_read2_b64 v[96:99], v145 offset0:111 offset1:144
	v_add_u32_e32 v146, 0x1000, v0
	ds_read2_b64 v[100:103], v146 offset0:49 offset1:82
	ds_read2_b64 v[106:109], v146 offset0:115 offset1:148
	ds_read2_b64 v[110:113], v146 offset0:181 offset1:214
	v_add_u32_e32 v147, 0x1400, v0
	ds_read2_b64 v[114:117], v147 offset0:119 offset1:152
	s_waitcnt lgkmcnt(4)
	v_pk_add_f32 v[134:135], v[130:131], v[98:99]
	v_pk_add_f32 v[98:99], v[130:131], v[98:99] neg_lo:[0,1] neg_hi:[0,1]
	s_waitcnt lgkmcnt(3)
	v_pk_add_f32 v[130:131], v[66:67], v[100:101]
	v_pk_add_f32 v[66:67], v[66:67], v[100:101] neg_lo:[0,1] neg_hi:[0,1]
	v_add_u32_e32 v70, 0x1800, v0
	v_pk_mul_f32 v[100:101], v[66:67], s[50:51]
	ds_read2_b64 v[118:121], v70 offset0:57 offset1:90
	ds_read2_b64 v[122:125], v70 offset0:123 offset1:156
	ds_read2_b64 v[126:129], v70 offset0:189 offset1:222
	ds_read_b64 v[132:133], v0 offset:8184
	v_pk_fma_f32 v[66:67], v[66:67], s[20:21], v[100:101] op_sel:[0,0,1] op_sel_hi:[1,0,0]
	v_pk_add_f32 v[100:101], v[68:69], v[102:103]
	v_pk_add_f32 v[68:69], v[68:69], v[102:103] neg_lo:[0,1] neg_hi:[0,1]
	v_mul_lo_u32 v105, v140, v105
	v_pk_mul_f32 v[102:103], v[68:69], s[14:15]
	v_cvt_f32_i32_e32 v105, v105
	v_pk_fma_f32 v[68:69], v[68:69], s[6:7], v[102:103] op_sel:[0,0,1] op_sel_hi:[1,0,0]
	s_waitcnt lgkmcnt(6)
	v_pk_add_f32 v[102:103], v[72:73], v[106:107]
	v_pk_add_f32 v[72:73], v[72:73], v[106:107] neg_lo:[0,1] neg_hi:[0,1]
	v_and_b32_e32 v71, 0xffffffe0, v71
	v_pk_mul_f32 v[106:107], v[72:73], s[52:53]
	v_cvt_f32_i32_e32 v71, v71
	v_pk_fma_f32 v[72:73], v[72:73], s[24:25], v[106:107] op_sel:[0,0,1] op_sel_hi:[1,0,0]
	v_pk_add_f32 v[106:107], v[74:75], v[108:109]
	v_pk_add_f32 v[74:75], v[74:75], v[108:109] neg_lo:[0,1] neg_hi:[0,1]
	v_mul_f32_e32 v71, 0x38800000, v71
	v_pk_mul_f32 v[108:109], v[74:75], s[10:11]
	s_nop 0
	v_pk_fma_f32 v[74:75], v[74:75], s[10:11], v[108:109] op_sel:[0,0,1] op_sel_hi:[1,0,0]
	s_waitcnt lgkmcnt(5)
	v_pk_add_f32 v[108:109], v[76:77], v[110:111]
	v_pk_add_f32 v[76:77], v[76:77], v[110:111] neg_lo:[0,1] neg_hi:[0,1]
	s_nop 0
	v_pk_mul_f32 v[110:111], v[76:77], s[24:25]
	s_nop 0
	v_pk_fma_f32 v[76:77], v[76:77], s[0:1], v[110:111] op_sel:[0,0,1] op_sel_hi:[1,0,0]
	v_pk_add_f32 v[110:111], v[78:79], v[112:113]
	v_pk_add_f32 v[78:79], v[78:79], v[112:113] neg_lo:[0,1] neg_hi:[0,1]
	s_nop 0
	v_pk_mul_f32 v[112:113], v[78:79], s[6:7]
	s_nop 0
	v_pk_fma_f32 v[78:79], v[78:79], s[14:15], v[112:113] op_sel:[0,0,1] op_sel_hi:[1,0,0]
	s_waitcnt lgkmcnt(4)
	v_pk_add_f32 v[112:113], v[80:81], v[114:115]
	v_pk_add_f32 v[80:81], v[80:81], v[114:115] neg_lo:[0,1] neg_hi:[0,1]
	s_nop 0
	v_pk_mul_f32 v[114:115], v[80:81], s[20:21]
	s_nop 0
	v_pk_fma_f32 v[80:81], v[80:81], s[48:49], v[114:115] op_sel:[0,0,1] op_sel_hi:[1,0,0]
	v_pk_add_f32 v[114:115], v[82:83], v[116:117]
	v_pk_add_f32 v[116:117], v[82:83], v[116:117] op_sel:[1,1] op_sel_hi:[0,0] neg_lo:[1,0] neg_hi:[0,1]
	s_mov_b64 s[48:49], -1
	s_waitcnt lgkmcnt(3)
	v_pk_add_f32 v[82:83], v[84:85], v[118:119]
	v_pk_add_f32 v[84:85], v[84:85], v[118:119] neg_lo:[0,1] neg_hi:[0,1]
	s_nop 0
	v_pk_mul_f32 v[118:119], v[84:85], s[20:21]
	s_nop 0
	v_pk_fma_f32 v[84:85], v[84:85], s[18:19], v[118:119] op_sel:[0,0,1] op_sel_hi:[1,0,0]
	v_pk_add_f32 v[118:119], v[86:87], v[120:121]
	v_pk_add_f32 v[86:87], v[86:87], v[120:121] neg_lo:[0,1] neg_hi:[0,1]
	s_nop 0
	v_pk_mul_f32 v[120:121], v[86:87], s[6:7]
	s_nop 0
	v_pk_fma_f32 v[86:87], v[86:87], s[4:5], v[120:121] op_sel:[0,0,1] op_sel_hi:[1,0,0]
	s_waitcnt lgkmcnt(2)
	v_pk_add_f32 v[120:121], v[88:89], v[122:123]
	v_pk_add_f32 v[88:89], v[88:89], v[122:123] neg_lo:[0,1] neg_hi:[0,1]
	s_nop 0
	v_pk_mul_f32 v[122:123], v[88:89], s[24:25]
	s_nop 0
	v_pk_fma_f32 v[88:89], v[88:89], s[22:23], v[122:123] op_sel:[0,0,1] op_sel_hi:[1,0,0]
	v_pk_add_f32 v[122:123], v[90:91], v[124:125]
	v_pk_add_f32 v[90:91], v[90:91], v[124:125] neg_lo:[0,1] neg_hi:[0,1]
	s_nop 0
	v_pk_mul_f32 v[124:125], v[90:91], s[10:11]
	s_nop 0
	v_pk_fma_f32 v[90:91], v[90:91], s[8:9], v[124:125] op_sel:[0,0,1] op_sel_hi:[1,0,0]
	s_waitcnt lgkmcnt(1)
	v_pk_add_f32 v[124:125], v[92:93], v[126:127]
	v_pk_add_f32 v[92:93], v[92:93], v[126:127] neg_lo:[0,1] neg_hi:[0,1]
	s_nop 0
	v_pk_mul_f32 v[126:127], v[92:93], s[52:53]
	s_nop 0
	v_pk_fma_f32 v[92:93], v[92:93], s[26:27], v[126:127] op_sel:[0,0,1] op_sel_hi:[1,0,0]
	v_pk_add_f32 v[126:127], v[94:95], v[128:129]
	v_pk_add_f32 v[94:95], v[94:95], v[128:129] neg_lo:[0,1] neg_hi:[0,1]
	s_nop 0
	v_pk_mul_f32 v[128:129], v[94:95], s[14:15]
	s_nop 0
	v_pk_fma_f32 v[94:95], v[94:95], s[12:13], v[128:129] op_sel:[0,0,1] op_sel_hi:[1,0,0]
	s_waitcnt lgkmcnt(0)
	v_pk_add_f32 v[128:129], v[96:97], v[132:133]
	v_pk_add_f32 v[96:97], v[96:97], v[132:133] neg_lo:[0,1] neg_hi:[0,1]
	s_nop 0
	v_pk_mul_f32 v[132:133], v[96:97], s[50:51]
	s_nop 0
	v_pk_fma_f32 v[96:97], v[96:97], s[34:35], v[132:133] op_sel:[0,0,1] op_sel_hi:[1,0,0]
	v_pk_add_f32 v[132:133], v[134:135], v[114:115]
	v_pk_add_f32 v[114:115], v[134:135], v[114:115] neg_lo:[0,1] neg_hi:[0,1]
	v_pk_add_f32 v[134:135], v[130:131], v[82:83]
	v_pk_add_f32 v[82:83], v[130:131], v[82:83] neg_lo:[0,1] neg_hi:[0,1]
	s_nop 0
	v_pk_mul_f32 v[130:131], v[82:83], s[14:15]
	s_nop 0
	v_pk_fma_f32 v[82:83], v[82:83], s[6:7], v[130:131] op_sel:[0,0,1] op_sel_hi:[1,0,0]
	v_pk_add_f32 v[130:131], v[100:101], v[118:119]
	v_pk_add_f32 v[100:101], v[100:101], v[118:119] neg_lo:[0,1] neg_hi:[0,1]
	s_nop 0
	v_pk_mul_f32 v[118:119], v[100:101], s[10:11]
	s_nop 0
	v_pk_fma_f32 v[100:101], v[100:101], s[10:11], v[118:119] op_sel:[0,0,1] op_sel_hi:[1,0,0]
	v_pk_add_f32 v[118:119], v[102:103], v[120:121]
	v_pk_add_f32 v[102:103], v[102:103], v[120:121] neg_lo:[0,1] neg_hi:[0,1]
	s_nop 0
	v_pk_mul_f32 v[120:121], v[102:103], s[6:7]
	s_nop 0
	v_pk_fma_f32 v[102:103], v[102:103], s[14:15], v[120:121] op_sel:[0,0,1] op_sel_hi:[1,0,0]
	v_pk_add_f32 v[120:121], v[106:107], v[122:123]
	v_pk_add_f32 v[122:123], v[106:107], v[122:123] op_sel:[1,1] op_sel_hi:[0,0] neg_lo:[1,0] neg_hi:[0,1]
	s_nop 0
	v_pk_add_f32 v[106:107], v[108:109], v[124:125]
	v_pk_add_f32 v[108:109], v[108:109], v[124:125] neg_lo:[0,1] neg_hi:[0,1]
	s_nop 0
	v_pk_mul_f32 v[124:125], v[108:109], s[6:7]
	s_nop 0
	v_pk_fma_f32 v[108:109], v[108:109], s[4:5], v[124:125] op_sel:[0,0,1] op_sel_hi:[1,0,0]
	v_pk_add_f32 v[124:125], v[110:111], v[126:127]
	v_pk_add_f32 v[110:111], v[110:111], v[126:127] neg_lo:[0,1] neg_hi:[0,1]
	s_nop 0
	v_pk_mul_f32 v[126:127], v[110:111], s[10:11]
	s_nop 0
	v_pk_fma_f32 v[110:111], v[110:111], s[8:9], v[126:127] op_sel:[0,0,1] op_sel_hi:[1,0,0]
	v_pk_add_f32 v[126:127], v[112:113], v[128:129]
	v_pk_add_f32 v[112:113], v[112:113], v[128:129] neg_lo:[0,1] neg_hi:[0,1]
	s_nop 0
	v_pk_mul_f32 v[128:129], v[112:113], s[14:15]
	s_nop 0
	v_pk_fma_f32 v[112:113], v[112:113], s[12:13], v[128:129] op_sel:[0,0,1] op_sel_hi:[1,0,0]
	v_pk_add_f32 v[128:129], v[98:99], v[116:117]
	v_pk_add_f32 v[98:99], v[98:99], v[116:117] neg_lo:[0,1] neg_hi:[0,1]
	v_pk_add_f32 v[116:117], v[66:67], v[84:85]
	v_pk_add_f32 v[66:67], v[66:67], v[84:85] neg_lo:[0,1] neg_hi:[0,1]
	s_nop 0
	v_pk_mul_f32 v[84:85], v[66:67], s[14:15]
	s_nop 0
	v_pk_fma_f32 v[66:67], v[66:67], s[6:7], v[84:85] op_sel:[0,0,1] op_sel_hi:[1,0,0]
	v_pk_add_f32 v[84:85], v[68:69], v[86:87]
	v_pk_add_f32 v[68:69], v[68:69], v[86:87] neg_lo:[0,1] neg_hi:[0,1]
	s_nop 0
	v_pk_mul_f32 v[86:87], v[68:69], s[10:11]
	s_nop 0
	v_pk_fma_f32 v[68:69], v[68:69], s[10:11], v[86:87] op_sel:[0,0,1] op_sel_hi:[1,0,0]
	v_pk_add_f32 v[86:87], v[72:73], v[88:89]
	v_pk_add_f32 v[72:73], v[72:73], v[88:89] neg_lo:[0,1] neg_hi:[0,1]
	s_nop 0
	v_pk_mul_f32 v[88:89], v[72:73], s[6:7]
	s_nop 0
	v_pk_fma_f32 v[72:73], v[72:73], s[14:15], v[88:89] op_sel:[0,0,1] op_sel_hi:[1,0,0]
	v_pk_add_f32 v[88:89], v[74:75], v[90:91]
	v_pk_add_f32 v[90:91], v[74:75], v[90:91] op_sel:[1,1] op_sel_hi:[0,0] neg_lo:[1,0] neg_hi:[0,1]
	s_nop 0
	v_pk_add_f32 v[74:75], v[76:77], v[92:93]
	v_pk_add_f32 v[76:77], v[76:77], v[92:93] neg_lo:[0,1] neg_hi:[0,1]
	s_nop 0
	v_pk_mul_f32 v[92:93], v[76:77], s[6:7]
	s_nop 0
	v_pk_fma_f32 v[76:77], v[76:77], s[4:5], v[92:93] op_sel:[0,0,1] op_sel_hi:[1,0,0]
	v_pk_add_f32 v[92:93], v[78:79], v[94:95]
	v_pk_add_f32 v[78:79], v[78:79], v[94:95] neg_lo:[0,1] neg_hi:[0,1]
	s_mov_b32 s5, 0
	v_pk_mul_f32 v[94:95], v[78:79], s[10:11]
	s_nop 0
	v_pk_fma_f32 v[78:79], v[78:79], s[8:9], v[94:95] op_sel:[0,0,1] op_sel_hi:[1,0,0]
	v_pk_add_f32 v[94:95], v[80:81], v[96:97]
	v_pk_add_f32 v[80:81], v[80:81], v[96:97] neg_lo:[0,1] neg_hi:[0,1]
	s_nop 0
	v_pk_mul_f32 v[96:97], v[80:81], s[14:15]
	s_nop 0
	v_pk_fma_f32 v[80:81], v[80:81], s[12:13], v[96:97] op_sel:[0,0,1] op_sel_hi:[1,0,0]
	v_pk_add_f32 v[96:97], v[132:133], v[120:121]
	v_pk_add_f32 v[120:121], v[132:133], v[120:121] neg_lo:[0,1] neg_hi:[0,1]
	v_pk_add_f32 v[132:133], v[134:135], v[106:107]
	v_pk_add_f32 v[106:107], v[134:135], v[106:107] neg_lo:[0,1] neg_hi:[0,1]
	s_nop 0
	v_pk_mul_f32 v[134:135], v[106:107], s[10:11]
	s_nop 0
	v_pk_fma_f32 v[106:107], v[106:107], s[10:11], v[134:135] op_sel:[0,0,1] op_sel_hi:[1,0,0]
	v_pk_add_f32 v[134:135], v[130:131], v[124:125]
	v_pk_add_f32 v[130:131], v[130:131], v[124:125] op_sel:[1,1] op_sel_hi:[0,0] neg_lo:[1,0] neg_hi:[0,1]
	s_nop 0
	v_pk_add_f32 v[124:125], v[118:119], v[126:127]
	v_pk_add_f32 v[118:119], v[118:119], v[126:127] neg_lo:[0,1] neg_hi:[0,1]
	s_nop 0
	v_pk_mul_f32 v[126:127], v[118:119], s[10:11]
	s_nop 0
	v_pk_fma_f32 v[118:119], v[118:119], s[8:9], v[126:127] op_sel:[0,0,1] op_sel_hi:[1,0,0]
	v_pk_add_f32 v[126:127], v[114:115], v[122:123]
	v_pk_add_f32 v[114:115], v[114:115], v[122:123] neg_lo:[0,1] neg_hi:[0,1]
	v_pk_add_f32 v[122:123], v[82:83], v[108:109]
	v_pk_add_f32 v[82:83], v[82:83], v[108:109] neg_lo:[0,1] neg_hi:[0,1]
	s_nop 0
	v_pk_mul_f32 v[108:109], v[82:83], s[10:11]
	s_nop 0
	v_pk_fma_f32 v[82:83], v[82:83], s[10:11], v[108:109] op_sel:[0,0,1] op_sel_hi:[1,0,0]
	v_pk_add_f32 v[108:109], v[100:101], v[110:111]
	v_pk_add_f32 v[110:111], v[100:101], v[110:111] op_sel:[1,1] op_sel_hi:[0,0] neg_lo:[1,0] neg_hi:[0,1]
	s_nop 0
	v_pk_add_f32 v[100:101], v[102:103], v[112:113]
	v_pk_add_f32 v[102:103], v[102:103], v[112:113] neg_lo:[0,1] neg_hi:[0,1]
	s_nop 0
	v_pk_mul_f32 v[112:113], v[102:103], s[10:11]
	s_nop 0
	v_pk_fma_f32 v[102:103], v[102:103], s[8:9], v[112:113] op_sel:[0,0,1] op_sel_hi:[1,0,0]
	v_pk_add_f32 v[112:113], v[128:129], v[88:89]
	v_pk_add_f32 v[88:89], v[128:129], v[88:89] neg_lo:[0,1] neg_hi:[0,1]
	v_pk_add_f32 v[128:129], v[116:117], v[74:75]
	v_pk_add_f32 v[74:75], v[116:117], v[74:75] neg_lo:[0,1] neg_hi:[0,1]
	s_nop 0
	v_pk_mul_f32 v[116:117], v[74:75], s[10:11]
	s_nop 0
	v_pk_fma_f32 v[74:75], v[74:75], s[10:11], v[116:117] op_sel:[0,0,1] op_sel_hi:[1,0,0]
	v_pk_add_f32 v[116:117], v[84:85], v[92:93]
	v_pk_add_f32 v[92:93], v[84:85], v[92:93] op_sel:[1,1] op_sel_hi:[0,0] neg_lo:[1,0] neg_hi:[0,1]
	s_nop 0
	v_pk_add_f32 v[84:85], v[86:87], v[94:95]
	v_pk_add_f32 v[86:87], v[86:87], v[94:95] neg_lo:[0,1] neg_hi:[0,1]
	s_nop 0
	v_pk_mul_f32 v[94:95], v[86:87], s[10:11]
	s_nop 0
	v_pk_fma_f32 v[86:87], v[86:87], s[8:9], v[94:95] op_sel:[0,0,1] op_sel_hi:[1,0,0]
	v_pk_add_f32 v[94:95], v[98:99], v[90:91]
	v_pk_add_f32 v[90:91], v[98:99], v[90:91] neg_lo:[0,1] neg_hi:[0,1]
	v_pk_add_f32 v[98:99], v[66:67], v[76:77]
	v_pk_add_f32 v[66:67], v[66:67], v[76:77] neg_lo:[0,1] neg_hi:[0,1]
	s_nop 0
	v_pk_mul_f32 v[76:77], v[66:67], s[10:11]
	s_nop 0
	v_pk_fma_f32 v[66:67], v[66:67], s[10:11], v[76:77] op_sel:[0,0,1] op_sel_hi:[1,0,0]
	v_pk_add_f32 v[76:77], v[68:69], v[78:79]
	v_pk_add_f32 v[78:79], v[68:69], v[78:79] op_sel:[1,1] op_sel_hi:[0,0] neg_lo:[1,0] neg_hi:[0,1]
	s_nop 0
	v_pk_add_f32 v[68:69], v[72:73], v[80:81]
	v_pk_add_f32 v[72:73], v[72:73], v[80:81] neg_lo:[0,1] neg_hi:[0,1]
	v_pk_add_f32 v[136:137], v[90:91], v[78:79]
	v_pk_mul_f32 v[80:81], v[72:73], s[10:11]
	v_pk_add_f32 v[78:79], v[90:91], v[78:79] neg_lo:[0,1] neg_hi:[0,1]
	v_pk_fma_f32 v[72:73], v[72:73], s[8:9], v[80:81] op_sel:[0,0,1] op_sel_hi:[1,0,0]
	v_pk_add_f32 v[80:81], v[96:97], v[134:135]
	v_pk_add_f32 v[96:97], v[96:97], v[134:135] neg_lo:[0,1] neg_hi:[0,1]
	v_pk_add_f32 v[134:135], v[132:133], v[124:125]
	v_pk_add_f32 v[132:133], v[132:133], v[124:125] op_sel:[1,1] op_sel_hi:[0,0] neg_lo:[1,0] neg_hi:[0,1]
	v_pk_add_f32 v[90:91], v[66:67], v[72:73]
	v_pk_add_f32 v[124:125], v[120:121], v[130:131]
	v_pk_add_f32 v[120:121], v[120:121], v[130:131] neg_lo:[0,1] neg_hi:[0,1]
	v_pk_add_f32 v[130:131], v[106:107], v[118:119]
	v_pk_add_f32 v[118:119], v[106:107], v[118:119] op_sel:[1,1] op_sel_hi:[0,0] neg_lo:[1,0] neg_hi:[0,1]
	v_pk_add_f32 v[72:73], v[66:67], v[72:73] op_sel:[1,1] op_sel_hi:[0,0] neg_lo:[1,0] neg_hi:[0,1]
	v_pk_add_f32 v[106:107], v[126:127], v[108:109]
	v_pk_add_f32 v[108:109], v[126:127], v[108:109] neg_lo:[0,1] neg_hi:[0,1]
	v_pk_add_f32 v[126:127], v[122:123], v[100:101]
	v_pk_add_f32 v[122:123], v[122:123], v[100:101] op_sel:[1,1] op_sel_hi:[0,0] neg_lo:[1,0] neg_hi:[0,1]
	v_pk_add_f32 v[100:101], v[114:115], v[110:111]
	v_pk_add_f32 v[110:111], v[114:115], v[110:111] neg_lo:[0,1] neg_hi:[0,1]
	v_pk_add_f32 v[114:115], v[82:83], v[102:103]
	v_pk_add_f32 v[102:103], v[82:83], v[102:103] op_sel:[1,1] op_sel_hi:[0,0] neg_lo:[1,0] neg_hi:[0,1]
	v_pk_add_f32 v[82:83], v[112:113], v[116:117]
	v_pk_add_f32 v[112:113], v[112:113], v[116:117] neg_lo:[0,1] neg_hi:[0,1]
	v_pk_add_f32 v[116:117], v[128:129], v[84:85]
	v_pk_add_f32 v[128:129], v[128:129], v[84:85] op_sel:[1,1] op_sel_hi:[0,0] neg_lo:[1,0] neg_hi:[0,1]
	v_pk_add_f32 v[138:139], v[80:81], v[134:135]
	v_pk_add_f32 v[84:85], v[88:89], v[92:93]
	v_pk_add_f32 v[88:89], v[88:89], v[92:93] neg_lo:[0,1] neg_hi:[0,1]
	v_pk_add_f32 v[92:93], v[74:75], v[86:87]
	v_pk_add_f32 v[86:87], v[74:75], v[86:87] op_sel:[1,1] op_sel_hi:[0,0] neg_lo:[1,0] neg_hi:[0,1]
	v_pk_add_f32 v[80:81], v[80:81], v[134:135] neg_lo:[0,1] neg_hi:[0,1]
	v_pk_add_f32 v[74:75], v[94:95], v[76:77]
	v_pk_add_f32 v[76:77], v[94:95], v[76:77] neg_lo:[0,1] neg_hi:[0,1]
	v_pk_add_f32 v[94:95], v[98:99], v[68:69]
	v_pk_add_f32 v[98:99], v[98:99], v[68:69] op_sel:[1,1] op_sel_hi:[0,0] neg_lo:[1,0] neg_hi:[0,1]
	v_pk_add_f32 v[134:135], v[96:97], v[132:133]
	v_pk_add_f32 v[96:97], v[96:97], v[132:133] neg_lo:[0,1] neg_hi:[0,1]
	v_pk_add_f32 v[132:133], v[124:125], v[130:131]
	v_pk_add_f32 v[124:125], v[124:125], v[130:131] neg_lo:[0,1] neg_hi:[0,1]
	v_pk_add_f32 v[130:131], v[120:121], v[118:119]
	v_pk_add_f32 v[68:69], v[120:121], v[118:119] neg_lo:[0,1] neg_hi:[0,1]
	v_pk_add_f32 v[118:119], v[106:107], v[126:127]
	v_pk_add_f32 v[106:107], v[106:107], v[126:127] neg_lo:[0,1] neg_hi:[0,1]
	v_pk_add_f32 v[126:127], v[78:79], v[72:73]
	v_pk_add_f32 v[72:73], v[78:79], v[72:73] neg_lo:[0,1] neg_hi:[0,1]
	v_mul_f32_e32 v78, 0x38800000, v105
	v_sin_f32_e32 v79, v78
	v_cos_f32_e32 v78, v78
	v_pk_add_f32 v[120:121], v[108:109], v[122:123]
	v_pk_add_f32 v[108:109], v[108:109], v[122:123] neg_lo:[0,1] neg_hi:[0,1]
	v_pk_add_f32 v[122:123], v[100:101], v[114:115]
	v_pk_add_f32 v[100:101], v[100:101], v[114:115] neg_lo:[0,1] neg_hi:[0,1]
	v_pk_add_f32 v[114:115], v[110:111], v[102:103]
	v_pk_add_f32 v[66:67], v[110:111], v[102:103] neg_lo:[0,1] neg_hi:[0,1]
	v_pk_add_f32 v[102:103], v[82:83], v[116:117]
	v_pk_add_f32 v[82:83], v[82:83], v[116:117] neg_lo:[0,1] neg_hi:[0,1]
	v_pk_add_f32 v[116:117], v[84:85], v[92:93]
	v_pk_add_f32 v[84:85], v[84:85], v[92:93] neg_lo:[0,1] neg_hi:[0,1]
	v_pk_add_f32 v[92:93], v[88:89], v[86:87]
	v_pk_add_f32 v[86:87], v[88:89], v[86:87] neg_lo:[0,1] neg_hi:[0,1]
	v_pk_add_f32 v[88:89], v[74:75], v[94:95]
	v_pk_add_f32 v[74:75], v[74:75], v[94:95] neg_lo:[0,1] neg_hi:[0,1]
	v_pk_add_f32 v[94:95], v[76:77], v[98:99]
	v_pk_add_f32 v[76:77], v[76:77], v[98:99] neg_lo:[0,1] neg_hi:[0,1]
	v_pk_add_f32 v[98:99], v[136:137], v[90:91]
	v_pk_add_f32 v[90:91], v[136:137], v[90:91] neg_lo:[0,1] neg_hi:[0,1]
	v_sin_f32_e32 v136, v71
	v_pk_add_f32 v[110:111], v[112:113], v[128:129]
	v_pk_add_f32 v[112:113], v[112:113], v[128:129] neg_lo:[0,1] neg_hi:[0,1]
	v_cos_f32_e32 v128, v71
	v_pk_mul_f32 v[140:141], v[138:139], v[78:79] op_sel:[1,1] op_sel_hi:[0,1] neg_lo:[0,1]
	s_nop 0
	v_pk_fma_f32 v[138:139], v[138:139], v[78:79], v[140:141] op_sel_hi:[1,0,1]
	ds_write_b64 v142, v[138:139]
	v_pk_mul_f32 v[138:139], v[136:137], v[78:79] op_sel:[0,1] op_sel_hi:[0,0] neg_lo:[1,0]
	v_pk_fma_f32 v[78:79], v[78:79], v[128:129], v[138:139] op_sel_hi:[1,0,1]
	s_nop 0
	v_pk_mul_f32 v[138:139], v[102:103], v[78:79] op_sel:[1,1] op_sel_hi:[0,1] neg_lo:[0,1]
	s_nop 0
	v_pk_fma_f32 v[102:103], v[102:103], v[78:79], v[138:139] op_sel_hi:[1,0,1]
	v_pk_mul_f32 v[138:139], v[136:137], v[78:79] op_sel:[0,1] op_sel_hi:[0,0] neg_lo:[1,0]
	v_pk_fma_f32 v[78:79], v[78:79], v[128:129], v[138:139] op_sel_hi:[1,0,1]
	s_nop 0
	v_pk_mul_f32 v[138:139], v[118:119], v[78:79] op_sel:[1,1] op_sel_hi:[0,1] neg_lo:[0,1]
	s_nop 0
	v_pk_fma_f32 v[118:119], v[118:119], v[78:79], v[138:139] op_sel_hi:[1,0,1]
	ds_write2_b64 v0, v[102:103], v[118:119] offset0:33 offset1:66
	v_pk_mul_f32 v[102:103], v[136:137], v[78:79] op_sel:[0,1] op_sel_hi:[0,0] neg_lo:[1,0]
	v_pk_fma_f32 v[78:79], v[78:79], v[128:129], v[102:103] op_sel_hi:[1,0,1]
	s_nop 0
	v_pk_mul_f32 v[102:103], v[88:89], v[78:79] op_sel:[1,1] op_sel_hi:[0,1] neg_lo:[0,1]
	s_nop 0
	v_pk_fma_f32 v[88:89], v[88:89], v[78:79], v[102:103] op_sel_hi:[1,0,1]
	v_pk_mul_f32 v[102:103], v[136:137], v[78:79] op_sel:[0,1] op_sel_hi:[0,0] neg_lo:[1,0]
	v_pk_fma_f32 v[78:79], v[78:79], v[128:129], v[102:103] op_sel_hi:[1,0,1]
	s_nop 0
	v_pk_mul_f32 v[102:103], v[132:133], v[78:79] op_sel:[1,1] op_sel_hi:[0,1] neg_lo:[0,1]
	s_nop 0
	v_pk_fma_f32 v[102:103], v[132:133], v[78:79], v[102:103] op_sel_hi:[1,0,1]
	ds_write2_b64 v0, v[88:89], v[102:103] offset0:99 offset1:132
	v_pk_mul_f32 v[88:89], v[136:137], v[78:79] op_sel:[0,1] op_sel_hi:[0,0] neg_lo:[1,0]
	v_pk_fma_f32 v[78:79], v[78:79], v[128:129], v[88:89] op_sel_hi:[1,0,1]
	s_nop 0
	v_pk_mul_f32 v[88:89], v[116:117], v[78:79] op_sel:[1,1] op_sel_hi:[0,1] neg_lo:[0,1]
	v_pk_mul_f32 v[102:103], v[136:137], v[78:79] op_sel:[0,1] op_sel_hi:[0,0] neg_lo:[1,0]
	v_pk_fma_f32 v[88:89], v[116:117], v[78:79], v[88:89] op_sel_hi:[1,0,1]
	v_pk_fma_f32 v[78:79], v[78:79], v[128:129], v[102:103] op_sel_hi:[1,0,1]
	s_nop 0
	v_pk_mul_f32 v[102:103], v[122:123], v[78:79] op_sel:[1,1] op_sel_hi:[0,1] neg_lo:[0,1]
	s_nop 0
	v_pk_fma_f32 v[102:103], v[122:123], v[78:79], v[102:103] op_sel_hi:[1,0,1]
	ds_write2_b64 v0, v[88:89], v[102:103] offset0:165 offset1:198
	v_pk_mul_f32 v[88:89], v[136:137], v[78:79] op_sel:[0,1] op_sel_hi:[0,0] neg_lo:[1,0]
	v_pk_fma_f32 v[78:79], v[78:79], v[128:129], v[88:89] op_sel_hi:[1,0,1]
	s_nop 0
	v_pk_mul_f32 v[88:89], v[98:99], v[78:79] op_sel:[1,1] op_sel_hi:[0,1] neg_lo:[0,1]
	s_nop 0
	v_pk_fma_f32 v[88:89], v[98:99], v[78:79], v[88:89] op_sel_hi:[1,0,1]
	v_pk_mul_f32 v[98:99], v[136:137], v[78:79] op_sel:[0,1] op_sel_hi:[0,0] neg_lo:[1,0]
	v_pk_fma_f32 v[78:79], v[78:79], v[128:129], v[98:99] op_sel_hi:[1,0,1]
	s_nop 0
	v_pk_mul_f32 v[98:99], v[134:135], v[78:79] op_sel:[1,1] op_sel_hi:[0,1] neg_lo:[0,1]
	s_nop 0
	v_pk_fma_f32 v[98:99], v[134:135], v[78:79], v[98:99] op_sel_hi:[1,0,1]
	ds_write2_b64 v143, v[88:89], v[98:99] offset0:103 offset1:136
	v_pk_mul_f32 v[88:89], v[136:137], v[78:79] op_sel:[0,1] op_sel_hi:[0,0] neg_lo:[1,0]
	v_pk_fma_f32 v[78:79], v[78:79], v[128:129], v[88:89] op_sel_hi:[1,0,1]
	s_nop 0
	v_pk_mul_f32 v[88:89], v[110:111], v[78:79] op_sel:[1,1] op_sel_hi:[0,1] neg_lo:[0,1]
	v_pk_mul_f32 v[98:99], v[136:137], v[78:79] op_sel:[0,1] op_sel_hi:[0,0] neg_lo:[1,0]
	v_pk_fma_f32 v[88:89], v[110:111], v[78:79], v[88:89] op_sel_hi:[1,0,1]
	v_pk_fma_f32 v[78:79], v[78:79], v[128:129], v[98:99] op_sel_hi:[1,0,1]
	s_nop 0
	v_pk_mul_f32 v[98:99], v[120:121], v[78:79] op_sel:[1,1] op_sel_hi:[0,1] neg_lo:[0,1]
	s_nop 0
	v_pk_fma_f32 v[98:99], v[120:121], v[78:79], v[98:99] op_sel_hi:[1,0,1]
	ds_write2_b64 v144, v[88:89], v[98:99] offset0:41 offset1:74
	v_pk_mul_f32 v[88:89], v[136:137], v[78:79] op_sel:[0,1] op_sel_hi:[0,0] neg_lo:[1,0]
	v_pk_fma_f32 v[78:79], v[78:79], v[128:129], v[88:89] op_sel_hi:[1,0,1]
	s_nop 0
	v_pk_mul_f32 v[88:89], v[94:95], v[78:79] op_sel:[1,1] op_sel_hi:[0,1] neg_lo:[0,1]
	s_nop 0
	v_pk_fma_f32 v[88:89], v[94:95], v[78:79], v[88:89] op_sel_hi:[1,0,1]
	v_pk_mul_f32 v[94:95], v[136:137], v[78:79] op_sel:[0,1] op_sel_hi:[0,0] neg_lo:[1,0]
	v_pk_fma_f32 v[78:79], v[78:79], v[128:129], v[94:95] op_sel_hi:[1,0,1]
	s_nop 0
	v_pk_mul_f32 v[94:95], v[130:131], v[78:79] op_sel:[1,1] op_sel_hi:[0,1] neg_lo:[0,1]
	v_pk_fma_f32 v[94:95], v[130:131], v[78:79], v[94:95] op_sel_hi:[1,0,1]
	ds_write2_b64 v144, v[88:89], v[94:95] offset0:107 offset1:140
	v_pk_mul_f32 v[88:89], v[136:137], v[78:79] op_sel:[0,1] op_sel_hi:[0,0] neg_lo:[1,0]
	v_pk_fma_f32 v[78:79], v[78:79], v[128:129], v[88:89] op_sel_hi:[1,0,1]
	s_nop 0
	v_pk_mul_f32 v[88:89], v[92:93], v[78:79] op_sel:[1,1] op_sel_hi:[0,1] neg_lo:[0,1]
	v_pk_fma_f32 v[88:89], v[92:93], v[78:79], v[88:89] op_sel_hi:[1,0,1]
	v_pk_mul_f32 v[92:93], v[136:137], v[78:79] op_sel:[0,1] op_sel_hi:[0,0] neg_lo:[1,0]
	v_pk_fma_f32 v[78:79], v[78:79], v[128:129], v[92:93] op_sel_hi:[1,0,1]
	s_nop 0
	v_pk_mul_f32 v[92:93], v[114:115], v[78:79] op_sel:[1,1] op_sel_hi:[0,1] neg_lo:[0,1]
	v_pk_fma_f32 v[92:93], v[114:115], v[78:79], v[92:93] op_sel_hi:[1,0,1]
	ds_write2_b64 v144, v[88:89], v[92:93] offset0:173 offset1:206
	v_pk_mul_f32 v[88:89], v[136:137], v[78:79] op_sel:[0,1] op_sel_hi:[0,0] neg_lo:[1,0]
	v_pk_fma_f32 v[78:79], v[78:79], v[128:129], v[88:89] op_sel_hi:[1,0,1]
	s_nop 0
	v_pk_mul_f32 v[88:89], v[126:127], v[78:79] op_sel:[1,1] op_sel_hi:[0,1] neg_lo:[0,1]
	v_pk_mul_f32 v[92:93], v[136:137], v[78:79] op_sel:[0,1] op_sel_hi:[0,0] neg_lo:[1,0]
	v_pk_fma_f32 v[88:89], v[126:127], v[78:79], v[88:89] op_sel_hi:[1,0,1]
	v_pk_fma_f32 v[78:79], v[78:79], v[128:129], v[92:93] op_sel_hi:[1,0,1]
	s_nop 0
	v_pk_mul_f32 v[92:93], v[80:81], v[78:79] op_sel:[1,1] op_sel_hi:[0,1] neg_lo:[0,1]
	v_pk_fma_f32 v[80:81], v[80:81], v[78:79], v[92:93] op_sel_hi:[1,0,1]
	ds_write2_b64 v145, v[88:89], v[80:81] offset0:111 offset1:144
	v_pk_mul_f32 v[80:81], v[136:137], v[78:79] op_sel:[0,1] op_sel_hi:[0,0] neg_lo:[1,0]
	v_pk_fma_f32 v[78:79], v[78:79], v[128:129], v[80:81] op_sel_hi:[1,0,1]
	s_nop 0
	v_pk_mul_f32 v[80:81], v[82:83], v[78:79] op_sel:[1,1] op_sel_hi:[0,1] neg_lo:[0,1]
	v_pk_fma_f32 v[80:81], v[82:83], v[78:79], v[80:81] op_sel_hi:[1,0,1]
	v_pk_mul_f32 v[82:83], v[136:137], v[78:79] op_sel:[0,1] op_sel_hi:[0,0] neg_lo:[1,0]
	v_pk_fma_f32 v[78:79], v[78:79], v[128:129], v[82:83] op_sel_hi:[1,0,1]
	s_nop 0
	v_pk_mul_f32 v[82:83], v[106:107], v[78:79] op_sel:[1,1] op_sel_hi:[0,1] neg_lo:[0,1]
	v_pk_fma_f32 v[82:83], v[106:107], v[78:79], v[82:83] op_sel_hi:[1,0,1]
	ds_write2_b64 v146, v[80:81], v[82:83] offset0:49 offset1:82
	v_pk_mul_f32 v[80:81], v[136:137], v[78:79] op_sel:[0,1] op_sel_hi:[0,0] neg_lo:[1,0]
	v_pk_fma_f32 v[78:79], v[78:79], v[128:129], v[80:81] op_sel_hi:[1,0,1]
	s_nop 0
	v_pk_mul_f32 v[80:81], v[74:75], v[78:79] op_sel:[1,1] op_sel_hi:[0,1] neg_lo:[0,1]
	v_pk_fma_f32 v[74:75], v[74:75], v[78:79], v[80:81] op_sel_hi:[1,0,1]
	v_pk_mul_f32 v[80:81], v[136:137], v[78:79] op_sel:[0,1] op_sel_hi:[0,0] neg_lo:[1,0]
	v_pk_fma_f32 v[78:79], v[78:79], v[128:129], v[80:81] op_sel_hi:[1,0,1]
	s_nop 0
	v_pk_mul_f32 v[80:81], v[124:125], v[78:79] op_sel:[1,1] op_sel_hi:[0,1] neg_lo:[0,1]
	v_pk_fma_f32 v[80:81], v[124:125], v[78:79], v[80:81] op_sel_hi:[1,0,1]
	ds_write2_b64 v146, v[74:75], v[80:81] offset0:115 offset1:148
	v_pk_mul_f32 v[74:75], v[136:137], v[78:79] op_sel:[0,1] op_sel_hi:[0,0] neg_lo:[1,0]
	v_pk_fma_f32 v[74:75], v[78:79], v[128:129], v[74:75] op_sel_hi:[1,0,1]
	s_nop 0
	v_pk_mul_f32 v[78:79], v[84:85], v[74:75] op_sel:[1,1] op_sel_hi:[0,1] neg_lo:[0,1]
	v_pk_mul_f32 v[80:81], v[136:137], v[74:75] op_sel:[0,1] op_sel_hi:[0,0] neg_lo:[1,0]
	v_pk_fma_f32 v[78:79], v[84:85], v[74:75], v[78:79] op_sel_hi:[1,0,1]
	v_pk_fma_f32 v[74:75], v[74:75], v[128:129], v[80:81] op_sel_hi:[1,0,1]
	s_nop 0
	v_pk_mul_f32 v[80:81], v[100:101], v[74:75] op_sel:[1,1] op_sel_hi:[0,1] neg_lo:[0,1]
	v_pk_fma_f32 v[80:81], v[100:101], v[74:75], v[80:81] op_sel_hi:[1,0,1]
	ds_write2_b64 v146, v[78:79], v[80:81] offset0:181 offset1:214
	v_pk_mul_f32 v[78:79], v[136:137], v[74:75] op_sel:[0,1] op_sel_hi:[0,0] neg_lo:[1,0]
	v_pk_fma_f32 v[74:75], v[74:75], v[128:129], v[78:79] op_sel_hi:[1,0,1]
	s_nop 0
	v_pk_mul_f32 v[78:79], v[90:91], v[74:75] op_sel:[1,1] op_sel_hi:[0,1] neg_lo:[0,1]
	v_pk_mul_f32 v[80:81], v[136:137], v[74:75] op_sel:[0,1] op_sel_hi:[0,0] neg_lo:[1,0]
	v_pk_fma_f32 v[78:79], v[90:91], v[74:75], v[78:79] op_sel_hi:[1,0,1]
	v_pk_fma_f32 v[74:75], v[74:75], v[128:129], v[80:81] op_sel_hi:[1,0,1]
	s_nop 0
	v_pk_mul_f32 v[80:81], v[96:97], v[74:75] op_sel:[1,1] op_sel_hi:[0,1] neg_lo:[0,1]
	v_pk_fma_f32 v[80:81], v[96:97], v[74:75], v[80:81] op_sel_hi:[1,0,1]
	ds_write2_b64 v147, v[78:79], v[80:81] offset0:119 offset1:152
	v_pk_mul_f32 v[78:79], v[136:137], v[74:75] op_sel:[0,1] op_sel_hi:[0,0] neg_lo:[1,0]
	v_pk_fma_f32 v[74:75], v[74:75], v[128:129], v[78:79] op_sel_hi:[1,0,1]
	s_nop 0
	v_pk_mul_f32 v[78:79], v[112:113], v[74:75] op_sel:[1,1] op_sel_hi:[0,1] neg_lo:[0,1]
	v_pk_mul_f32 v[80:81], v[136:137], v[74:75] op_sel:[0,1] op_sel_hi:[0,0] neg_lo:[1,0]
	v_pk_fma_f32 v[78:79], v[112:113], v[74:75], v[78:79] op_sel_hi:[1,0,1]
	v_pk_fma_f32 v[74:75], v[74:75], v[128:129], v[80:81] op_sel_hi:[1,0,1]
	s_nop 0
	v_pk_mul_f32 v[80:81], v[108:109], v[74:75] op_sel:[1,1] op_sel_hi:[0,1] neg_lo:[0,1]
	v_pk_fma_f32 v[80:81], v[108:109], v[74:75], v[80:81] op_sel_hi:[1,0,1]
	ds_write2_b64 v70, v[78:79], v[80:81] offset0:57 offset1:90
	v_pk_mul_f32 v[78:79], v[136:137], v[74:75] op_sel:[0,1] op_sel_hi:[0,0] neg_lo:[1,0]
	v_pk_fma_f32 v[74:75], v[74:75], v[128:129], v[78:79] op_sel_hi:[1,0,1]
	s_nop 0
	v_pk_mul_f32 v[78:79], v[76:77], v[74:75] op_sel:[1,1] op_sel_hi:[0,1] neg_lo:[0,1]
	v_pk_fma_f32 v[76:77], v[76:77], v[74:75], v[78:79] op_sel_hi:[1,0,1]
	v_pk_mul_f32 v[78:79], v[136:137], v[74:75] op_sel:[0,1] op_sel_hi:[0,0] neg_lo:[1,0]
	v_pk_fma_f32 v[74:75], v[74:75], v[128:129], v[78:79] op_sel_hi:[1,0,1]
	s_nop 0
	v_pk_mul_f32 v[78:79], v[68:69], v[74:75] op_sel:[1,1] op_sel_hi:[0,1] neg_lo:[0,1]
	v_pk_fma_f32 v[68:69], v[68:69], v[74:75], v[78:79] op_sel_hi:[1,0,1]
	ds_write2_b64 v70, v[76:77], v[68:69] offset0:123 offset1:156
	v_pk_mul_f32 v[68:69], v[136:137], v[74:75] op_sel:[0,1] op_sel_hi:[0,0] neg_lo:[1,0]
	v_pk_fma_f32 v[68:69], v[74:75], v[128:129], v[68:69] op_sel_hi:[1,0,1]
	s_nop 0
	v_pk_mul_f32 v[74:75], v[86:87], v[68:69] op_sel:[1,1] op_sel_hi:[0,1] neg_lo:[0,1]
	v_pk_mul_f32 v[76:77], v[136:137], v[68:69] op_sel:[0,1] op_sel_hi:[0,0] neg_lo:[1,0]
	v_pk_fma_f32 v[74:75], v[86:87], v[68:69], v[74:75] op_sel_hi:[1,0,1]
	v_pk_fma_f32 v[68:69], v[68:69], v[128:129], v[76:77] op_sel_hi:[1,0,1]
	s_nop 0
	v_pk_mul_f32 v[76:77], v[66:67], v[68:69] op_sel:[1,1] op_sel_hi:[0,1] neg_lo:[0,1]
	v_pk_fma_f32 v[66:67], v[66:67], v[68:69], v[76:77] op_sel_hi:[1,0,1]
	ds_write2_b64 v70, v[74:75], v[66:67] offset0:189 offset1:222
	v_pk_mul_f32 v[66:67], v[136:137], v[68:69] op_sel:[0,1] op_sel_hi:[0,0] neg_lo:[1,0]
	v_pk_fma_f32 v[66:67], v[68:69], v[128:129], v[66:67] op_sel_hi:[1,0,1]
	s_nop 0
	v_pk_mul_f32 v[68:69], v[72:73], v[66:67] op_sel:[1,1] op_sel_hi:[0,1] neg_lo:[0,1]
	v_pk_fma_f32 v[66:67], v[72:73], v[66:67], v[68:69] op_sel_hi:[1,0,1]
	ds_write_b64 v0, v[66:67] offset:8184
	s_waitcnt lgkmcnt(0)
	s_barrier
.LBB0_364:
	v_mov_b32 v66, 0
	v_cndmask_b32_e64 v0, 0, 1, s[48:49]
	v_add3_u32 v66, s5, v170, v66
	v_cmp_ne_u32_e64 s[0:1], 1, v0
	v_ashrrev_i32_e32 v0, 5, v66
	v_lshlrev_b32_e32 v70, 3, v66
	v_lshlrev_b32_e32 v0, 3, v0
	v_ashrrev_i32_e32 v67, 31, v66
	v_add3_u32 v0, 0, v0, v70
	v_add_u32_e32 v217, 0x10800, v0
	v_lshlrev_b64 v[66:67], 1, v[66:67]
	ds_read_b64 v[80:81], v0
	ds_read_b64 v[82:83], v0 offset:8448
	ds_read_b64 v[84:85], v0 offset:16896
	ds_read_b64 v[86:87], v0 offset:25344
	ds_read_b64 v[88:89], v0 offset:33792
	ds_read_b64 v[90:91], v0 offset:42240
	ds_read_b64 v[92:93], v0 offset:50688
	ds_read_b64 v[94:95], v0 offset:59136
	ds_read_b64 v[96:97], v217
	ds_read_b64 v[98:99], v217 offset:8448
	ds_read_b64 v[100:101], v217 offset:16896
	ds_read_b64 v[102:103], v217 offset:25344
	ds_read_b64 v[106:107], v217 offset:33792
	ds_read_b64 v[108:109], v217 offset:42240
	ds_read_b64 v[110:111], v217 offset:50688
	ds_read_b64 v[112:113], v217 offset:59136
	v_lshl_add_u64 v[68:69], s[44:45], 0, v[66:67]
	v_add_co_u32_e32 v70, vcc, s58, v68
	v_lshl_add_u64 v[66:67], s[46:47], 0, v[66:67]
	s_nop 0
	v_addc_co_u32_e32 v71, vcc, 0, v69, vcc
	v_add_co_u32_e32 v72, vcc, s59, v68
	s_waitcnt lgkmcnt(7)
	v_pk_add_f32 v[116:117], v[80:81], v[96:97]
	v_addc_co_u32_e32 v73, vcc, 0, v69, vcc
	v_pk_add_f32 v[80:81], v[80:81], v[96:97] neg_lo:[0,1] neg_hi:[0,1]
	s_waitcnt lgkmcnt(6)
	v_pk_add_f32 v[96:97], v[82:83], v[98:99]
	v_pk_add_f32 v[82:83], v[82:83], v[98:99] neg_lo:[0,1] neg_hi:[0,1]
	s_waitcnt lgkmcnt(5)
	v_pk_add_f32 v[98:99], v[84:85], v[100:101]
	v_pk_add_f32 v[84:85], v[84:85], v[100:101] neg_lo:[0,1] neg_hi:[0,1]
	s_waitcnt lgkmcnt(4)
	v_pk_add_f32 v[100:101], v[86:87], v[102:103]
	v_pk_add_f32 v[86:87], v[86:87], v[102:103] neg_lo:[0,1] neg_hi:[0,1]
	s_waitcnt lgkmcnt(3)
	v_pk_add_f32 v[102:103], v[88:89], v[106:107]
	v_pk_add_f32 v[122:123], v[88:89], v[106:107] op_sel:[1,1] op_sel_hi:[0,0] neg_lo:[1,0] neg_hi:[0,1]
	s_waitcnt lgkmcnt(2)
	v_pk_add_f32 v[106:107], v[90:91], v[108:109]
	v_pk_add_f32 v[90:91], v[90:91], v[108:109] neg_lo:[0,1] neg_hi:[0,1]
	s_waitcnt lgkmcnt(1)
	v_pk_add_f32 v[108:109], v[92:93], v[110:111]
	v_pk_add_f32 v[92:93], v[92:93], v[110:111] neg_lo:[0,1] neg_hi:[0,1]
	s_waitcnt lgkmcnt(0)
	v_pk_add_f32 v[110:111], v[94:95], v[112:113]
	v_pk_add_f32 v[94:95], v[94:95], v[112:113] neg_lo:[0,1] neg_hi:[0,1]
	s_movk_i32 s5, 0x200
	v_add_co_u32_e32 v74, vcc, s58, v66
	v_pk_mul_f32 v[112:113], v[82:83], s[14:15]
	v_pk_mul_f32 v[118:119], v[84:85], s[10:11]
	v_pk_mul_f32 v[120:121], v[86:87], s[6:7]
	v_pk_mul_f32 v[88:89], v[90:91], s[6:7]
	v_pk_mul_f32 v[124:125], v[92:93], s[10:11]
	v_pk_mul_f32 v[126:127], v[94:95], s[14:15]
	v_pk_add_f32 v[128:129], v[116:117], v[102:103]
	v_pk_add_f32 v[102:103], v[116:117], v[102:103] neg_lo:[0,1] neg_hi:[0,1]
	v_pk_add_f32 v[116:117], v[96:97], v[106:107]
	v_pk_add_f32 v[96:97], v[96:97], v[106:107] neg_lo:[0,1] neg_hi:[0,1]
	v_pk_add_f32 v[106:107], v[98:99], v[108:109]
	v_pk_add_f32 v[98:99], v[98:99], v[108:109] neg_lo:[0,1] neg_hi:[0,1]
	v_pk_add_f32 v[108:109], v[100:101], v[110:111]
	v_pk_add_f32 v[100:101], v[100:101], v[110:111] neg_lo:[0,1] neg_hi:[0,1]
	v_addc_co_u32_e32 v75, vcc, 0, v67, vcc
	v_pk_fma_f32 v[82:83], v[82:83], s[6:7], v[112:113] op_sel:[0,0,1] op_sel_hi:[1,0,0]
	v_pk_fma_f32 v[84:85], v[84:85], s[10:11], v[118:119] op_sel:[0,0,1] op_sel_hi:[1,0,0]
	v_pk_fma_f32 v[86:87], v[86:87], s[14:15], v[120:121] op_sel:[0,0,1] op_sel_hi:[1,0,0]
	v_pk_fma_f32 v[88:89], v[90:91], s[4:5], v[88:89] op_sel:[0,0,1] op_sel_hi:[1,0,0]
	v_pk_fma_f32 v[90:91], v[92:93], s[8:9], v[124:125] op_sel:[0,0,1] op_sel_hi:[1,0,0]
	v_pk_fma_f32 v[92:93], v[94:95], s[12:13], v[126:127] op_sel:[0,0,1] op_sel_hi:[1,0,0]
	v_pk_mul_f32 v[94:95], v[96:97], s[10:11]
	v_xor_b32_e32 v110, 0x80000000, v99
	v_mov_b32_e32 v111, v98
	v_pk_mul_f32 v[98:99], v[100:101], s[10:11]
	v_add_co_u32_e32 v76, vcc, s59, v66
	v_pk_add_f32 v[118:119], v[128:129], v[106:107]
	v_pk_add_f32 v[120:121], v[116:117], v[108:109]
	v_pk_add_f32 v[108:109], v[116:117], v[108:109] neg_lo:[0,1] neg_hi:[0,1]
	v_pk_fma_f32 v[94:95], v[96:97], s[10:11], v[94:95] op_sel:[0,0,1] op_sel_hi:[1,0,0]
	v_pk_fma_f32 v[96:97], v[100:101], s[8:9], v[98:99] op_sel:[0,0,1] op_sel_hi:[1,0,0]
	v_pk_add_f32 v[98:99], v[82:83], v[88:89]
	v_pk_add_f32 v[82:83], v[82:83], v[88:89] neg_lo:[0,1] neg_hi:[0,1]
	v_pk_add_f32 v[88:89], v[84:85], v[90:91]
	v_pk_add_f32 v[116:117], v[84:85], v[90:91] op_sel:[1,1] op_sel_hi:[0,0] neg_lo:[1,0] neg_hi:[0,1]
	v_pk_add_f32 v[90:91], v[86:87], v[92:93]
	v_pk_add_f32 v[86:87], v[86:87], v[92:93] neg_lo:[0,1] neg_hi:[0,1]
	v_addc_co_u32_e32 v77, vcc, 0, v67, vcc
	v_pk_add_f32 v[112:113], v[80:81], v[122:123]
	v_pk_add_f32 v[106:107], v[128:129], v[106:107] neg_lo:[0,1] neg_hi:[0,1]
	v_xor_b32_e32 v92, 0x80000000, v109
	v_mov_b32_e32 v93, v108
	v_pk_add_f32 v[100:101], v[102:103], v[110:111]
	v_pk_add_f32 v[102:103], v[102:103], v[110:111] neg_lo:[0,1] neg_hi:[0,1]
	v_pk_add_f32 v[108:109], v[118:119], v[120:121]
	v_pk_mul_f32 v[110:111], v[82:83], s[10:11]
	v_pk_mul_f32 v[84:85], v[86:87], s[10:11]
	v_add_co_u32_e32 v78, vcc, s60, v68
	v_pk_add_f32 v[118:119], v[94:95], v[96:97]
	v_pk_add_f32 v[94:95], v[94:95], v[96:97] neg_lo:[0,1] neg_hi:[0,1]
	v_pk_add_f32 v[96:97], v[112:113], v[88:89]
	v_pk_add_f32 v[88:89], v[112:113], v[88:89] neg_lo:[0,1] neg_hi:[0,1]
	v_pk_add_f32 v[112:113], v[98:99], v[90:91]
	v_pk_add_f32 v[90:91], v[98:99], v[90:91] neg_lo:[0,1] neg_hi:[0,1]
	v_pk_add_f32 v[92:93], v[106:107], v[92:93]
	v_cvt_pk_bf16_f32 v0, v108, s0
	v_pk_fma_f32 v[82:83], v[82:83], s[10:11], v[110:111] op_sel:[0,0,1] op_sel_hi:[1,0,0]
	v_pk_fma_f32 v[84:85], v[86:87], s[8:9], v[84:85] op_sel:[0,0,1] op_sel_hi:[1,0,0]
	v_addc_co_u32_e32 v79, vcc, 0, v69, vcc
	v_pk_add_f32 v[80:81], v[80:81], v[122:123] neg_lo:[0,1] neg_hi:[0,1]
	v_cvt_pk_bf16_f32 v105, v109, s0
	v_xor_b32_e32 v86, 0x80000000, v95
	v_mov_b32_e32 v87, v94
	v_xor_b32_e32 v94, 0x80000000, v91
	v_mov_b32_e32 v95, v90
	v_pk_add_f32 v[98:99], v[100:101], v[118:119]
	v_pk_add_f32 v[96:97], v[96:97], v[112:113]
	global_store_short v[68:69], v0, off
	global_store_short v[66:67], v105, off
	v_cvt_pk_bf16_f32 v0, v92, s0
	v_cvt_pk_bf16_f32 v100, v93, s0
	v_pk_add_f32 v[92:93], v[82:83], v[84:85]
	v_pk_add_f32 v[82:83], v[82:83], v[84:85] neg_lo:[0,1] neg_hi:[0,1]
	v_add_co_u32_e32 v114, vcc, 0x3000, v66
	v_pk_add_f32 v[90:91], v[80:81], v[116:117]
	v_pk_add_f32 v[80:81], v[80:81], v[116:117] neg_lo:[0,1] neg_hi:[0,1]
	v_pk_add_f32 v[84:85], v[102:103], v[86:87]
	v_pk_add_f32 v[86:87], v[88:89], v[94:95]
	v_cvt_pk_bf16_f32 v94, v96, s0
	v_xor_b32_e32 v88, 0x80000000, v83
	v_mov_b32_e32 v89, v82
	v_addc_co_u32_e32 v115, vcc, 0, v67, vcc
	v_cvt_pk_bf16_f32 v95, v97, s0
	v_cvt_pk_bf16_f32 v96, v98, s0
	v_cvt_pk_bf16_f32 v97, v99, s0
	global_store_short v[72:73], v0, off
	global_store_short v[76:77], v100, off
	v_pk_add_f32 v[82:83], v[90:91], v[92:93]
	global_store_short v[68:69], v94, off offset:2048
	global_store_short v[66:67], v95, off offset:2048
	global_store_short v[72:73], v96, off offset:-4096
	global_store_short v[76:77], v97, off offset:-4096
	v_cvt_pk_bf16_f32 v0, v86, s0
	v_pk_add_f32 v[66:67], v[80:81], v[88:89]
	s_mov_b64 s[48:49], 0
	s_and_b64 vcc, exec, s[0:1]
	v_cvt_pk_bf16_f32 v68, v87, s0
	v_cvt_pk_bf16_f32 v69, v84, s0
	v_cvt_pk_bf16_f32 v84, v85, s0
	v_cvt_pk_bf16_f32 v80, v82, s0
	v_cvt_pk_bf16_f32 v81, v83, s0
	global_store_short v[72:73], v0, off offset:2048
	global_store_short v[76:77], v68, off offset:2048
	global_store_short v[78:79], v69, off
	global_store_short v[114:115], v84, off
	global_store_short v[70:71], v80, off offset:2048
	global_store_short v[74:75], v81, off offset:2048
	v_cvt_pk_bf16_f32 v0, v66, s0
	v_cvt_pk_bf16_f32 v66, v67, s0
	global_store_short v[78:79], v0, off offset:2048
	global_store_short v[114:115], v66, off offset:2048
	s_cbranch_vccz .LBB0_364
	s_mov_b64 s[0:1], 0x4000
	s_mov_b64 s[44:45], 0
	s_and_b64 vcc, exec, s[42:43]
	s_cbranch_vccz .LBB0_361
	s_add_i32 s40, s40, s30
	s_cmpk_gt_i32 s40, 0x3ff
	s_barrier
	s_cbranch_scc0 .LBB0_358
